# NSA compressed branch: V_cmp^T staged once per tile in LDS (shared by 8 waves, padded rows) and PV fragments read from LDS; mLSTM loop-invariant loads hoisted; compress k-loop loads batched
# speedup vs baseline: 1.0915x; 1.0279x over previous
.LBB0_187:
	s_lshr_b32 s0, s76, 6
	s_and_b32 s1, s0, 0x3fffffc
	s_add_i32 s1, s74, s1
	s_lshl_b32 s2, s1, 3
	s_add_i32 s2, s56, s2
	s_and_b32 s2, s2, 0x7f
	s_lshl_b32 s72, s2, 4
	s_lshl_b32 s2, s76, 3
	s_and_b32 s2, s2, 0x80
	s_and_b32 s1, s1, 15
	s_add_i32 s2, s56, s2
	s_lshl_b32 s1, s1, 3
	s_add_i32 s2, s2, s1
	s_bfe_u32 s75, s2, 0x10007
	s_and_b32 s0, s0, 12
	v_mov_b32_e32 v0, 0xe8
	s_lshl_b32 s1, s75, 2
	s_add_i32 s0, s0, s76
	s_or_b32 s82, s1, 1
	s_and_b32 s1, s76, 0x1ffffff0
	v_add_u32_e32 v0, 0, v0
	s_and_b32 s0, s0, 15
	v_add_u32_e32 v0, 0x20400, v0
	s_or_b32 s0, s0, s1
	ds_read_b64 v[0:1], v0
	s_lshl_b32 s0, s0, 3
	s_add_i32 s0, s0, s56
	s_bfe_u32 s2, s0, 0x10007
	s_ashr_i32 s94, s0, 8
	s_lshl_b32 s0, s0, 4
	s_and_b32 s81, s0, 0x7f0
	s_lshl_b32 s0, s94, 1
	s_or_b32 s84, s0, s2
	s_waitcnt lgkmcnt(0)
	v_readfirstlane_b32 s86, v0
	v_mbcnt_lo_u32_b32 v106, -1, 0
	v_mbcnt_hi_u32_b32 v106, -1, v106
	s_ashr_i32 s85, s84, 31
	v_and_b32_e32 v190, 15, v106
	v_ashrrev_i32_e32 v32, 4, v106
	v_cmp_lt_i32_e32 vcc, v218, v213
	v_xor_b32_e32 v0, 32, v211
	s_lshl_b32 s95, s94, 11
	v_or_b32_e32 v191, s81, v190
	s_lshl_b64 s[0:1], s[84:85], 14
	v_cndmask_b32_e32 v9, v211, v218, vcc
	v_cmp_lt_i32_e32 vcc, v0, v213
	v_lshlrev_b32_e32 v144, 2, v32
	v_readfirstlane_b32 s87, v1
	s_add_u32 s6, s86, s0
	v_subrev_u32_e32 v4, 31, v191
	v_cndmask_b32_e32 v10, v211, v0, vcc
	v_lshlrev_b32_e32 v0, 6, v32
	v_or_b32_e32 v15, 1, v144
	s_addc_u32 s7, s87, s1
	s_add_u32 s100, s6, 0x600000
	s_addc_u32 s101, s7, 0
	v_lshlrev_b32_e32 v204, 4, v106
	v_mov_b32_e32 v205, s56
	v_lshl_add_u32 v204, v205, 11, v204
	global_load_dwordx4 v[196:199], v204, s[100:101]
	global_load_dwordx4 v[200:203], v204, s[100:101] offset:1024
	v_cmp_gt_i32_e32 vcc, 32, v32
	v_cmp_le_i32_e64 s[0:1], v0, v4
	s_movk_i32 s8, 0x7f
	v_lshlrev_b32_e32 v5, 4, v15
	v_or_b32_e32 v18, 3, v144
	v_or_b32_e32 v19, 2, v144
	s_and_b64 s[4:5], vcc, s[0:1]
	v_lshlrev_b32_e32 v160, 7, v190
	v_ashrrev_i32_e32 v145, 31, v144
	v_cmp_gt_i32_e32 vcc, s8, v15
	v_cmp_le_i32_e64 s[0:1], v5, v4
	v_lshlrev_b32_e32 v5, 4, v18
	v_lshlrev_b32_e32 v6, 4, v19
	v_add_u32_e32 v24, 16, v144
	v_lshl_add_u64 v[2:3], s[6:7], 0, v[160:161]
	v_lshl_add_u64 v[0:1], v[144:145], 1, s[6:7]
	s_and_b64 s[6:7], vcc, s[0:1]
	v_cmp_gt_i32_e32 vcc, s8, v19
	v_cmp_gt_i32_e64 s[0:1], s8, v18
	v_cmp_le_i32_e64 s[10:11], v6, v4
	v_cmp_le_i32_e64 s[8:9], v5, v4
	v_add_u32_e32 v22, 17, v144
	v_lshlrev_b32_e32 v5, 4, v24
	s_and_b64 s[10:11], vcc, s[10:11]
	v_cmp_le_i32_e32 vcc, v5, v4
	v_lshlrev_b32_e32 v5, 4, v22
	v_add_u32_e32 v26, 18, v144
	v_add_u32_e32 v25, 19, v144
	s_and_b64 s[8:9], s[0:1], s[8:9]
	v_cmp_le_i32_e64 s[0:1], v5, v4
	v_cmp_gt_i32_e64 s[18:19], 28, v32
	v_lshlrev_b32_e32 v5, 4, v25
	v_lshlrev_b32_e32 v6, 4, v26
	v_add_u32_e32 v29, 32, v144
	s_and_b64 s[12:13], s[18:19], vcc
	s_and_b64 s[14:15], s[18:19], s[0:1]
	v_cmp_le_i32_e32 vcc, v6, v4
	v_cmp_le_i32_e64 s[0:1], v5, v4
	v_add_u32_e32 v28, 33, v144
	v_lshlrev_b32_e32 v5, 4, v29
	v_cmp_gt_i32_e64 s[16:17], 27, v32
	s_and_b64 s[20:21], s[18:19], vcc
	v_cmp_le_i32_e32 vcc, v5, v4
	v_lshlrev_b32_e32 v5, 4, v28
	v_add_u32_e32 v30, 34, v144
	v_add_u32_e32 v31, 35, v144
	s_and_b64 s[16:17], s[16:17], s[0:1]
	v_cmp_le_i32_e64 s[0:1], v5, v4
	v_cmp_gt_i32_e64 s[28:29], 24, v32
	v_lshlrev_b32_e32 v5, 4, v31
	v_lshlrev_b32_e32 v6, 4, v30
	v_add_u32_e32 v39, 48, v144
	s_and_b64 s[22:23], s[28:29], vcc
	s_and_b64 s[24:25], s[28:29], s[0:1]
	v_cmp_le_i32_e32 vcc, v6, v4
	v_cmp_le_i32_e64 s[0:1], v5, v4
	v_add_u32_e32 v38, 49, v144
	v_lshlrev_b32_e32 v5, 4, v39
	v_cmp_gt_i32_e64 s[18:19], 23, v32
	s_and_b64 s[28:29], s[28:29], vcc
	v_cmp_le_i32_e32 vcc, v5, v4
	v_lshlrev_b32_e32 v5, 4, v38
	v_add_u32_e32 v40, 50, v144
	v_add_u32_e32 v41, 51, v144
	s_and_b64 s[26:27], s[18:19], s[0:1]
	v_cmp_le_i32_e64 s[0:1], v5, v4
	v_cmp_gt_i32_e64 s[38:39], 20, v32
	v_lshlrev_b32_e32 v5, 4, v41
	v_lshlrev_b32_e32 v6, 4, v40
	v_add_u32_e32 v48, 0x43, v144
	v_cmp_gt_i32_e64 s[18:19], 19, v32
	s_and_b64 s[30:31], s[38:39], vcc
	s_and_b64 s[34:35], s[38:39], s[0:1]
	v_cmp_le_i32_e32 vcc, v6, v4
	v_cmp_le_i32_e64 s[0:1], v5, v4
	v_add_u32_e32 v47, 64, v144
	v_lshlrev_b32_e32 v6, 4, v48
	s_and_b64 s[36:37], s[18:19], s[0:1]
	v_add_u32_e32 v46, 0x41, v144
	v_lshlrev_b32_e32 v5, 4, v47
	v_cmp_gt_i32_e64 s[0:1], 15, v32
	v_cmp_le_i32_e64 s[18:19], v6, v4
	s_and_b64 s[38:39], s[38:39], vcc
	v_cmp_le_i32_e32 vcc, v5, v4
	v_lshlrev_b32_e32 v5, 4, v46
	s_and_b64 s[40:41], s[0:1], s[18:19]
	v_cmp_gt_i32_e64 s[0:1], 16, v32
	v_add_u32_e32 v49, 0x42, v144
	s_and_b64 s[42:43], s[0:1], vcc
	v_cmp_le_i32_e32 vcc, v5, v4
	v_lshlrev_b32_e32 v5, 4, v49
	v_add_u32_e32 v54, 0x53, v144
	s_and_b64 s[44:45], s[0:1], vcc
	v_cmp_le_i32_e32 vcc, v5, v4
	v_lshlrev_b32_e32 v5, 4, v54
	v_add_u32_e32 v56, 0x50, v144
	s_and_b64 s[46:47], s[0:1], vcc
	v_cmp_gt_i32_e32 vcc, 11, v32
	v_cmp_le_i32_e64 s[0:1], v5, v4
	v_add_u32_e32 v55, 0x51, v144
	v_lshlrev_b32_e32 v5, 4, v56
	s_and_b64 s[48:49], vcc, s[0:1]
	v_lshlrev_b32_e32 v6, 4, v55
	v_cmp_le_i32_e32 vcc, v5, v4
	v_cmp_gt_i32_e64 s[0:1], 12, v32
	v_add_u32_e32 v57, 0x52, v144
	s_and_b64 s[50:51], s[0:1], vcc
	v_cmp_le_i32_e32 vcc, v6, v4
	v_lshlrev_b32_e32 v5, 4, v57
	v_add_u32_e32 v62, 0x63, v144
	s_and_b64 s[52:53], s[0:1], vcc
	v_cmp_le_i32_e32 vcc, v5, v4
	v_lshlrev_b32_e32 v5, 4, v62
	v_add_u32_e32 v64, 0x60, v144
	s_and_b64 s[54:55], s[0:1], vcc
	v_cmp_gt_i32_e32 vcc, 7, v32
	v_cmp_le_i32_e64 s[0:1], v5, v4
	v_add_u32_e32 v63, 0x61, v144
	v_lshlrev_b32_e32 v5, 4, v64
	s_and_b64 s[56:57], vcc, s[0:1]
	v_lshlrev_b32_e32 v6, 4, v63
	v_cmp_le_i32_e32 vcc, v5, v4
	v_cmp_gt_i32_e64 s[0:1], 8, v32
	v_add_u32_e32 v65, 0x62, v144
	s_and_b64 s[58:59], s[0:1], vcc
	v_cmp_le_i32_e32 vcc, v6, v4
	v_lshlrev_b32_e32 v5, 4, v65
	v_add_u32_e32 v70, 0x73, v144
	s_and_b64 s[60:61], s[0:1], vcc
	v_cmp_le_i32_e32 vcc, v5, v4
	v_lshlrev_b32_e32 v5, 4, v70
	v_add_u32_e32 v72, 0x70, v144
	s_and_b64 s[62:63], s[0:1], vcc
	v_cmp_gt_i32_e32 vcc, 3, v32
	v_cmp_le_i32_e64 s[0:1], v5, v4
	v_add_u32_e32 v71, 0x71, v144
	v_lshlrev_b32_e32 v5, 4, v72
	s_and_b64 s[64:65], vcc, s[0:1]
	v_lshlrev_b32_e32 v6, 4, v71
	v_cmp_le_i32_e32 vcc, v5, v4
	v_cmp_gt_i32_e64 s[0:1], 4, v32
	v_add_u32_e32 v73, 0x72, v144
	s_and_b64 s[66:67], s[0:1], vcc
	v_cmp_le_i32_e32 vcc, v6, v4
	v_lshlrev_b32_e32 v5, 4, v73
	s_and_b64 s[68:69], s[0:1], vcc
	v_cmp_le_i32_e32 vcc, v5, v4
	s_and_b64 s[70:71], s[0:1], vcc
	s_or_b32 s0, s95, s72
	v_or_b32_e32 v4, s0, v190
	v_ashrrev_i32_e32 v5, 31, v4
	v_lshlrev_b32_e32 v146, 3, v32
	v_lshlrev_b64 v[6:7], 7, v[4:5]
	s_mul_i32 s0, s75, 48
	v_add_u32_e32 v11, 48, v106
	v_ashrrev_i32_e32 v147, 31, v146
	v_or_b32_e32 v6, s0, v6
	v_readlane_b32 s0, v253, 31
	v_lshlrev_b32_e32 v193, 2, v9
	v_lshlrev_b32_e32 v194, 2, v10
	v_and_or_b32 v9, v11, 63, v212
	v_lshlrev_b64 v[10:11], 1, v[146:147]
	v_lshl_add_u32 v192, v106, 2, s0
	v_lshl_add_u64 v[2:3], v[2:3], 0, v[10:11]
	s_mov_b64 s[0:1], 0x400000
	v_cvt_f32_i32_e32 v14, v144
	v_cvt_f32_i32_e32 v15, v15
	v_cvt_f32_u32_e32 v8, v191
	v_lshl_add_u64 v[16:17], v[2:3], 0, s[0:1]
	s_mov_b64 s[0:1], 0x600000
	v_cvt_f32_i32_e32 v21, v18
	v_cvt_f32_i32_e32 v20, v19
	v_lshl_add_u64 v[12:13], v[0:1], 0, s[0:1]
	s_mov_b32 s0, 0x41780000
	v_cvt_f32_i32_e32 v23, v22
	v_cvt_f32_i32_e32 v22, v24
	v_mov_b64_e32 v[74:75], s[0:1]
	s_mov_b32 s18, 0x41800000
	v_cvt_f32_i32_e32 v25, v25
	v_cvt_f32_i32_e32 v24, v26
	v_pk_fma_f32 v[14:15], v[14:15], s[18:19], v[74:75] op_sel_hi:[1,0,0]
	v_cvt_f32_i32_e32 v35, v31
	v_pk_add_f32 v[18:19], v[8:9], v[14:15] op_sel_hi:[0,1] neg_lo:[0,1] neg_hi:[0,1]
	v_pk_fma_f32 v[14:15], v[20:21], s[18:19], v[74:75] op_sel_hi:[1,0,0]
	v_cvt_f32_i32_e32 v34, v30
	v_pk_add_f32 v[20:21], v[8:9], v[14:15] op_sel_hi:[0,1] neg_lo:[0,1] neg_hi:[0,1]
	v_pk_fma_f32 v[14:15], v[22:23], s[18:19], v[74:75] op_sel_hi:[1,0,0]
	v_cvt_f32_i32_e32 v43, v41
	v_pk_add_f32 v[22:23], v[8:9], v[14:15] op_sel_hi:[0,1] neg_lo:[0,1] neg_hi:[0,1]
	v_pk_fma_f32 v[14:15], v[24:25], s[18:19], v[74:75] op_sel_hi:[1,0,0]
	v_cvt_f32_i32_e32 v42, v40
	v_pk_add_f32 v[24:25], v[8:9], v[14:15] op_sel_hi:[0,1] neg_lo:[0,1] neg_hi:[0,1]
	v_cvt_f32_i32_e32 v15, v28
	v_cvt_f32_i32_e32 v14, v29
	v_cvt_f32_i32_e32 v51, v48
	v_cvt_f32_i32_e32 v50, v49
	v_cvt_f32_i32_e32 v59, v54
	v_pk_fma_f32 v[14:15], v[14:15], s[18:19], v[74:75] op_sel_hi:[1,0,0]
	v_cvt_f32_i32_e32 v58, v57
	v_pk_add_f32 v[30:31], v[8:9], v[14:15] op_sel_hi:[0,1] neg_lo:[0,1] neg_hi:[0,1]
	v_pk_fma_f32 v[14:15], v[34:35], s[18:19], v[74:75] op_sel_hi:[1,0,0]
	s_mov_b64 s[0:1], 0x401000
	v_pk_add_f32 v[34:35], v[8:9], v[14:15] op_sel_hi:[0,1] neg_lo:[0,1] neg_hi:[0,1]
	v_cvt_f32_i32_e32 v15, v38
	v_cvt_f32_i32_e32 v14, v39
	v_lshl_add_u64 v[26:27], v[2:3], 0, s[0:1]
	s_mov_b64 s[0:1], 0x401040
	v_lshl_add_u64 v[28:29], v[2:3], 0, s[0:1]
	v_pk_fma_f32 v[14:15], v[14:15], s[18:19], v[74:75] op_sel_hi:[1,0,0]
	s_mov_b64 s[0:1], 0x401800
	v_pk_add_f32 v[40:41], v[8:9], v[14:15] op_sel_hi:[0,1] neg_lo:[0,1] neg_hi:[0,1]
	v_pk_fma_f32 v[14:15], v[42:43], s[18:19], v[74:75] op_sel_hi:[1,0,0]
	v_lshl_add_u64 v[36:37], v[2:3], 0, s[0:1]
	v_pk_add_f32 v[42:43], v[8:9], v[14:15] op_sel_hi:[0,1] neg_lo:[0,1] neg_hi:[0,1]
	v_cvt_f32_i32_e32 v15, v46
	v_cvt_f32_i32_e32 v14, v47
	s_mov_b64 s[0:1], 0x401840
	v_cvt_f32_i32_e32 v67, v62
	v_cvt_f32_i32_e32 v66, v65
	v_pk_fma_f32 v[14:15], v[14:15], s[18:19], v[74:75] op_sel_hi:[1,0,0]
	v_lshl_add_u64 v[38:39], v[2:3], 0, s[0:1]
	v_pk_add_f32 v[48:49], v[8:9], v[14:15] op_sel_hi:[0,1] neg_lo:[0,1] neg_hi:[0,1]
	v_pk_fma_f32 v[14:15], v[50:51], s[18:19], v[74:75] op_sel_hi:[1,0,0]
	s_mov_b64 s[0:1], 0x402000
	v_pk_add_f32 v[50:51], v[8:9], v[14:15] op_sel_hi:[0,1] neg_lo:[0,1] neg_hi:[0,1]
	v_cvt_f32_i32_e32 v15, v55
	v_cvt_f32_i32_e32 v14, v56
	v_lshl_add_u64 v[44:45], v[2:3], 0, s[0:1]
	s_mov_b64 s[0:1], 0x402040
	v_lshl_add_u64 v[46:47], v[2:3], 0, s[0:1]
	v_pk_fma_f32 v[14:15], v[14:15], s[18:19], v[74:75] op_sel_hi:[1,0,0]
	s_mov_b64 s[0:1], 0x402800
	v_pk_add_f32 v[56:57], v[8:9], v[14:15] op_sel_hi:[0,1] neg_lo:[0,1] neg_hi:[0,1]
	v_pk_fma_f32 v[14:15], v[58:59], s[18:19], v[74:75] op_sel_hi:[1,0,0]
	v_lshl_add_u64 v[52:53], v[2:3], 0, s[0:1]
	v_pk_add_f32 v[58:59], v[8:9], v[14:15] op_sel_hi:[0,1] neg_lo:[0,1] neg_hi:[0,1]
	v_cvt_f32_i32_e32 v15, v63
	v_cvt_f32_i32_e32 v14, v64
	s_mov_b64 s[0:1], 0x402840
	v_lshl_add_u64 v[54:55], v[2:3], 0, s[0:1]
	s_mov_b64 s[0:1], 0x403000
	v_pk_fma_f32 v[14:15], v[14:15], s[18:19], v[74:75] op_sel_hi:[1,0,0]
	v_lshl_add_u64 v[60:61], v[2:3], 0, s[0:1]
	v_pk_add_f32 v[64:65], v[8:9], v[14:15] op_sel_hi:[0,1] neg_lo:[0,1] neg_hi:[0,1]
	v_pk_fma_f32 v[14:15], v[66:67], s[18:19], v[74:75] op_sel_hi:[1,0,0]
	s_mov_b64 s[0:1], 0x403040
	v_pk_add_f32 v[66:67], v[8:9], v[14:15] op_sel_hi:[0,1] neg_lo:[0,1] neg_hi:[0,1]
	v_cvt_f32_i32_e32 v15, v71
	v_cvt_f32_i32_e32 v14, v72
	v_cvt_f32_i32_e32 v77, v70
	v_cvt_f32_i32_e32 v76, v73
	v_lshl_add_u64 v[62:63], v[2:3], 0, s[0:1]
	s_mov_b64 s[0:1], 0x403800
	v_lshl_add_u64 v[68:69], v[2:3], 0, s[0:1]
	s_mov_b64 s[0:1], 0x403840
	v_lshl_add_u64 v[70:71], v[2:3], 0, s[0:1]
	v_pk_fma_f32 v[2:3], v[14:15], s[18:19], v[74:75] op_sel_hi:[1,0,0]
	v_lshlrev_b32_e32 v160, 8, v190
	v_pk_add_f32 v[72:73], v[8:9], v[2:3] op_sel_hi:[0,1] neg_lo:[0,1] neg_hi:[0,1]
	v_pk_fma_f32 v[2:3], v[76:77], s[18:19], v[74:75] op_sel_hi:[1,0,0]
	v_lshlrev_b32_e32 v33, 2, v9
	v_pk_add_f32 v[74:75], v[8:9], v[2:3] op_sel_hi:[0,1] neg_lo:[0,1] neg_hi:[0,1]
	v_lshl_add_u64 v[76:77], v[12:13], 0, v[160:161]
	v_or_b32_e32 v2, 0x1000, v160
	v_mov_b32_e32 v3, v161
	v_or_b32_e32 v8, 0x2000, v160
	v_mov_b32_e32 v9, v161
	v_or_b32_e32 v160, 0x3000, v160
	s_mov_b64 s[0:1], 0x600040
	v_lshl_add_u64 v[78:79], v[12:13], 0, v[2:3]
	v_lshl_add_u64 v[80:81], v[12:13], 0, v[8:9]
	v_lshl_add_u64 v[82:83], v[12:13], 0, v[160:161]
	v_lshl_add_u64 v[12:13], v[0:1], 0, s[0:1]
	s_mov_b64 s[0:1], 0x600080
	v_lshlrev_b64 v[4:5], 10, v[4:5]
	v_lshl_add_u64 v[84:85], v[12:13], 0, v[2:3]
	v_lshl_add_u64 v[86:87], v[12:13], 0, v[8:9]
	v_lshl_add_u64 v[88:89], v[12:13], 0, v[160:161]
	v_lshl_add_u64 v[12:13], v[0:1], 0, s[0:1]
	s_mov_b64 s[0:1], 0x6000c0
	v_lshl_or_b32 v4, s75, 9, v4
	v_lshl_add_u64 v[0:1], v[0:1], 0, s[0:1]
	s_mov_b64 s[0:1], 0x2f200020
	v_mov_b32_e32 v14, 0
	v_lshl_add_u64 v[90:91], v[12:13], 0, v[2:3]
	v_lshl_add_u64 v[92:93], v[12:13], 0, v[8:9]
	v_lshl_add_u64 v[94:95], v[12:13], 0, v[160:161]
	v_lshl_add_u64 v[96:97], v[0:1], 0, v[2:3]
	v_lshl_add_u64 v[98:99], v[0:1], 0, v[8:9]
	v_lshl_add_u64 v[100:101], v[0:1], 0, v[160:161]
	v_lshl_add_u64 v[102:103], v[6:7], 0, s[0:1]
	v_lshl_add_u64 v[104:105], v[4:5], 0, v[10:11]
	v_mov_b32_e32 v15, v14
	v_mov_b32_e32 v12, v14
	v_mov_b32_e32 v13, v14
	v_mov_b32_e32 v10, v14
	v_mov_b32_e32 v11, v14
	v_mov_b32_e32 v8, v14
	v_mov_b32_e32 v9, v14
	s_mov_b32 s0, 0
	v_cmp_lt_i32_e64 s[18:19], 0, v32
	v_lshrrev_b32_e32 v206, 4, v106
	v_lshl_add_u32 v206, v205, 3, v206
	v_mul_u32_u24_e32 v206, 272, v206
	v_and_b32_e32 v207, 15, v106
	v_lshl_add_u32 v206, v207, 4, v206
	v_add_u32_e32 v206, 0x20500, v206
	v_mul_u32_u24_e32 v195, 272, v190
	v_lshl_add_u32 v195, v144, 1, v195
	v_add_u32_e32 v195, 0x20500, v195
	s_waitcnt vmcnt(0) lgkmcnt(0)
	s_barrier
	ds_write_b128 v206, v[196:199]
	ds_write_b128 v206, v[200:203] offset:1088
	s_waitcnt lgkmcnt(0)
	s_barrier
	s_mov_b32 s72, 0x42fc0000
.LBB0_188:
	v_lshl_add_u64 v[0:1], s[86:87], 0, v[104:105]
	s_mov_b32 s1, 0x15200000
	v_add_co_u32_e32 v0, vcc, s1, v0
	v_cvt_f32_u32_e32 v107, s82
	s_nop 0
	v_addc_co_u32_e32 v1, vcc, 0, v1, vcc
	global_load_dwordx4 v[4:7], v[0:1], off
	s_nop 0
	global_load_dwordx4 v[0:3], v[0:1], off offset:64
	v_cmp_lt_f32_e32 vcc, s72, v107
	s_nop 1
	v_cndmask_b32_e32 v108, 0, v220, vcc
	v_sub_f32_e32 v107, v108, v107
	v_exp_f32_e32 v107, v107
	s_and_b64 vcc, vcc, exec
	s_cselect_b32 s1, 0xffffffc0, 0
	v_ldexp_f32 v152, v107, s1
	global_load_dwordx4 v[108:111], v[16:17], off
	global_load_dwordx4 v[196:199], v[16:17], off offset:64
	global_load_dwordx4 v[112:115], v[16:17], off offset:2048
	global_load_dwordx4 v[200:203], v[16:17], off offset:2112
	global_load_dwordx4 v[116:119], v[26:27], off
	global_load_dwordx4 v[204:207], v[28:29], off
	global_load_dwordx4 v[120:123], v[36:37], off
	global_load_dwordx4 v[228:231], v[38:39], off
	global_load_dwordx4 v[124:127], v[44:45], off
	global_load_dwordx4 v[232:235], v[46:47], off
	global_load_dwordx4 v[128:131], v[52:53], off
	global_load_dwordx4 v[236:239], v[54:55], off
	global_load_dwordx4 v[132:135], v[60:61], off
	global_load_dwordx4 v[136:139], v[68:69], off
	global_load_dwordx4 v[140:143], v[62:63], off
	global_load_dwordx4 v[148:151], v[70:71], off
	s_waitcnt vmcnt(14) lgkmcnt(0)
	v_mfma_f32_16x16x32_bf16 v[108:111], v[108:111], v[4:7], 0
	v_mfma_f32_16x16x32_bf16 v[108:111], v[196:199], v[0:3], v[108:111]
	s_waitcnt vmcnt(12)
	v_mfma_f32_16x16x32_bf16 v[112:115], v[112:115], v[4:7], 0
	v_mfma_f32_16x16x32_bf16 v[112:115], v[200:203], v[0:3], v[112:115]
	s_waitcnt vmcnt(10)
	v_mfma_f32_16x16x32_bf16 v[116:119], v[116:119], v[4:7], 0
	v_mfma_f32_16x16x32_bf16 v[116:119], v[204:207], v[0:3], v[116:119]
	s_waitcnt vmcnt(8)
	v_mfma_f32_16x16x32_bf16 v[120:123], v[120:123], v[4:7], 0
	v_mfma_f32_16x16x32_bf16 v[120:123], v[228:231], v[0:3], v[120:123]
	s_waitcnt vmcnt(6)
	v_mfma_f32_16x16x32_bf16 v[124:127], v[124:127], v[4:7], 0
	v_mfma_f32_16x16x32_bf16 v[124:127], v[232:235], v[0:3], v[124:127]
	s_waitcnt vmcnt(4)
	v_mfma_f32_16x16x32_bf16 v[128:131], v[128:131], v[4:7], 0
	v_mfma_f32_16x16x32_bf16 v[128:131], v[236:239], v[0:3], v[128:131]
	v_pk_mul_f32 v[154:155], v[22:23], v[152:153] op_sel_hi:[1,0]
	v_pk_mul_f32 v[156:157], v[24:25], v[152:153] op_sel_hi:[1,0]
	v_pk_mul_f32 v[180:181], v[40:41], v[152:153] op_sel_hi:[1,0]
	v_pk_mul_f32 v[182:183], v[42:43], v[152:153] op_sel_hi:[1,0]
	v_pk_mul_f32 v[188:189], v[18:19], v[152:153] op_sel_hi:[1,0]
	v_pk_mul_f32 v[158:159], v[72:73], v[152:153] op_sel_hi:[1,0]
	v_pk_mul_f32 v[166:167], v[74:75], v[152:153] op_sel_hi:[1,0]
	v_pk_mul_f32 v[168:169], v[64:65], v[152:153] op_sel_hi:[1,0]
	v_pk_mul_f32 v[170:171], v[66:67], v[152:153] op_sel_hi:[1,0]
	v_pk_mul_f32 v[172:173], v[56:57], v[152:153] op_sel_hi:[1,0]
	v_pk_mul_f32 v[174:175], v[58:59], v[152:153] op_sel_hi:[1,0]
	v_pk_mul_f32 v[176:177], v[48:49], v[152:153] op_sel_hi:[1,0]
	v_pk_mul_f32 v[178:179], v[50:51], v[152:153] op_sel_hi:[1,0]
	v_pk_mul_f32 v[184:185], v[30:31], v[152:153] op_sel_hi:[1,0]
	v_pk_mul_f32 v[186:187], v[34:35], v[152:153] op_sel_hi:[1,0]
	v_pk_mul_f32 v[152:153], v[20:21], v[152:153] op_sel_hi:[1,0]
	v_pk_fma_f32 v[112:113], v[112:113], s[90:91], v[154:155] op_sel_hi:[1,0,1] neg_lo:[0,0,1] neg_hi:[0,0,1]
	v_pk_fma_f32 v[114:115], v[114:115], s[90:91], v[156:157] op_sel_hi:[1,0,1] neg_lo:[0,0,1] neg_hi:[0,0,1]
	v_pk_fma_f32 v[120:121], v[120:121], s[90:91], v[180:181] op_sel_hi:[1,0,1] neg_lo:[0,0,1] neg_hi:[0,0,1]
	v_pk_fma_f32 v[122:123], v[122:123], s[90:91], v[182:183] op_sel_hi:[1,0,1] neg_lo:[0,0,1] neg_hi:[0,0,1]
	v_pk_fma_f32 v[108:109], v[108:109], s[90:91], v[188:189] op_sel_hi:[1,0,1] neg_lo:[0,0,1] neg_hi:[0,0,1]
	v_pk_fma_f32 v[110:111], v[110:111], s[90:91], v[152:153] op_sel_hi:[1,0,1] neg_lo:[0,0,1] neg_hi:[0,0,1]
	v_cndmask_b32_e64 v107, v221, v113, s[14:15]
	v_cndmask_b32_e64 v113, v221, v115, s[16:17]
	v_cndmask_b32_e64 v115, v221, v121, s[34:35]
	v_cndmask_b32_e64 v121, v221, v123, s[36:37]
	v_cndmask_b32_e64 v123, v221, v109, s[6:7]
	v_cndmask_b32_e64 v152, v221, v108, s[4:5]
	v_cndmask_b32_e64 v153, v221, v111, s[8:9]
	v_cndmask_b32_e64 v154, v221, v110, s[10:11]
	v_max3_f32 v108, v152, s73, v123
	v_cndmask_b32_e64 v112, v221, v112, s[12:13]
	v_max3_f32 v108, v108, v154, v153
	v_pk_fma_f32 v[116:117], v[116:117], s[90:91], v[184:185] op_sel_hi:[1,0,1] neg_lo:[0,0,1] neg_hi:[0,0,1]
	v_cndmask_b32_e64 v114, v221, v114, s[20:21]
	v_max3_f32 v155, v108, v112, v107
	v_pk_fma_f32 v[118:119], v[118:119], s[90:91], v[186:187] op_sel_hi:[1,0,1] neg_lo:[0,0,1] neg_hi:[0,0,1]
	v_cndmask_b32_e64 v117, v221, v117, s[24:25]
	v_cndmask_b32_e64 v116, v221, v116, s[22:23]
	v_cndmask_b32_e64 v119, v221, v119, s[26:27]
	v_cndmask_b32_e64 v118, v221, v118, s[28:29]
	v_cndmask_b32_e64 v120, v221, v120, s[30:31]
	v_pk_fma_f32 v[124:125], v[124:125], s[90:91], v[176:177] op_sel_hi:[1,0,1] neg_lo:[0,0,1] neg_hi:[0,0,1]
	v_cndmask_b32_e64 v122, v221, v122, s[38:39]
	v_pk_fma_f32 v[126:127], v[126:127], s[90:91], v[178:179] op_sel_hi:[1,0,1] neg_lo:[0,0,1] neg_hi:[0,0,1]
	v_cndmask_b32_e64 v125, v221, v125, s[44:45]
	v_cndmask_b32_e64 v124, v221, v124, s[42:43]
	v_pk_fma_f32 v[128:129], v[128:129], s[90:91], v[172:173] op_sel_hi:[1,0,1] neg_lo:[0,0,1] neg_hi:[0,0,1]
	v_cndmask_b32_e64 v127, v221, v127, s[40:41]
	v_cndmask_b32_e64 v126, v221, v126, s[46:47]
	v_pk_fma_f32 v[130:131], v[130:131], s[90:91], v[174:175] op_sel_hi:[1,0,1] neg_lo:[0,0,1] neg_hi:[0,0,1]
	v_cndmask_b32_e64 v129, v221, v129, s[52:53]
	v_cndmask_b32_e64 v128, v221, v128, s[50:51]
	v_cndmask_b32_e64 v131, v221, v131, s[48:49]
	v_cndmask_b32_e64 v130, v221, v130, s[54:55]
	v_cmp_lt_f32_e32 vcc, s92, v123
	s_waitcnt vmcnt(0) lgkmcnt(0)
	v_mfma_f32_16x16x32_bf16 v[108:111], v[132:135], v[4:7], 0
	v_max3_f32 v132, v155, v114, v113
	v_max3_f32 v132, v132, v116, v117
	v_max3_f32 v132, v132, v118, v119
	v_mfma_f32_16x16x32_bf16 v[4:7], v[136:139], v[4:7], 0
	v_max3_f32 v132, v132, v120, v115
	v_max3_f32 v132, v132, v122, v121
	v_max3_f32 v132, v132, v124, v125
	v_mfma_f32_16x16x32_bf16 v[108:111], v[140:143], v[0:3], v[108:111]
	v_max3_f32 v132, v132, v126, v127
	v_max3_f32 v132, v132, v128, v129
	v_max3_f32 v132, v132, v130, v131
	v_mfma_f32_16x16x32_bf16 v[0:3], v[148:151], v[0:3], v[4:7]
	s_nop 3
	v_fma_f32 v4, v108, s90, -v168
	v_fma_f32 v5, v109, s90, -v169
	s_nop 1
	v_pk_fma_f32 v[0:1], v[0:1], s[90:91], v[158:159] op_sel_hi:[1,0,1] neg_lo:[0,0,1] neg_hi:[0,0,1]
	v_pk_fma_f32 v[6:7], v[110:111], s[90:91], v[170:171] op_sel_hi:[1,0,1] neg_lo:[0,0,1] neg_hi:[0,0,1]
	v_cndmask_b32_e64 v137, v221, v5, s[60:61]
	v_cndmask_b32_e64 v138, v221, v4, s[58:59]
	v_cndmask_b32_e64 v134, v221, v0, s[66:67]
	v_cndmask_b32_e64 v139, v221, v7, s[56:57]
	v_cndmask_b32_e64 v140, v221, v6, s[62:63]
	v_max3_f32 v0, v132, v138, v137
	v_pk_fma_f32 v[2:3], v[2:3], s[90:91], v[166:167] op_sel_hi:[1,0,1] neg_lo:[0,0,1] neg_hi:[0,0,1]
	v_cndmask_b32_e64 v133, v221, v1, s[68:69]
	v_max3_f32 v0, v0, v140, v139
	v_cndmask_b32_e64 v135, v221, v3, s[64:65]
	v_cndmask_b32_e64 v136, v221, v2, s[70:71]
	v_max3_f32 v0, v0, v134, v133
	v_max3_f32 v0, v0, v136, v135
	ds_bpermute_b32 v1, v193, v0
	s_waitcnt lgkmcnt(0)
	v_max_f32_e32 v1, v1, v1
	v_max_f32_e32 v0, v0, v1
	ds_bpermute_b32 v1, v194, v0
	s_waitcnt lgkmcnt(0)
	v_max_f32_e32 v1, v1, v1
	v_max_f32_e32 v132, v0, v1
	v_sub_f32_e32 v1, v123, v132
	v_sub_f32_e32 v0, v152, v132
	v_mul_f32_e32 v1, 0x3fb8aa3b, v1
	v_sub_f32_e32 v3, v153, v132
	v_mul_f32_e32 v0, 0x3fb8aa3b, v0
	v_exp_f32_e32 v1, v1
	v_sub_f32_e32 v2, v154, v132
	v_mul_f32_e32 v3, 0x3fb8aa3b, v3
	v_exp_f32_e32 v0, v0
	v_sub_f32_e32 v5, v107, v132
	v_mul_f32_e32 v2, 0x3fb8aa3b, v2
	v_exp_f32_e32 v3, v3
	v_sub_f32_e32 v4, v112, v132
	v_mul_f32_e32 v5, 0x3fb8aa3b, v5
	v_exp_f32_e32 v2, v2
	v_mul_f32_e32 v4, 0x3fb8aa3b, v4
	v_exp_f32_e32 v5, v5
	v_cndmask_b32_e32 v1, 0, v1, vcc
	v_cmp_lt_f32_e32 vcc, s92, v152
	v_exp_f32_e32 v4, v4
	v_sub_f32_e32 v7, v113, v132
	v_cndmask_b32_e32 v0, 0, v0, vcc
	v_cmp_lt_f32_e32 vcc, s92, v153
	v_add_f32_e32 v6, 0, v0
	v_add_f32_e32 v6, v1, v6
	v_cndmask_b32_e32 v3, 0, v3, vcc
	v_cmp_lt_f32_e32 vcc, s92, v154
	v_mul_f32_e32 v7, 0x3fb8aa3b, v7
	v_exp_f32_e32 v7, v7
	v_cndmask_b32_e32 v2, 0, v2, vcc
	v_cmp_lt_f32_e32 vcc, s92, v107
	v_add_f32_e32 v6, v2, v6
	v_add_f32_e32 v6, v3, v6
	v_cndmask_b32_e32 v5, 0, v5, vcc
	v_cmp_lt_f32_e32 vcc, s92, v112
	v_sub_f32_e32 v109, v117, v132
	v_sub_f32_e32 v108, v116, v132
	v_cndmask_b32_e32 v4, 0, v4, vcc
	v_add_f32_e32 v6, v4, v6
	v_add_f32_e32 v107, v5, v6
	v_sub_f32_e32 v6, v114, v132
	v_mul_f32_e32 v6, 0x3fb8aa3b, v6
	v_exp_f32_e32 v6, v6
	v_mul_f32_e32 v109, 0x3fb8aa3b, v109
	v_exp_f32_e32 v109, v109
	v_mul_f32_e32 v108, 0x3fb8aa3b, v108
	v_sub_f32_e32 v111, v119, v132
	v_cmp_lt_f32_e32 vcc, s92, v113
	v_exp_f32_e32 v108, v108
	v_sub_f32_e32 v110, v118, v132
	v_mul_f32_e32 v111, 0x3fb8aa3b, v111
	v_cndmask_b32_e32 v7, 0, v7, vcc
	v_cmp_lt_f32_e32 vcc, s92, v114
	v_exp_f32_e32 v111, v111
	v_mul_f32_e32 v110, 0x3fb8aa3b, v110
	v_cndmask_b32_e32 v6, 0, v6, vcc
	v_cmp_lt_f32_e32 vcc, s92, v117
	v_exp_f32_e32 v110, v110
	v_sub_f32_e32 v113, v115, v132
	v_cndmask_b32_e32 v109, 0, v109, vcc
	v_cmp_lt_f32_e32 vcc, s92, v116
	v_sub_f32_e32 v112, v120, v132
	v_mul_f32_e32 v113, 0x3fb8aa3b, v113
	v_cndmask_b32_e32 v108, 0, v108, vcc
	v_cmp_lt_f32_e32 vcc, s92, v119
	v_add_f32_e32 v107, v6, v107
	v_exp_f32_e32 v113, v113
	v_cndmask_b32_e32 v111, 0, v111, vcc
	v_cmp_lt_f32_e32 vcc, s92, v118
	v_mul_f32_e32 v112, 0x3fb8aa3b, v112
	v_add_f32_e32 v107, v7, v107
	v_cndmask_b32_e32 v110, 0, v110, vcc
	v_cmp_lt_f32_e32 vcc, s92, v115
	v_sub_f32_e32 v115, v121, v132
	v_exp_f32_e32 v112, v112
	v_sub_f32_e32 v114, v122, v132
	v_mul_f32_e32 v115, 0x3fb8aa3b, v115
	v_add_f32_e32 v107, v108, v107
	v_exp_f32_e32 v115, v115
	v_mul_f32_e32 v114, 0x3fb8aa3b, v114
	v_sub_f32_e32 v117, v125, v132
	v_add_f32_e32 v107, v109, v107
	v_exp_f32_e32 v114, v114
	v_sub_f32_e32 v116, v124, v132
	v_mul_f32_e32 v117, 0x3fb8aa3b, v117
	v_add_f32_e32 v107, v110, v107
	v_cndmask_b32_e32 v113, 0, v113, vcc
	v_cmp_lt_f32_e32 vcc, s92, v120
	v_exp_f32_e32 v117, v117
	v_mul_f32_e32 v116, 0x3fb8aa3b, v116
	v_sub_f32_e32 v119, v127, v132
	v_add_f32_e32 v107, v111, v107
	v_cndmask_b32_e32 v112, 0, v112, vcc
	v_cmp_lt_f32_e32 vcc, s92, v121
	v_exp_f32_e32 v116, v116
	v_sub_f32_e32 v118, v126, v132
	v_mul_f32_e32 v119, 0x3fb8aa3b, v119
	v_add_f32_e32 v107, v112, v107
	v_cndmask_b32_e32 v115, 0, v115, vcc
	v_cmp_lt_f32_e32 vcc, s92, v122
	v_exp_f32_e32 v119, v119
	v_mul_f32_e32 v118, 0x3fb8aa3b, v118
	v_sub_f32_e32 v121, v129, v132
	v_add_f32_e32 v107, v113, v107
	v_cndmask_b32_e32 v114, 0, v114, vcc
	v_cmp_lt_f32_e32 vcc, s92, v125
	v_exp_f32_e32 v118, v118
	v_sub_f32_e32 v120, v128, v132
	v_mul_f32_e32 v121, 0x3fb8aa3b, v121
	v_add_f32_e32 v107, v114, v107
	v_cndmask_b32_e32 v117, 0, v117, vcc
	v_cmp_lt_f32_e32 vcc, s92, v124
	v_exp_f32_e32 v121, v121
	v_mul_f32_e32 v120, 0x3fb8aa3b, v120
	v_sub_f32_e32 v123, v131, v132
	v_add_f32_e32 v107, v115, v107
	v_cndmask_b32_e32 v116, 0, v116, vcc
	v_cmp_lt_f32_e32 vcc, s92, v127
	v_exp_f32_e32 v120, v120
	v_sub_f32_e32 v122, v130, v132
	v_mul_f32_e32 v123, 0x3fb8aa3b, v123
	v_add_f32_e32 v107, v116, v107
	v_cndmask_b32_e32 v119, 0, v119, vcc
	v_cmp_lt_f32_e32 vcc, s92, v126
	v_exp_f32_e32 v123, v123
	v_mul_f32_e32 v122, 0x3fb8aa3b, v122
	v_sub_f32_e32 v125, v137, v132
	v_add_f32_e32 v107, v117, v107
	v_cndmask_b32_e32 v118, 0, v118, vcc
	v_cmp_lt_f32_e32 vcc, s92, v129
	v_exp_f32_e32 v122, v122
	v_sub_f32_e32 v124, v138, v132
	v_mul_f32_e32 v125, 0x3fb8aa3b, v125
	v_add_f32_e32 v107, v118, v107
	v_cndmask_b32_e32 v121, 0, v121, vcc
	v_cmp_lt_f32_e32 vcc, s92, v128
	v_exp_f32_e32 v125, v125
	v_mul_f32_e32 v124, 0x3fb8aa3b, v124
	v_sub_f32_e32 v127, v139, v132
	v_add_f32_e32 v107, v119, v107
	v_cndmask_b32_e32 v120, 0, v120, vcc
	v_cmp_lt_f32_e32 vcc, s92, v131
	v_exp_f32_e32 v124, v124
	v_sub_f32_e32 v126, v140, v132
	v_mul_f32_e32 v127, 0x3fb8aa3b, v127
	v_add_f32_e32 v107, v120, v107
	v_cndmask_b32_e32 v123, 0, v123, vcc
	v_cmp_lt_f32_e32 vcc, s92, v130
	v_exp_f32_e32 v127, v127
	v_mul_f32_e32 v126, 0x3fb8aa3b, v126
	v_sub_f32_e32 v129, v133, v132
	v_add_f32_e32 v107, v121, v107
	v_cndmask_b32_e32 v122, 0, v122, vcc
	v_cmp_lt_f32_e32 vcc, s92, v137
	v_exp_f32_e32 v126, v126
	v_sub_f32_e32 v128, v134, v132
	v_mul_f32_e32 v129, 0x3fb8aa3b, v129
	v_add_f32_e32 v107, v122, v107
	v_cndmask_b32_e32 v125, 0, v125, vcc
	v_cmp_lt_f32_e32 vcc, s92, v138
	v_exp_f32_e32 v129, v129
	v_mul_f32_e32 v128, 0x3fb8aa3b, v128
	v_sub_f32_e32 v131, v135, v132
	v_add_f32_e32 v107, v123, v107
	v_cndmask_b32_e32 v124, 0, v124, vcc
	v_cmp_lt_f32_e32 vcc, s92, v139
	v_exp_f32_e32 v128, v128
	v_sub_f32_e32 v130, v136, v132
	v_mul_f32_e32 v131, 0x3fb8aa3b, v131
	v_add_f32_e32 v107, v124, v107
	v_cndmask_b32_e32 v127, 0, v127, vcc
	v_cmp_lt_f32_e32 vcc, s92, v140
	v_exp_f32_e32 v131, v131
	v_mul_f32_e32 v130, 0x3fb8aa3b, v130
	v_add_f32_e32 v107, v125, v107
	v_cndmask_b32_e32 v126, 0, v126, vcc
	v_cmp_lt_f32_e32 vcc, s92, v133
	v_exp_f32_e32 v130, v130
	v_add_f32_e32 v107, v126, v107
	v_cndmask_b32_e32 v129, 0, v129, vcc
	v_cmp_lt_f32_e32 vcc, s92, v134
	v_add_f32_e32 v107, v127, v107
	s_nop 0
	v_cndmask_b32_e32 v128, 0, v128, vcc
	v_cmp_lt_f32_e32 vcc, s92, v135
	v_add_f32_e32 v107, v128, v107
	v_add_f32_e32 v107, v129, v107
	v_cndmask_b32_e32 v131, 0, v131, vcc
	v_cmp_lt_f32_e32 vcc, s92, v136
	s_nop 1
	v_cndmask_b32_e32 v130, 0, v130, vcc
	v_add_f32_e32 v107, v130, v107
	v_add_f32_e32 v107, v131, v107
	ds_bpermute_b32 v132, v193, v107
	s_waitcnt lgkmcnt(0)
	v_add_f32_e32 v107, v107, v132
	ds_bpermute_b32 v132, v194, v107
	s_waitcnt lgkmcnt(0)
	v_add_f32_e32 v107, v107, v132
	v_div_scale_f32 v132, vcc, v107, v107, 1.0
	v_rcp_f32_e32 v133, v132
	s_nop 0
	v_fma_f32 v134, -v132, v133, 1.0
	v_fmac_f32_e32 v133, v134, v133
	v_div_scale_f32 v134, vcc, 1.0, v107, 1.0
	v_mul_f32_e32 v135, v134, v133
	v_fma_f32 v136, -v132, v135, v134
	v_fmac_f32_e32 v135, v136, v133
	v_fma_f32 v132, -v132, v135, v134
	v_div_fmas_f32 v132, v132, v133, v135
	v_div_fixup_f32 v132, v132, v107, 1.0
	v_cmp_lt_f32_e32 vcc, 0, v107
	s_nop 1
	v_cndmask_b32_e32 v132, 0, v132, vcc
	v_pk_mul_f32 v[134:135], v[2:3], v[132:133] op_sel_hi:[1,0]
	v_pk_mul_f32 v[136:137], v[6:7], v[132:133] op_sel_hi:[1,0]
	ds_bpermute_b32 v2, v33, v135
	ds_bpermute_b32 v107, v33, v137
	v_pk_mul_f32 v[138:139], v[0:1], v[132:133] op_sel_hi:[1,0]
	v_pk_mul_f32 v[140:141], v[4:5], v[132:133] op_sel_hi:[1,0]
	v_mov_b32_e32 v4, v139
	s_waitcnt lgkmcnt(1)
	v_cndmask_b32_e64 v0, 0, v2, s[18:19]
	s_waitcnt lgkmcnt(0)
	v_cndmask_b32_e64 v1, v2, v107, s[18:19]
	v_mov_b32_e32 v2, v138
	v_mov_b32_e32 v3, v140
	v_mov_b32_e32 v5, v141
	v_pk_add_f32 v[2:3], v[2:3], v[4:5]
	v_mov_b32_e32 v4, v134
	v_mov_b32_e32 v5, v136
	v_mov_b32_e32 v6, v135
	v_mov_b32_e32 v7, v137
	v_pk_add_f32 v[4:5], v[4:5], v[6:7]
	v_pk_mul_f32 v[148:149], v[110:111], v[132:133] op_sel_hi:[1,0]
	v_pk_mul_f32 v[152:153], v[114:115], v[132:133] op_sel_hi:[1,0]
	v_pk_add_f32 v[2:3], v[2:3], v[4:5]
	ds_bpermute_b32 v6, v33, v149
	ds_bpermute_b32 v7, v33, v153
	v_pk_add_f32 v[0:1], v[0:1], v[2:3]
	v_pk_mul_f32 v[142:143], v[108:109], v[132:133] op_sel_hi:[1,0]
	v_pk_mul_f32 v[150:151], v[112:113], v[132:133] op_sel_hi:[1,0]
	v_pk_add_f32 v[14:15], v[14:15], v[0:1]
	v_mov_b32_e32 v0, v142
	v_mov_b32_e32 v1, v150
	v_mov_b32_e32 v2, v143
	v_mov_b32_e32 v3, v151
	v_pk_add_f32 v[0:1], v[0:1], v[2:3]
	v_mov_b32_e32 v2, v148
	v_mov_b32_e32 v3, v152
	v_mov_b32_e32 v4, v149
	v_mov_b32_e32 v5, v153
	v_pk_add_f32 v[2:3], v[2:3], v[4:5]
	v_pk_mul_f32 v[156:157], v[118:119], v[132:133] op_sel_hi:[1,0]
	v_pk_mul_f32 v[166:167], v[122:123], v[132:133] op_sel_hi:[1,0]
	v_pk_add_f32 v[0:1], v[0:1], v[2:3]
	s_waitcnt lgkmcnt(0)
	v_cndmask_b32_e64 v3, v6, v7, s[18:19]
	v_cndmask_b32_e64 v2, v107, v6, s[18:19]
	ds_bpermute_b32 v6, v33, v157
	ds_bpermute_b32 v107, v33, v167
	v_pk_add_f32 v[0:1], v[0:1], v[2:3]
	v_pk_mul_f32 v[154:155], v[116:117], v[132:133] op_sel_hi:[1,0]
	v_pk_mul_f32 v[158:159], v[120:121], v[132:133] op_sel_hi:[1,0]
	v_pk_add_f32 v[12:13], v[12:13], v[0:1]
	v_mov_b32_e32 v0, v154
	v_mov_b32_e32 v1, v158
	v_mov_b32_e32 v2, v155
	v_mov_b32_e32 v3, v159
	v_pk_add_f32 v[0:1], v[0:1], v[2:3]
	v_mov_b32_e32 v2, v156
	v_mov_b32_e32 v3, v166
	v_mov_b32_e32 v4, v157
	v_mov_b32_e32 v5, v167
	v_pk_add_f32 v[2:3], v[2:3], v[4:5]
	v_pk_mul_f32 v[4:5], v[128:129], v[132:133] op_sel_hi:[1,0]
	v_pk_add_f32 v[0:1], v[0:1], v[2:3]
	s_waitcnt lgkmcnt(0)
	v_cndmask_b32_e64 v3, v6, v107, s[18:19]
	v_cndmask_b32_e64 v2, v7, v6, s[18:19]
	v_pk_add_f32 v[0:1], v[0:1], v[2:3]
	v_pk_mul_f32 v[2:3], v[126:127], v[132:133] op_sel_hi:[1,0]
	v_pk_mul_f32 v[6:7], v[130:131], v[132:133] op_sel_hi:[1,0]
	ds_bpermute_b32 v114, v33, v3
	ds_bpermute_b32 v115, v33, v7
	v_pk_add_f32 v[10:11], v[10:11], v[0:1]
	v_pk_mul_f32 v[0:1], v[124:125], v[132:133] op_sel_hi:[1,0]
	v_mov_b32_e32 v109, v4
	v_mov_b32_e32 v108, v0
	v_mov_b32_e32 v110, v1
	v_mov_b32_e32 v111, v5
	v_pk_add_f32 v[108:109], v[108:109], v[110:111]
	v_mov_b32_e32 v110, v2
	v_mov_b32_e32 v111, v6
	v_mov_b32_e32 v112, v3
	v_mov_b32_e32 v113, v7
	v_pk_add_f32 v[110:111], v[110:111], v[112:113]
	s_nop 0
	v_pk_add_f32 v[108:109], v[108:109], v[110:111]
	s_waitcnt lgkmcnt(0)
	v_cndmask_b32_e64 v111, v114, v115, s[18:19]
	v_cndmask_b32_e64 v110, v107, v114, s[18:19]
	v_pk_add_f32 v[108:109], v[108:109], v[110:111]
	s_nop 0
	v_pk_add_f32 v[8:9], v[8:9], v[108:109]
	v_cvt_pk_bf16_f32 v116, v138, v139
	v_cvt_pk_bf16_f32 v117, v134, v135
	v_cvt_pk_bf16_f32 v118, v140, v141
	v_cvt_pk_bf16_f32 v119, v136, v137
	ds_read_b64 v[196:197], v195 offset:0
	ds_read_b64 v[198:199], v195 offset:32
	ds_read_b64 v[200:201], v195 offset:4352
	ds_read_b64 v[202:203], v195 offset:4384
	ds_read_b64 v[204:205], v195 offset:8704
	ds_read_b64 v[206:207], v195 offset:8736
	ds_read_b64 v[228:229], v195 offset:13056
	ds_read_b64 v[230:231], v195 offset:13088
	ds_read_b64 v[232:233], v195 offset:64
	ds_read_b64 v[234:235], v195 offset:96
	ds_read_b64 v[236:237], v195 offset:4416
	ds_read_b64 v[238:239], v195 offset:4448
	ds_read_b64 v[240:241], v195 offset:8768
	ds_read_b64 v[242:243], v195 offset:8800
	ds_read_b64 v[244:245], v195 offset:13120
	ds_read_b64 v[246:247], v195 offset:13152
	global_load_dword v107, v102, s[86:87]
	s_waitcnt lgkmcnt(8)
	s_nop 0
	v_mfma_f32_16x16x32_bf16 v[108:111], v[196:199], v[116:119], 0
	v_mfma_f32_16x16x32_bf16 v[112:115], v[200:203], v[116:119], 0
	v_mfma_f32_16x16x32_bf16 v[120:123], v[204:207], v[116:119], 0
	v_mfma_f32_16x16x32_bf16 v[116:119], v[228:231], v[116:119], 0
	v_cvt_pk_bf16_f32 v124, v142, v143
	v_cvt_pk_bf16_f32 v125, v148, v149
	v_cvt_pk_bf16_f32 v126, v150, v151
	v_cvt_pk_bf16_f32 v127, v152, v153
	ds_read_b64 v[196:197], v195 offset:128
	ds_read_b64 v[198:199], v195 offset:160
	ds_read_b64 v[200:201], v195 offset:4480
	ds_read_b64 v[202:203], v195 offset:4512
	ds_read_b64 v[204:205], v195 offset:8832
	ds_read_b64 v[206:207], v195 offset:8864
	ds_read_b64 v[228:229], v195 offset:13184
	ds_read_b64 v[230:231], v195 offset:13216
	s_waitcnt lgkmcnt(8)
	s_nop 0
	v_mfma_f32_16x16x32_bf16 v[108:111], v[232:235], v[124:127], v[108:111]
	v_mfma_f32_16x16x32_bf16 v[112:115], v[236:239], v[124:127], v[112:115]
	v_mfma_f32_16x16x32_bf16 v[120:123], v[240:243], v[124:127], v[120:123]
	v_mfma_f32_16x16x32_bf16 v[116:119], v[244:247], v[124:127], v[116:119]
	v_cvt_pk_bf16_f32 v124, v154, v155
	v_cvt_pk_bf16_f32 v125, v156, v157
	v_cvt_pk_bf16_f32 v126, v158, v159
	v_cvt_pk_bf16_f32 v127, v166, v167
	ds_read_b64 v[232:233], v195 offset:192
	ds_read_b64 v[234:235], v195 offset:224
	ds_read_b64 v[236:237], v195 offset:4544
	ds_read_b64 v[238:239], v195 offset:4576
	ds_read_b64 v[240:241], v195 offset:8896
	ds_read_b64 v[242:243], v195 offset:8928
	ds_read_b64 v[244:245], v195 offset:13248
	ds_read_b64 v[246:247], v195 offset:13280
	s_waitcnt lgkmcnt(8)
	s_nop 0
	v_mfma_f32_16x16x32_bf16 v[108:111], v[196:199], v[124:127], v[108:111]
	v_mfma_f32_16x16x32_bf16 v[112:115], v[200:203], v[124:127], v[112:115]
	v_mfma_f32_16x16x32_bf16 v[120:123], v[204:207], v[124:127], v[120:123]
	v_mfma_f32_16x16x32_bf16 v[116:119], v[228:231], v[124:127], v[116:119]
	v_cvt_pk_bf16_f32 v0, v0, v1
	v_cvt_pk_bf16_f32 v1, v2, v3
	v_cvt_pk_bf16_f32 v2, v4, v5
	v_cvt_pk_bf16_f32 v3, v6, v7
	s_waitcnt lgkmcnt(0)
	s_nop 0
	v_mfma_f32_16x16x32_bf16 v[4:7], v[232:235], v[0:3], v[108:111]
	s_nop 2
	v_mfma_f32_16x16x32_bf16 v[108:111], v[236:239], v[0:3], v[112:115]
	s_nop 2
	v_mfma_f32_16x16x32_bf16 v[112:115], v[240:243], v[0:3], v[120:123]
	v_mfma_f32_16x16x32_bf16 v[0:3], v[244:247], v[0:3], v[116:119]
	s_nop 2
	v_add_u32_e32 v116, s0, v192
	s_waitcnt vmcnt(0) lgkmcnt(0)
	v_mul_f32_e32 v107, 0xbfb8aa3b, v107
	v_exp_f32_e32 v107, v107
	s_nop 0
	v_add_f32_e32 v107, 1.0, v107
	v_rcp_f32_e32 v107, v107
	s_nop 0
	v_mul_f32_e32 v4, v4, v107
	v_mul_f32_e32 v5, v5, v107
	ds_write2st64_b32 v116, v4, v5 offset1:1
	v_mul_f32_e32 v4, v6, v107
	v_mul_f32_e32 v5, v7, v107
	ds_write2st64_b32 v116, v4, v5 offset0:2 offset1:3
	v_mul_f32_e32 v4, v108, v107
	v_mul_f32_e32 v5, v109, v107
	ds_write2st64_b32 v116, v4, v5 offset0:4 offset1:5
	v_mul_f32_e32 v4, v110, v107
	v_mul_f32_e32 v5, v111, v107
	ds_write2st64_b32 v116, v4, v5 offset0:6 offset1:7
	v_mul_f32_e32 v4, v112, v107
	v_mul_f32_e32 v5, v113, v107
	v_mul_f32_e32 v0, v0, v107
	v_mul_f32_e32 v1, v1, v107
	ds_write2st64_b32 v116, v4, v5 offset0:8 offset1:9
	v_mul_f32_e32 v4, v114, v107
	v_mul_f32_e32 v5, v115, v107
	ds_write2st64_b32 v116, v0, v1 offset0:12 offset1:13
	v_mul_f32_e32 v0, v2, v107
	v_mul_f32_e32 v1, v3, v107
	ds_write2st64_b32 v116, v4, v5 offset0:10 offset1:11
	ds_write2st64_b32 v116, v0, v1 offset0:14 offset1:15
	s_addk_i32 s0, 0x1000
	s_add_i32 s82, s82, 1
	v_lshl_add_u64 v[102:103], v[102:103], 0, 12
	s_cmpk_eq_i32 s0, 0x4000
	v_lshl_add_u64 v[104:105], v[104:105], 0, s[96:97]
	s_cbranch_scc0 .LBB0_188
	s_or_b32 s0, s95, s81
	v_or_b32_e32 v0, s0, v190
	v_ashrrev_i32_e32 v1, 31, v0
	v_lshlrev_b64 v[2:3], 7, v[0:1]
	v_lshl_add_u64 v[2:3], s[86:87], 0, v[2:3]
	s_mul_i32 s82, s2, 48
	v_lshl_add_u64 v[2:3], v[2:3], 0, s[82:83]
	s_mov_b64 s[0:1], 0x2f200020
	v_lshl_add_u64 v[148:149], v[2:3], 0, s[0:1]
	s_lshl_b32 s0, s2, 2
	s_or_b32 s1, s0, 1
	v_cvt_f32_ubyte0_e32 v2, s1
	v_cmp_lt_f32_e32 vcc, s72, v2
	s_or_b32 s1, s0, 2
	v_cvt_f32_ubyte0_e32 v3, s1
	v_cndmask_b32_e32 v6, 0, v220, vcc
	v_sub_f32_e32 v2, v6, v2
	v_exp_f32_e32 v2, v2
	s_or_b32 s1, s0, 3
	s_add_i32 s0, s0, 4
	v_cvt_f32_ubyte0_e32 v4, s1
	v_cvt_f32_ubyte0_e32 v5, s0
	s_and_b64 s[0:1], vcc, exec
	s_cselect_b32 s0, 0xffffffc0, 0
	v_cmp_lt_f32_e32 vcc, s72, v3
	v_ldexp_f32 v34, v2, s0
	s_and_b64 s[0:1], vcc, exec
	v_cndmask_b32_e32 v2, 0, v220, vcc
	v_sub_f32_e32 v2, v2, v3
	v_exp_f32_e32 v2, v2
	s_cselect_b32 s0, 0xffffffc0, 0
	v_cmp_lt_f32_e32 vcc, s72, v4
	v_and_or_b32 v17, v211, 64, v190
	v_ldexp_f32 v35, v2, s0
	v_cndmask_b32_e32 v2, 0, v220, vcc
	v_sub_f32_e32 v2, v2, v4
	v_exp_f32_e32 v2, v2
	s_and_b64 s[0:1], vcc, exec
	s_cselect_b32 s0, 0xffffffc0, 0
	v_cmp_lt_f32_e32 vcc, s72, v5
	v_ldexp_f32 v36, v2, s0
	s_and_b64 s[0:1], vcc, exec
	v_cndmask_b32_e32 v2, 0, v220, vcc
	v_sub_f32_e32 v2, v2, v5
	v_exp_f32_e32 v2, v2
	s_cselect_b32 s0, 0xffffffc0, 0
	s_lshr_b32 s20, s81, 6
	s_add_i32 s22, s20, -1
	v_cmp_eq_u32_e64 s[4:5], s20, v32
	v_cmp_eq_u32_e64 s[6:7], s22, v32
	v_ldexp_f32 v37, v2, s0
	v_cmp_gt_u32_e64 s[0:1], 16, v106
	s_or_b64 s[4:5], s[4:5], s[6:7]
	s_or_b64 s[0:1], s[4:5], s[0:1]
	v_cmp_lt_i32_e32 vcc, s20, v32
	v_cndmask_b32_e64 v2, v14, v222, s[0:1]
	v_lshlrev_b32_e32 v17, 2, v17
	v_cndmask_b32_e32 v14, v2, v221, vcc
	v_add_u32_e32 v2, 4, v32
	v_cmp_eq_u32_e64 s[0:1], 0, v2
	v_cmp_eq_u32_e64 s[6:7], s20, v2
	s_or_b64 s[6:7], s[0:1], s[6:7]
	v_cmp_eq_u32_e64 s[0:1], s22, v2
	s_or_b64 s[0:1], s[6:7], s[0:1]
	v_cmp_lt_i32_e64 s[4:5], s20, v2
	v_cndmask_b32_e64 v3, v15, v222, s[0:1]
	ds_bpermute_b32 v18, v17, v14
	v_cndmask_b32_e64 v15, v3, v221, s[4:5]
	v_add_u32_e32 v3, 8, v32
	v_cmp_eq_u32_e64 s[0:1], 0, v3
	v_cmp_eq_u32_e64 s[8:9], s20, v3
	s_or_b64 s[8:9], s[0:1], s[8:9]
	v_cmp_eq_u32_e64 s[0:1], s22, v3
	s_or_b64 s[0:1], s[8:9], s[0:1]
	v_cmp_lt_i32_e64 s[6:7], s20, v3
	v_cndmask_b32_e64 v4, v12, v222, s[0:1]
	v_cmp_lt_i32_e64 s[24:25], -8, v32
	v_cndmask_b32_e64 v12, v4, v221, s[6:7]
	v_add_u32_e32 v4, 12, v32
	v_cmp_eq_u32_e64 s[0:1], 0, v4
	v_cmp_eq_u32_e64 s[10:11], s20, v4
	s_or_b64 s[10:11], s[0:1], s[10:11]
	v_cmp_eq_u32_e64 s[0:1], s22, v4
	s_or_b64 s[0:1], s[10:11], s[0:1]
	v_cmp_lt_i32_e64 s[8:9], s20, v4
	v_cndmask_b32_e64 v5, v13, v222, s[0:1]
	v_cmp_lt_i32_e64 s[28:29], -12, v32
	v_cndmask_b32_e64 v13, v5, v221, s[8:9]
	v_add_u32_e32 v5, 16, v32
	v_cmp_eq_u32_e64 s[0:1], 0, v5
	v_cmp_eq_u32_e64 s[12:13], s20, v5
	s_or_b64 s[12:13], s[0:1], s[12:13]
	v_cmp_eq_u32_e64 s[0:1], s22, v5
	s_or_b64 s[0:1], s[12:13], s[0:1]
	v_cmp_lt_i32_e64 s[10:11], s20, v5
	v_cndmask_b32_e64 v6, v10, v222, s[0:1]
	v_cmp_lt_i32_e64 s[34:35], -16, v32
	v_cndmask_b32_e64 v10, v6, v221, s[10:11]
	v_add_u32_e32 v6, 20, v32
	v_cmp_eq_u32_e64 s[0:1], 0, v6
	v_cmp_eq_u32_e64 s[14:15], s20, v6
	s_or_b64 s[14:15], s[0:1], s[14:15]
	v_cmp_eq_u32_e64 s[0:1], s22, v6
	s_or_b64 s[0:1], s[14:15], s[0:1]
	v_cmp_lt_i32_e64 s[12:13], s20, v6
	v_cndmask_b32_e64 v7, v11, v222, s[0:1]
	s_movk_i32 s30, 0xffe8
	v_cndmask_b32_e64 v11, v7, v221, s[12:13]
	v_add_u32_e32 v7, 24, v32
	v_cmp_eq_u32_e64 s[0:1], 0, v7
	v_cmp_eq_u32_e64 s[16:17], s20, v7
	s_or_b64 s[16:17], s[0:1], s[16:17]
	v_cmp_eq_u32_e64 s[0:1], s22, v7
	s_or_b64 s[0:1], s[16:17], s[0:1]
	v_cmp_lt_i32_e64 s[14:15], s20, v7
	v_cndmask_b32_e64 v8, v8, v222, s[0:1]
	s_waitcnt lgkmcnt(0)
	v_cmp_eq_f32_e64 s[26:27], v11, v18
	v_cndmask_b32_e64 v16, v8, v221, s[14:15]
	v_add_u32_e32 v8, 28, v32
	v_cmp_lt_i32_e64 s[16:17], s20, v8
	v_cmp_eq_u32_e64 s[0:1], 0, v8
	v_cmp_eq_u32_e64 s[20:21], s20, v8
	s_or_b64 s[20:21], s[0:1], s[20:21]
	v_cmp_eq_u32_e64 s[0:1], s22, v8
	s_or_b64 s[0:1], s[20:21], s[0:1]
	v_cmp_eq_f32_e64 s[20:21], v14, v18
	v_cndmask_b32_e64 v9, v9, v222, s[0:1]
	v_cmp_lt_f32_e64 s[0:1], v14, v18
	s_and_b64 s[20:21], s[18:19], s[20:21]
	s_or_b64 s[0:1], s[0:1], s[20:21]
	v_cmp_eq_f32_e64 s[22:23], v15, v18
	v_cmp_lt_i32_e64 s[20:21], -4, v32
	v_cndmask_b32_e64 v19, 0, 1, s[0:1]
	v_cmp_lt_f32_e64 s[0:1], v15, v18
	s_and_b64 s[22:23], s[20:21], s[22:23]
	s_or_b64 s[0:1], s[0:1], s[22:23]
	v_cmp_eq_f32_e64 s[22:23], v12, v18
	v_cndmask_b32_e64 v20, 0, 1, s[0:1]
	v_cmp_lt_f32_e64 s[0:1], v12, v18
	s_and_b64 s[22:23], s[24:25], s[22:23]
	s_or_b64 s[0:1], s[0:1], s[22:23]
	v_cmp_eq_f32_e64 s[22:23], v13, v18
	v_cndmask_b32_e64 v21, 0, 1, s[0:1]
	v_cmp_lt_f32_e64 s[0:1], v13, v18
	s_and_b64 s[22:23], s[28:29], s[22:23]
	s_or_b64 s[0:1], s[0:1], s[22:23]
	v_cmp_eq_f32_e64 s[22:23], v10, v18
	v_cndmask_b32_e64 v22, 0, 1, s[0:1]
	v_cmp_lt_f32_e64 s[0:1], v10, v18
	s_and_b64 s[22:23], s[34:35], s[22:23]
	s_or_b64 s[0:1], s[0:1], s[22:23]
	v_cndmask_b32_e64 v23, 0, 1, s[0:1]
	s_movk_i32 s0, 0xffec
	v_cmp_lt_i32_e64 s[0:1], s0, v32
	v_cmp_lt_f32_e64 s[22:23], v11, v18
	s_and_b64 s[26:27], s[0:1], s[26:27]
	s_or_b64 s[22:23], s[22:23], s[26:27]
	v_cmp_eq_f32_e64 s[26:27], v16, v18
	v_cmp_lt_i32_e64 s[30:31], s30, v32
	ds_bpermute_b32 v26, v17, v15
	v_cndmask_b32_e64 v9, v9, v221, s[16:17]
	v_cndmask_b32_e64 v24, 0, 1, s[22:23]
	v_cmp_lt_f32_e64 s[22:23], v16, v18
	s_and_b64 s[26:27], s[30:31], s[26:27]
	s_movk_i32 s36, 0xffe4
	s_or_b64 s[22:23], s[22:23], s[26:27]
	v_cmp_eq_f32_e64 s[26:27], v9, v18
	v_cmp_lt_i32_e64 s[36:37], s36, v32
	v_cndmask_b32_e64 v25, 0, 1, s[22:23]
	v_cmp_lt_f32_e64 s[22:23], v9, v18
	s_and_b64 s[26:27], s[36:37], s[26:27]
	s_or_b64 s[22:23], s[22:23], s[26:27]
	v_cndmask_b32_e64 v18, 0, 1, s[22:23]
	s_waitcnt lgkmcnt(0)
	v_cmp_eq_f32_e64 s[36:37], v14, v26
	v_cmp_lt_i32_e64 s[22:23], 4, v32
	v_cmp_lt_f32_e64 s[26:27], v14, v26
	s_and_b64 s[36:37], s[22:23], s[36:37]
	s_or_b64 s[26:27], s[26:27], s[36:37]
	v_addc_co_u32_e64 v19, s[26:27], 0, v19, s[26:27]
	v_cmp_eq_f32_e64 s[36:37], v15, v26
	v_cmp_lt_f32_e64 s[26:27], v15, v26
	s_and_b64 s[36:37], s[18:19], s[36:37]
	s_or_b64 s[26:27], s[26:27], s[36:37]
	v_cmp_eq_f32_e64 s[36:37], v12, v26
	v_cndmask_b32_e64 v27, 0, 1, s[26:27]
	v_cmp_lt_f32_e64 s[26:27], v12, v26
	s_and_b64 s[36:37], s[20:21], s[36:37]
	s_or_b64 s[26:27], s[26:27], s[36:37]
	v_addc_co_u32_e64 v21, s[26:27], 0, v21, s[26:27]
	v_cmp_eq_f32_e64 s[36:37], v13, v26
	v_cmp_lt_f32_e64 s[26:27], v13, v26
	s_and_b64 s[36:37], s[24:25], s[36:37]
	s_or_b64 s[26:27], s[26:27], s[36:37]
	v_cmp_eq_f32_e64 s[36:37], v10, v26
	v_add_u32_e32 v20, v27, v20
	v_cndmask_b32_e64 v27, 0, 1, s[26:27]
	v_cmp_lt_f32_e64 s[26:27], v10, v26
	s_and_b64 s[36:37], s[28:29], s[36:37]
	s_or_b64 s[26:27], s[26:27], s[36:37]
	v_addc_co_u32_e64 v23, s[26:27], 0, v23, s[26:27]
	v_cmp_eq_f32_e64 s[36:37], v11, v26
	v_cmp_lt_f32_e64 s[26:27], v11, v26
	s_and_b64 s[36:37], s[34:35], s[36:37]
	s_or_b64 s[26:27], s[26:27], s[36:37]
	v_cmp_eq_f32_e64 s[36:37], v16, v26
	v_cndmask_b32_e64 v28, 0, 1, s[26:27]
	v_cmp_lt_f32_e64 s[26:27], v16, v26
	s_and_b64 s[36:37], s[0:1], s[36:37]
	ds_bpermute_b32 v29, v17, v12
	s_or_b64 s[26:27], s[26:27], s[36:37]
	v_addc_co_u32_e64 v25, s[26:27], 0, v25, s[26:27]
	v_cmp_eq_f32_e64 s[36:37], v9, v26
	v_cmp_lt_f32_e64 s[26:27], v9, v26
	s_and_b64 s[30:31], s[30:31], s[36:37]
	s_or_b64 s[26:27], s[26:27], s[30:31]
	v_cndmask_b32_e64 v26, 0, 1, s[26:27]
	s_waitcnt lgkmcnt(0)
	v_cmp_eq_f32_e64 s[36:37], v14, v29
	v_cmp_lt_i32_e64 s[26:27], 8, v32
	v_cmp_lt_f32_e64 s[30:31], v14, v29
	s_and_b64 s[36:37], s[26:27], s[36:37]
	s_or_b64 s[30:31], s[30:31], s[36:37]
	v_cmp_eq_f32_e64 s[36:37], v15, v29
	v_cndmask_b32_e64 v30, 0, 1, s[30:31]
	v_cmp_lt_f32_e64 s[30:31], v15, v29
	s_and_b64 s[36:37], s[22:23], s[36:37]
	s_or_b64 s[30:31], s[30:31], s[36:37]
	v_cmp_eq_f32_e64 s[36:37], v12, v29
	v_cndmask_b32_e64 v31, 0, 1, s[30:31]
	v_cmp_lt_f32_e64 s[30:31], v12, v29
	s_and_b64 s[36:37], s[18:19], s[36:37]
	s_or_b64 s[30:31], s[30:31], s[36:37]
	v_cmp_eq_f32_e64 s[36:37], v13, v29
	v_cndmask_b32_e64 v38, 0, 1, s[30:31]
	v_cmp_lt_f32_e64 s[30:31], v13, v29
	s_and_b64 s[36:37], s[20:21], s[36:37]
	s_or_b64 s[30:31], s[30:31], s[36:37]
	v_addc_co_u32_e64 v22, s[30:31], v27, v22, s[30:31]
	v_cmp_eq_f32_e64 s[36:37], v10, v29
	v_cmp_lt_f32_e64 s[30:31], v10, v29
	s_and_b64 s[36:37], s[24:25], s[36:37]
	s_or_b64 s[30:31], s[30:31], s[36:37]
	v_cmp_eq_f32_e64 s[36:37], v11, v29
	v_cndmask_b32_e64 v27, 0, 1, s[30:31]
	v_cmp_lt_f32_e64 s[30:31], v11, v29
	s_and_b64 s[36:37], s[28:29], s[36:37]
	s_or_b64 s[30:31], s[30:31], s[36:37]
	v_addc_co_u32_e64 v24, s[30:31], v28, v24, s[30:31]
	v_cmp_eq_f32_e64 s[36:37], v16, v29
	v_cmp_lt_f32_e64 s[30:31], v16, v29
	s_and_b64 s[36:37], s[34:35], s[36:37]
	s_or_b64 s[30:31], s[30:31], s[36:37]
	v_cmp_eq_f32_e64 s[36:37], v9, v29
	v_cndmask_b32_e64 v28, 0, 1, s[30:31]
	v_cmp_lt_f32_e64 s[30:31], v9, v29
	s_and_b64 s[0:1], s[0:1], s[36:37]
	s_or_b64 s[0:1], s[30:31], s[0:1]
	v_addc_co_u32_e64 v18, s[0:1], v26, v18, s[0:1]
	ds_bpermute_b32 v26, v17, v13
	v_cmp_lt_i32_e64 s[30:31], 12, v32
	v_lshlrev_b32_e64 v2, v2, 1
	v_lshlrev_b32_e64 v3, v3, 1
	v_lshlrev_b32_e64 v4, v4, 1
	s_waitcnt lgkmcnt(0)
	v_cmp_eq_f32_e64 s[36:37], v14, v26
	v_cmp_lt_f32_e64 s[0:1], v14, v26
	s_and_b64 s[36:37], s[30:31], s[36:37]
	s_or_b64 s[0:1], s[0:1], s[36:37]
	v_addc_co_u32_e64 v19, s[0:1], v19, v30, s[0:1]
	v_cmp_eq_f32_e64 s[36:37], v15, v26
	v_cmp_lt_f32_e64 s[0:1], v15, v26
	s_and_b64 s[36:37], s[26:27], s[36:37]
	s_or_b64 s[0:1], s[0:1], s[36:37]
	v_addc_co_u32_e64 v20, s[0:1], v20, v31, s[0:1]
	v_cmp_eq_f32_e64 s[36:37], v12, v26
	v_cmp_lt_f32_e64 s[0:1], v12, v26
	s_and_b64 s[36:37], s[22:23], s[36:37]
	s_or_b64 s[0:1], s[0:1], s[36:37]
	v_addc_co_u32_e64 v21, s[0:1], v21, v38, s[0:1]
	v_cmp_eq_f32_e64 s[36:37], v13, v26
	v_cmp_lt_f32_e64 s[0:1], v13, v26
	s_and_b64 s[36:37], s[18:19], s[36:37]
	s_or_b64 s[0:1], s[0:1], s[36:37]
	v_cmp_eq_f32_e64 s[36:37], v10, v26
	v_cndmask_b32_e64 v29, 0, 1, s[0:1]
	v_cmp_lt_f32_e64 s[0:1], v10, v26
	s_and_b64 s[36:37], s[20:21], s[36:37]
	s_or_b64 s[0:1], s[0:1], s[36:37]
	v_addc_co_u32_e64 v23, s[0:1], v23, v27, s[0:1]
	v_cmp_eq_f32_e64 s[36:37], v11, v26
	v_cmp_lt_f32_e64 s[0:1], v11, v26
	s_and_b64 s[36:37], s[24:25], s[36:37]
	s_or_b64 s[0:1], s[0:1], s[36:37]
	v_cmp_eq_f32_e64 s[36:37], v16, v26
	v_cndmask_b32_e64 v27, 0, 1, s[0:1]
	v_cmp_lt_f32_e64 s[0:1], v16, v26
	s_and_b64 s[36:37], s[28:29], s[36:37]
	s_or_b64 s[0:1], s[0:1], s[36:37]
	v_addc_co_u32_e64 v25, s[0:1], v25, v28, s[0:1]
	ds_bpermute_b32 v28, v17, v10
	v_cmp_eq_f32_e64 s[36:37], v9, v26
	v_cmp_lt_f32_e64 s[0:1], v9, v26
	s_and_b64 s[34:35], s[34:35], s[36:37]
	s_or_b64 s[0:1], s[0:1], s[34:35]
	s_waitcnt lgkmcnt(0)
	v_cmp_eq_f32_e64 s[36:37], v14, v28
	v_cmp_lt_i32_e64 s[34:35], 16, v32
	v_cndmask_b32_e64 v26, 0, 1, s[0:1]
	v_cmp_lt_f32_e64 s[0:1], v14, v28
	s_and_b64 s[36:37], s[34:35], s[36:37]
	s_or_b64 s[0:1], s[0:1], s[36:37]
	v_cmp_eq_f32_e64 s[36:37], v15, v28
	v_add_u32_e32 v22, v22, v29
	v_cndmask_b32_e64 v29, 0, 1, s[0:1]
	v_cmp_lt_f32_e64 s[0:1], v15, v28
	s_and_b64 s[36:37], s[30:31], s[36:37]
	s_or_b64 s[0:1], s[0:1], s[36:37]
	v_cmp_eq_f32_e64 s[36:37], v12, v28
	v_cndmask_b32_e64 v30, 0, 1, s[0:1]
	v_cmp_lt_f32_e64 s[0:1], v12, v28
	s_and_b64 s[36:37], s[26:27], s[36:37]
	s_or_b64 s[0:1], s[0:1], s[36:37]
	v_cmp_eq_f32_e64 s[36:37], v13, v28
	v_cndmask_b32_e64 v31, 0, 1, s[0:1]
	v_cmp_lt_f32_e64 s[0:1], v13, v28
	s_and_b64 s[36:37], s[22:23], s[36:37]
	s_or_b64 s[0:1], s[0:1], s[36:37]
	v_cmp_eq_f32_e64 s[36:37], v10, v28
	v_cndmask_b32_e64 v38, 0, 1, s[0:1]
	v_cmp_lt_f32_e64 s[0:1], v10, v28
	s_and_b64 s[36:37], s[18:19], s[36:37]
	s_or_b64 s[0:1], s[0:1], s[36:37]
	v_cmp_eq_f32_e64 s[36:37], v11, v28
	v_cndmask_b32_e64 v39, 0, 1, s[0:1]
	v_cmp_lt_f32_e64 s[0:1], v11, v28
	s_and_b64 s[36:37], s[20:21], s[36:37]
	s_or_b64 s[0:1], s[0:1], s[36:37]
	v_addc_co_u32_e64 v24, s[0:1], v24, v27, s[0:1]
	v_cmp_eq_f32_e64 s[36:37], v16, v28
	v_cmp_lt_f32_e64 s[0:1], v16, v28
	s_and_b64 s[36:37], s[24:25], s[36:37]
	s_or_b64 s[0:1], s[0:1], s[36:37]
	v_cmp_eq_f32_e64 s[36:37], v9, v28
	v_cndmask_b32_e64 v27, 0, 1, s[0:1]
	v_cmp_lt_f32_e64 s[0:1], v9, v28
	s_and_b64 s[28:29], s[28:29], s[36:37]
	s_or_b64 s[0:1], s[0:1], s[28:29]
	v_addc_co_u32_e64 v18, s[0:1], v18, v26, s[0:1]
	ds_bpermute_b32 v26, v17, v11
	v_cmp_lt_i32_e64 s[0:1], 20, v32
	v_lshlrev_b64 v[0:1], 10, v[0:1]
	s_mov_b32 s38, 1
	v_lshl_add_u64 v[0:1], s[86:87], 0, v[0:1]
	s_waitcnt lgkmcnt(0)
	v_cmp_eq_f32_e64 s[36:37], v14, v26
	v_cmp_lt_f32_e64 s[28:29], v14, v26
	s_and_b64 s[36:37], s[0:1], s[36:37]
	s_or_b64 s[28:29], s[28:29], s[36:37]
	v_addc_co_u32_e64 v19, s[28:29], v19, v29, s[28:29]
	v_cmp_eq_f32_e64 s[36:37], v15, v26
	v_cmp_lt_f32_e64 s[28:29], v15, v26
	s_and_b64 s[36:37], s[34:35], s[36:37]
	s_or_b64 s[28:29], s[28:29], s[36:37]
	v_addc_co_u32_e64 v20, s[28:29], v20, v30, s[28:29]
	v_cmp_eq_f32_e64 s[36:37], v12, v26
	v_cmp_lt_f32_e64 s[28:29], v12, v26
	s_and_b64 s[36:37], s[30:31], s[36:37]
	s_or_b64 s[28:29], s[28:29], s[36:37]
	v_addc_co_u32_e64 v21, s[28:29], v21, v31, s[28:29]
	v_cmp_eq_f32_e64 s[36:37], v13, v26
	v_cmp_lt_f32_e64 s[28:29], v13, v26
	s_and_b64 s[36:37], s[26:27], s[36:37]
	s_or_b64 s[28:29], s[28:29], s[36:37]
	v_addc_co_u32_e64 v22, s[28:29], v22, v38, s[28:29]
	v_cmp_eq_f32_e64 s[36:37], v10, v26
	v_cmp_lt_f32_e64 s[28:29], v10, v26
	s_and_b64 s[36:37], s[22:23], s[36:37]
	s_or_b64 s[28:29], s[28:29], s[36:37]
	v_addc_co_u32_e64 v23, s[28:29], v23, v39, s[28:29]
	v_cmp_eq_f32_e64 s[36:37], v11, v26
	v_cmp_lt_f32_e64 s[28:29], v11, v26
	s_and_b64 s[36:37], s[18:19], s[36:37]
	s_or_b64 s[28:29], s[28:29], s[36:37]
	v_cmp_eq_f32_e64 s[36:37], v16, v26
	v_cndmask_b32_e64 v28, 0, 1, s[28:29]
	v_cmp_lt_f32_e64 s[28:29], v16, v26
	s_and_b64 s[36:37], s[20:21], s[36:37]
	s_or_b64 s[28:29], s[28:29], s[36:37]
	v_addc_co_u32_e64 v25, s[28:29], v25, v27, s[28:29]
	ds_bpermute_b32 v27, v17, v16
	v_cmp_eq_f32_e64 s[36:37], v9, v26
	v_cmp_lt_f32_e64 s[28:29], v9, v26
	s_and_b64 s[24:25], s[24:25], s[36:37]
	s_or_b64 s[24:25], s[28:29], s[24:25]
	s_waitcnt lgkmcnt(0)
	v_cmp_eq_f32_e64 s[28:29], v14, v27
	v_cmp_lt_i32_e64 s[36:37], 24, v32
	v_cndmask_b32_e64 v26, 0, 1, s[24:25]
	v_cmp_lt_f32_e64 s[24:25], v14, v27
	s_and_b64 s[28:29], s[36:37], s[28:29]
	s_or_b64 s[24:25], s[24:25], s[28:29]
	v_cmp_eq_f32_e64 s[28:29], v15, v27
	v_add_u32_e32 v24, v24, v28
	v_cndmask_b32_e64 v28, 0, 1, s[24:25]
	v_cmp_lt_f32_e64 s[24:25], v15, v27
	s_and_b64 s[28:29], s[0:1], s[28:29]
	s_or_b64 s[24:25], s[24:25], s[28:29]
	v_cmp_eq_f32_e64 s[28:29], v12, v27
	v_cndmask_b32_e64 v29, 0, 1, s[24:25]
	v_cmp_lt_f32_e64 s[24:25], v12, v27
	s_and_b64 s[28:29], s[34:35], s[28:29]
	s_or_b64 s[24:25], s[24:25], s[28:29]
	v_cmp_eq_f32_e64 s[28:29], v13, v27
	v_cndmask_b32_e64 v30, 0, 1, s[24:25]
	v_cmp_lt_f32_e64 s[24:25], v13, v27
	s_and_b64 s[28:29], s[30:31], s[28:29]
	s_or_b64 s[24:25], s[24:25], s[28:29]
	v_cmp_eq_f32_e64 s[28:29], v10, v27
	v_cndmask_b32_e64 v31, 0, 1, s[24:25]
	v_cmp_lt_f32_e64 s[24:25], v10, v27
	s_and_b64 s[28:29], s[26:27], s[28:29]
	s_or_b64 s[24:25], s[24:25], s[28:29]
	v_cmp_eq_f32_e64 s[28:29], v11, v27
	v_cndmask_b32_e64 v38, 0, 1, s[24:25]
	v_cmp_lt_f32_e64 s[24:25], v11, v27
	s_and_b64 s[28:29], s[22:23], s[28:29]
	s_or_b64 s[24:25], s[24:25], s[28:29]
	v_cmp_eq_f32_e64 s[28:29], v16, v27
	v_cndmask_b32_e64 v39, 0, 1, s[24:25]
	v_cmp_lt_f32_e64 s[24:25], v16, v27
	s_and_b64 s[28:29], s[18:19], s[28:29]
	s_or_b64 s[24:25], s[24:25], s[28:29]
	v_cmp_eq_f32_e64 s[28:29], v9, v27
	v_cndmask_b32_e64 v40, 0, 1, s[24:25]
	v_cmp_lt_f32_e64 s[24:25], v9, v27
	s_and_b64 s[20:21], s[20:21], s[28:29]
	s_or_b64 s[20:21], s[24:25], s[20:21]
	v_addc_co_u32_e64 v18, s[20:21], v18, v26, s[20:21]
	ds_bpermute_b32 v26, v17, v9
	v_cmp_lt_i32_e64 s[28:29], 28, v32
	v_ashrrev_i32_e32 v33, 31, v32
	s_waitcnt lgkmcnt(0)
	v_cmp_eq_f32_e64 s[24:25], v14, v26
	v_cmp_lt_f32_e64 s[20:21], v14, v26
	s_and_b64 s[24:25], s[28:29], s[24:25]
	s_or_b64 s[20:21], s[20:21], s[24:25]
	v_addc_co_u32_e64 v19, s[20:21], v19, v28, s[20:21]
	v_cmp_eq_f32_e64 s[24:25], v15, v26
	v_cmp_lt_f32_e64 s[20:21], v15, v26
	s_and_b64 s[24:25], s[36:37], s[24:25]
	s_or_b64 s[20:21], s[20:21], s[24:25]
	v_addc_co_u32_e64 v20, s[20:21], v20, v29, s[20:21]
	v_cmp_eq_f32_e64 s[24:25], v12, v26
	v_cmp_lt_f32_e64 s[20:21], v12, v26
	s_and_b64 s[0:1], s[0:1], s[24:25]
	s_or_b64 s[0:1], s[20:21], s[0:1]
	v_addc_co_u32_e64 v21, s[0:1], v21, v30, s[0:1]
	v_cmp_eq_f32_e64 s[20:21], v13, v26
	v_cmp_lt_f32_e64 s[0:1], v13, v26
	s_and_b64 s[20:21], s[34:35], s[20:21]
	s_or_b64 s[0:1], s[0:1], s[20:21]
	v_addc_co_u32_e64 v22, s[0:1], v22, v31, s[0:1]
	v_cmp_eq_f32_e64 s[20:21], v10, v26
	v_cmp_lt_f32_e64 s[0:1], v10, v26
	s_and_b64 s[20:21], s[30:31], s[20:21]
	s_or_b64 s[0:1], s[0:1], s[20:21]
	v_addc_co_u32_e64 v23, s[0:1], v23, v38, s[0:1]
	v_cmp_eq_f32_e64 s[20:21], v11, v26
	v_cmp_lt_f32_e64 s[0:1], v11, v26
	s_and_b64 s[20:21], s[26:27], s[20:21]
	s_or_b64 s[0:1], s[0:1], s[20:21]
	v_addc_co_u32_e64 v24, s[0:1], v24, v39, s[0:1]
	v_cmp_eq_f32_e64 s[20:21], v16, v26
	v_cmp_lt_f32_e64 s[0:1], v16, v26
	s_and_b64 s[20:21], s[22:23], s[20:21]
	s_or_b64 s[0:1], s[0:1], s[20:21]
	v_addc_co_u32_e64 v25, s[0:1], v25, v40, s[0:1]
	v_cmp_eq_f32_e64 s[20:21], v9, v26
	v_cmp_lt_f32_e64 s[0:1], v9, v26
	s_and_b64 s[18:19], s[18:19], s[20:21]
	s_or_b64 s[0:1], s[0:1], s[18:19]
	v_cndmask_b32_e64 v26, 0, 1, s[0:1]
	v_add_u32_e32 v18, v18, v26
	ds_bpermute_b32 v26, v17, v14 offset:64
	v_cmp_lt_i32_e64 s[18:19], 1, v32
	v_cmp_lt_i32_e64 s[24:25], -7, v32
	v_cmp_lt_i32_e64 s[28:29], -11, v32
	v_cmp_lt_i32_e64 s[34:35], -15, v32
	s_waitcnt lgkmcnt(0)
	v_cmp_eq_f32_e64 s[20:21], v14, v26
	v_cmp_lt_f32_e64 s[0:1], v14, v26
	s_and_b64 s[20:21], s[18:19], s[20:21]
	s_or_b64 s[0:1], s[0:1], s[20:21]
	v_cmp_eq_f32_e64 s[22:23], v15, v26
	v_cmp_lt_i32_e64 s[20:21], -3, v32
	v_cndmask_b32_e64 v27, 0, 1, s[0:1]
	v_cmp_lt_f32_e64 s[0:1], v15, v26
	s_and_b64 s[22:23], s[20:21], s[22:23]
	s_or_b64 s[0:1], s[0:1], s[22:23]
	v_cmp_eq_f32_e64 s[22:23], v12, v26
	v_cndmask_b32_e64 v28, 0, 1, s[0:1]
	v_cmp_lt_f32_e64 s[0:1], v12, v26
	s_and_b64 s[22:23], s[24:25], s[22:23]
	s_or_b64 s[0:1], s[0:1], s[22:23]
	v_cmp_eq_f32_e64 s[22:23], v13, v26
	v_cndmask_b32_e64 v29, 0, 1, s[0:1]
	v_cmp_lt_f32_e64 s[0:1], v13, v26
	s_and_b64 s[22:23], s[28:29], s[22:23]
	s_or_b64 s[0:1], s[0:1], s[22:23]
	v_cmp_eq_f32_e64 s[22:23], v10, v26
	v_cndmask_b32_e64 v30, 0, 1, s[0:1]
	v_cmp_lt_f32_e64 s[0:1], v10, v26
	s_and_b64 s[22:23], s[34:35], s[22:23]
	s_or_b64 s[0:1], s[0:1], s[22:23]
	v_cndmask_b32_e64 v31, 0, 1, s[0:1]
	s_movk_i32 s0, 0xffed
	v_cmp_eq_f32_e64 s[26:27], v11, v26
	v_cmp_lt_i32_e64 s[0:1], s0, v32
	v_cmp_lt_f32_e64 s[22:23], v11, v26
	s_and_b64 s[26:27], s[0:1], s[26:27]
	s_movk_i32 s30, 0xffe9
	s_or_b64 s[22:23], s[22:23], s[26:27]
	v_cmp_eq_f32_e64 s[26:27], v16, v26
	v_cmp_lt_i32_e64 s[30:31], s30, v32
	ds_bpermute_b32 v40, v17, v15 offset:64
	v_cndmask_b32_e64 v38, 0, 1, s[22:23]
	v_cmp_lt_f32_e64 s[22:23], v16, v26
	s_and_b64 s[26:27], s[30:31], s[26:27]
	s_movk_i32 s36, 0xffe5
	s_or_b64 s[22:23], s[22:23], s[26:27]
	v_cmp_eq_f32_e64 s[26:27], v9, v26
	v_cmp_lt_i32_e64 s[36:37], s36, v32
	v_cndmask_b32_e64 v39, 0, 1, s[22:23]
	v_cmp_lt_f32_e64 s[22:23], v9, v26
	s_and_b64 s[26:27], s[36:37], s[26:27]
	s_or_b64 s[22:23], s[22:23], s[26:27]
	v_cndmask_b32_e64 v26, 0, 1, s[22:23]
	s_waitcnt lgkmcnt(0)
	v_cmp_eq_f32_e64 s[36:37], v14, v40
	v_cmp_lt_i32_e64 s[22:23], 5, v32
	v_cmp_lt_f32_e64 s[26:27], v14, v40
	s_and_b64 s[36:37], s[22:23], s[36:37]
	s_or_b64 s[26:27], s[26:27], s[36:37]
	v_addc_co_u32_e64 v19, s[26:27], v19, v27, s[26:27]
	v_cmp_eq_f32_e64 s[36:37], v15, v40
	v_cmp_lt_f32_e64 s[26:27], v15, v40
	s_and_b64 s[36:37], s[18:19], s[36:37]
	s_or_b64 s[26:27], s[26:27], s[36:37]
	v_addc_co_u32_e64 v20, s[26:27], v20, v28, s[26:27]
	v_cmp_eq_f32_e64 s[36:37], v12, v40
	v_cmp_lt_f32_e64 s[26:27], v12, v40
	s_and_b64 s[36:37], s[20:21], s[36:37]
	s_or_b64 s[26:27], s[26:27], s[36:37]
	v_addc_co_u32_e64 v21, s[26:27], v21, v29, s[26:27]
	v_cmp_eq_f32_e64 s[36:37], v13, v40
	v_cmp_lt_f32_e64 s[26:27], v13, v40
	s_and_b64 s[36:37], s[24:25], s[36:37]
	s_or_b64 s[26:27], s[26:27], s[36:37]
	v_addc_co_u32_e64 v22, s[26:27], v22, v30, s[26:27]
	v_cmp_eq_f32_e64 s[36:37], v10, v40
	v_cmp_lt_f32_e64 s[26:27], v10, v40
	s_and_b64 s[36:37], s[28:29], s[36:37]
	s_or_b64 s[26:27], s[26:27], s[36:37]
	v_addc_co_u32_e64 v23, s[26:27], v23, v31, s[26:27]
	v_cmp_eq_f32_e64 s[36:37], v11, v40
	v_cmp_lt_f32_e64 s[26:27], v11, v40
	s_and_b64 s[36:37], s[34:35], s[36:37]
	s_or_b64 s[26:27], s[26:27], s[36:37]
	v_addc_co_u32_e64 v24, s[26:27], v24, v38, s[26:27]
	v_cmp_eq_f32_e64 s[36:37], v16, v40
	v_cmp_lt_f32_e64 s[26:27], v16, v40
	s_and_b64 s[36:37], s[0:1], s[36:37]
	s_or_b64 s[26:27], s[26:27], s[36:37]
	v_addc_co_u32_e64 v25, s[26:27], v25, v39, s[26:27]
	v_cmp_eq_f32_e64 s[36:37], v9, v40
	v_cmp_lt_f32_e64 s[26:27], v9, v40
	s_and_b64 s[30:31], s[30:31], s[36:37]
	s_or_b64 s[26:27], s[26:27], s[30:31]
	v_addc_co_u32_e64 v18, s[26:27], v18, v26, s[26:27]
	ds_bpermute_b32 v26, v17, v12 offset:64
	v_cmp_lt_i32_e64 s[26:27], 9, v32
	ds_bpermute_b32 v40, v17, v13 offset:64
	s_waitcnt lgkmcnt(1)
	v_cmp_eq_f32_e64 s[36:37], v14, v26
	v_cmp_lt_f32_e64 s[30:31], v14, v26
	s_and_b64 s[36:37], s[26:27], s[36:37]
	s_or_b64 s[30:31], s[30:31], s[36:37]
	v_cmp_eq_f32_e64 s[36:37], v15, v26
	v_cndmask_b32_e64 v27, 0, 1, s[30:31]
	v_cmp_lt_f32_e64 s[30:31], v15, v26
	s_and_b64 s[36:37], s[22:23], s[36:37]
	s_or_b64 s[30:31], s[30:31], s[36:37]
	v_cmp_eq_f32_e64 s[36:37], v12, v26
	v_cndmask_b32_e64 v28, 0, 1, s[30:31]
	v_cmp_lt_f32_e64 s[30:31], v12, v26
	s_and_b64 s[36:37], s[18:19], s[36:37]
	s_or_b64 s[30:31], s[30:31], s[36:37]
	v_cmp_eq_f32_e64 s[36:37], v13, v26
	v_cndmask_b32_e64 v29, 0, 1, s[30:31]
	v_cmp_lt_f32_e64 s[30:31], v13, v26
	s_and_b64 s[36:37], s[20:21], s[36:37]
	s_or_b64 s[30:31], s[30:31], s[36:37]
	v_cmp_eq_f32_e64 s[36:37], v10, v26
	v_cndmask_b32_e64 v30, 0, 1, s[30:31]
	v_cmp_lt_f32_e64 s[30:31], v10, v26
	s_and_b64 s[36:37], s[24:25], s[36:37]
	s_or_b64 s[30:31], s[30:31], s[36:37]
	v_cmp_eq_f32_e64 s[36:37], v11, v26
	v_cndmask_b32_e64 v31, 0, 1, s[30:31]
	v_cmp_lt_f32_e64 s[30:31], v11, v26
	s_and_b64 s[36:37], s[28:29], s[36:37]
	s_or_b64 s[30:31], s[30:31], s[36:37]
	v_cmp_eq_f32_e64 s[36:37], v16, v26
	v_cndmask_b32_e64 v38, 0, 1, s[30:31]
	v_cmp_lt_f32_e64 s[30:31], v16, v26
	s_and_b64 s[36:37], s[34:35], s[36:37]
	s_or_b64 s[30:31], s[30:31], s[36:37]
	v_cmp_eq_f32_e64 s[36:37], v9, v26
	v_cndmask_b32_e64 v39, 0, 1, s[30:31]
	v_cmp_lt_f32_e64 s[30:31], v9, v26
	s_and_b64 s[0:1], s[0:1], s[36:37]
	s_or_b64 s[0:1], s[30:31], s[0:1]
	s_waitcnt lgkmcnt(0)
	v_cmp_eq_f32_e64 s[36:37], v14, v40
	v_cmp_lt_i32_e64 s[30:31], 13, v32
	v_cndmask_b32_e64 v26, 0, 1, s[0:1]
	v_cmp_lt_f32_e64 s[0:1], v14, v40
	s_and_b64 s[36:37], s[30:31], s[36:37]
	s_or_b64 s[0:1], s[0:1], s[36:37]
	v_addc_co_u32_e64 v19, s[0:1], v19, v27, s[0:1]
	v_cmp_eq_f32_e64 s[36:37], v15, v40
	v_cmp_lt_f32_e64 s[0:1], v15, v40
	s_and_b64 s[36:37], s[26:27], s[36:37]
	s_or_b64 s[0:1], s[0:1], s[36:37]
	v_addc_co_u32_e64 v20, s[0:1], v20, v28, s[0:1]
	v_cmp_eq_f32_e64 s[36:37], v12, v40
	v_cmp_lt_f32_e64 s[0:1], v12, v40
	s_and_b64 s[36:37], s[22:23], s[36:37]
	s_or_b64 s[0:1], s[0:1], s[36:37]
	v_addc_co_u32_e64 v21, s[0:1], v21, v29, s[0:1]
	v_cmp_eq_f32_e64 s[36:37], v13, v40
	v_cmp_lt_f32_e64 s[0:1], v13, v40
	s_and_b64 s[36:37], s[18:19], s[36:37]
	s_or_b64 s[0:1], s[0:1], s[36:37]
	v_addc_co_u32_e64 v22, s[0:1], v22, v30, s[0:1]
	v_cmp_eq_f32_e64 s[36:37], v10, v40
	v_cmp_lt_f32_e64 s[0:1], v10, v40
	s_and_b64 s[36:37], s[20:21], s[36:37]
	s_or_b64 s[0:1], s[0:1], s[36:37]
	v_addc_co_u32_e64 v23, s[0:1], v23, v31, s[0:1]
	v_cmp_eq_f32_e64 s[36:37], v11, v40
	v_cmp_lt_f32_e64 s[0:1], v11, v40
	s_and_b64 s[36:37], s[24:25], s[36:37]
	s_or_b64 s[0:1], s[0:1], s[36:37]
	v_addc_co_u32_e64 v24, s[0:1], v24, v38, s[0:1]
	v_cmp_eq_f32_e64 s[36:37], v16, v40
	v_cmp_lt_f32_e64 s[0:1], v16, v40
	s_and_b64 s[36:37], s[28:29], s[36:37]
	s_or_b64 s[0:1], s[0:1], s[36:37]
	v_addc_co_u32_e64 v25, s[0:1], v25, v39, s[0:1]
	v_cmp_eq_f32_e64 s[36:37], v9, v40
	v_cmp_lt_f32_e64 s[0:1], v9, v40
	s_and_b64 s[34:35], s[34:35], s[36:37]
	s_or_b64 s[0:1], s[0:1], s[34:35]
	v_addc_co_u32_e64 v18, s[0:1], v18, v26, s[0:1]
	ds_bpermute_b32 v26, v17, v10 offset:64
	v_cmp_lt_i32_e64 s[34:35], 17, v32
	ds_bpermute_b32 v40, v17, v11 offset:64
	s_waitcnt lgkmcnt(1)
	v_cmp_eq_f32_e64 s[36:37], v14, v26
	v_cmp_lt_f32_e64 s[0:1], v14, v26
	s_and_b64 s[36:37], s[34:35], s[36:37]
	s_or_b64 s[0:1], s[0:1], s[36:37]
	v_cmp_eq_f32_e64 s[36:37], v15, v26
	v_cndmask_b32_e64 v27, 0, 1, s[0:1]
	v_cmp_lt_f32_e64 s[0:1], v15, v26
	s_and_b64 s[36:37], s[30:31], s[36:37]
	s_or_b64 s[0:1], s[0:1], s[36:37]
	v_cmp_eq_f32_e64 s[36:37], v12, v26
	v_cndmask_b32_e64 v28, 0, 1, s[0:1]
	v_cmp_lt_f32_e64 s[0:1], v12, v26
	s_and_b64 s[36:37], s[26:27], s[36:37]
	s_or_b64 s[0:1], s[0:1], s[36:37]
	v_cmp_eq_f32_e64 s[36:37], v13, v26
	v_cndmask_b32_e64 v29, 0, 1, s[0:1]
	v_cmp_lt_f32_e64 s[0:1], v13, v26
	s_and_b64 s[36:37], s[22:23], s[36:37]
	s_or_b64 s[0:1], s[0:1], s[36:37]
	v_cmp_eq_f32_e64 s[36:37], v10, v26
	v_cndmask_b32_e64 v30, 0, 1, s[0:1]
	v_cmp_lt_f32_e64 s[0:1], v10, v26
	s_and_b64 s[36:37], s[18:19], s[36:37]
	s_or_b64 s[0:1], s[0:1], s[36:37]
	v_cmp_eq_f32_e64 s[36:37], v11, v26
	v_cndmask_b32_e64 v31, 0, 1, s[0:1]
	v_cmp_lt_f32_e64 s[0:1], v11, v26
	s_and_b64 s[36:37], s[20:21], s[36:37]
	s_or_b64 s[0:1], s[0:1], s[36:37]
	v_cmp_eq_f32_e64 s[36:37], v16, v26
	v_cndmask_b32_e64 v38, 0, 1, s[0:1]
	v_cmp_lt_f32_e64 s[0:1], v16, v26
	s_and_b64 s[36:37], s[24:25], s[36:37]
	s_or_b64 s[0:1], s[0:1], s[36:37]
	v_cmp_eq_f32_e64 s[36:37], v9, v26
	v_cndmask_b32_e64 v39, 0, 1, s[0:1]
	v_cmp_lt_f32_e64 s[0:1], v9, v26
	s_and_b64 s[28:29], s[28:29], s[36:37]
	s_or_b64 s[0:1], s[0:1], s[28:29]
	v_cndmask_b32_e64 v26, 0, 1, s[0:1]
	s_waitcnt lgkmcnt(0)
	v_cmp_eq_f32_e64 s[36:37], v14, v40
	v_cmp_lt_i32_e64 s[0:1], 21, v32
	v_cmp_lt_f32_e64 s[28:29], v14, v40
	s_and_b64 s[36:37], s[0:1], s[36:37]
	s_or_b64 s[28:29], s[28:29], s[36:37]
	v_addc_co_u32_e64 v19, s[28:29], v19, v27, s[28:29]
	v_cmp_eq_f32_e64 s[36:37], v15, v40
	v_cmp_lt_f32_e64 s[28:29], v15, v40
	s_and_b64 s[36:37], s[34:35], s[36:37]
	s_or_b64 s[28:29], s[28:29], s[36:37]
	v_addc_co_u32_e64 v20, s[28:29], v20, v28, s[28:29]
	v_cmp_eq_f32_e64 s[36:37], v12, v40
	v_cmp_lt_f32_e64 s[28:29], v12, v40
	s_and_b64 s[36:37], s[30:31], s[36:37]
	s_or_b64 s[28:29], s[28:29], s[36:37]
	v_addc_co_u32_e64 v21, s[28:29], v21, v29, s[28:29]
	v_cmp_eq_f32_e64 s[36:37], v13, v40
	v_cmp_lt_f32_e64 s[28:29], v13, v40
	s_and_b64 s[36:37], s[26:27], s[36:37]
	s_or_b64 s[28:29], s[28:29], s[36:37]
	v_addc_co_u32_e64 v22, s[28:29], v22, v30, s[28:29]
	v_cmp_eq_f32_e64 s[36:37], v10, v40
	v_cmp_lt_f32_e64 s[28:29], v10, v40
	s_and_b64 s[36:37], s[22:23], s[36:37]
	s_or_b64 s[28:29], s[28:29], s[36:37]
	v_addc_co_u32_e64 v23, s[28:29], v23, v31, s[28:29]
	v_cmp_eq_f32_e64 s[36:37], v11, v40
	v_cmp_lt_f32_e64 s[28:29], v11, v40
	s_and_b64 s[36:37], s[18:19], s[36:37]
	s_or_b64 s[28:29], s[28:29], s[36:37]
	v_addc_co_u32_e64 v24, s[28:29], v24, v38, s[28:29]
	v_cmp_eq_f32_e64 s[36:37], v16, v40
	v_cmp_lt_f32_e64 s[28:29], v16, v40
	s_and_b64 s[36:37], s[20:21], s[36:37]
	s_or_b64 s[28:29], s[28:29], s[36:37]
	v_addc_co_u32_e64 v25, s[28:29], v25, v39, s[28:29]
	v_cmp_eq_f32_e64 s[36:37], v9, v40
	v_cmp_lt_f32_e64 s[28:29], v9, v40
	s_and_b64 s[24:25], s[24:25], s[36:37]
	s_or_b64 s[24:25], s[28:29], s[24:25]
	v_addc_co_u32_e64 v18, s[24:25], v18, v26, s[24:25]
	ds_bpermute_b32 v26, v17, v16 offset:64
	v_cmp_lt_i32_e64 s[36:37], 25, v32
	ds_bpermute_b32 v40, v17, v9 offset:64
	s_waitcnt lgkmcnt(1)
	v_cmp_eq_f32_e64 s[28:29], v14, v26
	v_cmp_lt_f32_e64 s[24:25], v14, v26
	s_and_b64 s[28:29], s[36:37], s[28:29]
	s_or_b64 s[24:25], s[24:25], s[28:29]
	v_cmp_eq_f32_e64 s[28:29], v15, v26
	v_cndmask_b32_e64 v27, 0, 1, s[24:25]
	v_cmp_lt_f32_e64 s[24:25], v15, v26
	s_and_b64 s[28:29], s[0:1], s[28:29]
	s_or_b64 s[24:25], s[24:25], s[28:29]
	v_cmp_eq_f32_e64 s[28:29], v12, v26
	v_cndmask_b32_e64 v28, 0, 1, s[24:25]
	v_cmp_lt_f32_e64 s[24:25], v12, v26
	s_and_b64 s[28:29], s[34:35], s[28:29]
	s_or_b64 s[24:25], s[24:25], s[28:29]
	v_cmp_eq_f32_e64 s[28:29], v13, v26
	v_cndmask_b32_e64 v29, 0, 1, s[24:25]
	v_cmp_lt_f32_e64 s[24:25], v13, v26
	s_and_b64 s[28:29], s[30:31], s[28:29]
	s_or_b64 s[24:25], s[24:25], s[28:29]
	v_cmp_eq_f32_e64 s[28:29], v10, v26
	v_cndmask_b32_e64 v30, 0, 1, s[24:25]
	v_cmp_lt_f32_e64 s[24:25], v10, v26
	s_and_b64 s[28:29], s[26:27], s[28:29]
	s_or_b64 s[24:25], s[24:25], s[28:29]
	v_cmp_eq_f32_e64 s[28:29], v11, v26
	v_cndmask_b32_e64 v31, 0, 1, s[24:25]
	v_cmp_lt_f32_e64 s[24:25], v11, v26
	s_and_b64 s[28:29], s[22:23], s[28:29]
	s_or_b64 s[24:25], s[24:25], s[28:29]
	v_cmp_eq_f32_e64 s[28:29], v16, v26
	v_cndmask_b32_e64 v38, 0, 1, s[24:25]
	v_cmp_lt_f32_e64 s[24:25], v16, v26
	s_and_b64 s[28:29], s[18:19], s[28:29]
	s_or_b64 s[24:25], s[24:25], s[28:29]
	v_cmp_eq_f32_e64 s[28:29], v9, v26
	v_cndmask_b32_e64 v39, 0, 1, s[24:25]
	v_cmp_lt_f32_e64 s[24:25], v9, v26
	s_and_b64 s[20:21], s[20:21], s[28:29]
	s_or_b64 s[20:21], s[24:25], s[20:21]
	s_waitcnt lgkmcnt(0)
	v_cmp_eq_f32_e64 s[24:25], v14, v40
	v_cmp_lt_i32_e64 s[28:29], 29, v32
	v_cndmask_b32_e64 v26, 0, 1, s[20:21]
	v_cmp_lt_f32_e64 s[20:21], v14, v40
	s_and_b64 s[24:25], s[28:29], s[24:25]
	s_or_b64 s[20:21], s[20:21], s[24:25]
	v_addc_co_u32_e64 v19, s[20:21], v19, v27, s[20:21]
	v_cmp_eq_f32_e64 s[24:25], v15, v40
	v_cmp_lt_f32_e64 s[20:21], v15, v40
	s_and_b64 s[24:25], s[36:37], s[24:25]
	s_or_b64 s[20:21], s[20:21], s[24:25]
	v_addc_co_u32_e64 v20, s[20:21], v20, v28, s[20:21]
	v_cmp_eq_f32_e64 s[24:25], v12, v40
	v_cmp_lt_f32_e64 s[20:21], v12, v40
	s_and_b64 s[0:1], s[0:1], s[24:25]
	s_or_b64 s[0:1], s[20:21], s[0:1]
	v_addc_co_u32_e64 v21, s[0:1], v21, v29, s[0:1]
	v_cmp_eq_f32_e64 s[20:21], v13, v40
	v_cmp_lt_f32_e64 s[0:1], v13, v40
	s_and_b64 s[20:21], s[34:35], s[20:21]
	s_or_b64 s[0:1], s[0:1], s[20:21]
	v_addc_co_u32_e64 v22, s[0:1], v22, v30, s[0:1]
	v_cmp_eq_f32_e64 s[20:21], v10, v40
	v_cmp_lt_f32_e64 s[0:1], v10, v40
	s_and_b64 s[20:21], s[30:31], s[20:21]
	s_or_b64 s[0:1], s[0:1], s[20:21]
	v_addc_co_u32_e64 v23, s[0:1], v23, v31, s[0:1]
	v_cmp_eq_f32_e64 s[20:21], v11, v40
	v_cmp_lt_f32_e64 s[0:1], v11, v40
	s_and_b64 s[20:21], s[26:27], s[20:21]
	s_or_b64 s[0:1], s[0:1], s[20:21]
	v_addc_co_u32_e64 v24, s[0:1], v24, v38, s[0:1]
	v_cmp_eq_f32_e64 s[20:21], v16, v40
	v_cmp_lt_f32_e64 s[0:1], v16, v40
	s_and_b64 s[20:21], s[22:23], s[20:21]
	s_or_b64 s[0:1], s[0:1], s[20:21]
	v_addc_co_u32_e64 v25, s[0:1], v25, v39, s[0:1]
	v_cmp_eq_f32_e64 s[20:21], v9, v40
	v_cmp_lt_f32_e64 s[0:1], v9, v40
	s_and_b64 s[18:19], s[18:19], s[20:21]
	s_or_b64 s[0:1], s[0:1], s[18:19]
	v_addc_co_u32_e64 v18, s[0:1], v18, v26, s[0:1]
	ds_bpermute_b32 v26, v17, v14 offset:128
	v_cmp_lt_i32_e64 s[18:19], 2, v32
	v_cmp_lt_i32_e64 s[24:25], -6, v32
	v_cmp_lt_i32_e64 s[28:29], -10, v32
	v_cmp_lt_i32_e64 s[34:35], -14, v32
	s_waitcnt lgkmcnt(0)
	v_cmp_eq_f32_e64 s[20:21], v14, v26
	v_cmp_lt_f32_e64 s[0:1], v14, v26
	s_and_b64 s[20:21], s[18:19], s[20:21]
	s_or_b64 s[0:1], s[0:1], s[20:21]
	v_cmp_eq_f32_e64 s[22:23], v15, v26
	v_cmp_lt_i32_e64 s[20:21], -2, v32
	v_cndmask_b32_e64 v27, 0, 1, s[0:1]
	v_cmp_lt_f32_e64 s[0:1], v15, v26
	s_and_b64 s[22:23], s[20:21], s[22:23]
	s_or_b64 s[0:1], s[0:1], s[22:23]
	v_cmp_eq_f32_e64 s[22:23], v12, v26
	v_cndmask_b32_e64 v28, 0, 1, s[0:1]
	v_cmp_lt_f32_e64 s[0:1], v12, v26
	s_and_b64 s[22:23], s[24:25], s[22:23]
	s_or_b64 s[0:1], s[0:1], s[22:23]
	v_cmp_eq_f32_e64 s[22:23], v13, v26
	v_cndmask_b32_e64 v29, 0, 1, s[0:1]
	v_cmp_lt_f32_e64 s[0:1], v13, v26
	s_and_b64 s[22:23], s[28:29], s[22:23]
	s_or_b64 s[0:1], s[0:1], s[22:23]
	v_cmp_eq_f32_e64 s[22:23], v10, v26
	v_cndmask_b32_e64 v30, 0, 1, s[0:1]
	v_cmp_lt_f32_e64 s[0:1], v10, v26
	s_and_b64 s[22:23], s[34:35], s[22:23]
	s_or_b64 s[0:1], s[0:1], s[22:23]
	v_cndmask_b32_e64 v31, 0, 1, s[0:1]
	s_movk_i32 s0, 0xffee
	v_cmp_eq_f32_e64 s[26:27], v11, v26
	v_cmp_lt_i32_e64 s[0:1], s0, v32
	v_cmp_lt_f32_e64 s[22:23], v11, v26
	s_and_b64 s[26:27], s[0:1], s[26:27]
	s_movk_i32 s30, 0xffea
	s_or_b64 s[22:23], s[22:23], s[26:27]
	v_cmp_eq_f32_e64 s[26:27], v16, v26
	v_cmp_lt_i32_e64 s[30:31], s30, v32
	ds_bpermute_b32 v40, v17, v15 offset:128
	v_cndmask_b32_e64 v38, 0, 1, s[22:23]
	v_cmp_lt_f32_e64 s[22:23], v16, v26
	s_and_b64 s[26:27], s[30:31], s[26:27]
	s_movk_i32 s36, 0xffe6
	s_or_b64 s[22:23], s[22:23], s[26:27]
	v_cmp_eq_f32_e64 s[26:27], v9, v26
	v_cmp_lt_i32_e64 s[36:37], s36, v32
	v_cndmask_b32_e64 v39, 0, 1, s[22:23]
	v_cmp_lt_f32_e64 s[22:23], v9, v26
	s_and_b64 s[26:27], s[36:37], s[26:27]
	s_or_b64 s[22:23], s[22:23], s[26:27]
	v_cndmask_b32_e64 v26, 0, 1, s[22:23]
	s_waitcnt lgkmcnt(0)
	v_cmp_eq_f32_e64 s[36:37], v14, v40
	v_cmp_lt_i32_e64 s[22:23], 6, v32
	v_cmp_lt_f32_e64 s[26:27], v14, v40
	s_and_b64 s[36:37], s[22:23], s[36:37]
	s_or_b64 s[26:27], s[26:27], s[36:37]
	v_addc_co_u32_e64 v19, s[26:27], v19, v27, s[26:27]
	v_cmp_eq_f32_e64 s[36:37], v15, v40
	v_cmp_lt_f32_e64 s[26:27], v15, v40
	s_and_b64 s[36:37], s[18:19], s[36:37]
	s_or_b64 s[26:27], s[26:27], s[36:37]
	v_addc_co_u32_e64 v20, s[26:27], v20, v28, s[26:27]
	v_cmp_eq_f32_e64 s[36:37], v12, v40
	v_cmp_lt_f32_e64 s[26:27], v12, v40
	s_and_b64 s[36:37], s[20:21], s[36:37]
	s_or_b64 s[26:27], s[26:27], s[36:37]
	v_addc_co_u32_e64 v21, s[26:27], v21, v29, s[26:27]
	v_cmp_eq_f32_e64 s[36:37], v13, v40
	v_cmp_lt_f32_e64 s[26:27], v13, v40
	s_and_b64 s[36:37], s[24:25], s[36:37]
	s_or_b64 s[26:27], s[26:27], s[36:37]
	v_addc_co_u32_e64 v22, s[26:27], v22, v30, s[26:27]
	v_cmp_eq_f32_e64 s[36:37], v10, v40
	v_cmp_lt_f32_e64 s[26:27], v10, v40
	s_and_b64 s[36:37], s[28:29], s[36:37]
	s_or_b64 s[26:27], s[26:27], s[36:37]
	v_addc_co_u32_e64 v23, s[26:27], v23, v31, s[26:27]
	v_cmp_eq_f32_e64 s[36:37], v11, v40
	v_cmp_lt_f32_e64 s[26:27], v11, v40
	s_and_b64 s[36:37], s[34:35], s[36:37]
	s_or_b64 s[26:27], s[26:27], s[36:37]
	v_addc_co_u32_e64 v24, s[26:27], v24, v38, s[26:27]
	v_cmp_eq_f32_e64 s[36:37], v16, v40
	v_cmp_lt_f32_e64 s[26:27], v16, v40
	s_and_b64 s[36:37], s[0:1], s[36:37]
	s_or_b64 s[26:27], s[26:27], s[36:37]
	v_addc_co_u32_e64 v25, s[26:27], v25, v39, s[26:27]
	v_cmp_eq_f32_e64 s[36:37], v9, v40
	v_cmp_lt_f32_e64 s[26:27], v9, v40
	s_and_b64 s[30:31], s[30:31], s[36:37]
	s_or_b64 s[26:27], s[26:27], s[30:31]
	v_addc_co_u32_e64 v18, s[26:27], v18, v26, s[26:27]
	ds_bpermute_b32 v26, v17, v12 offset:128
	v_cmp_lt_i32_e64 s[26:27], 10, v32
	ds_bpermute_b32 v40, v17, v13 offset:128
	s_waitcnt lgkmcnt(1)
	v_cmp_eq_f32_e64 s[36:37], v14, v26
	v_cmp_lt_f32_e64 s[30:31], v14, v26
	s_and_b64 s[36:37], s[26:27], s[36:37]
	s_or_b64 s[30:31], s[30:31], s[36:37]
	v_cmp_eq_f32_e64 s[36:37], v15, v26
	v_cndmask_b32_e64 v27, 0, 1, s[30:31]
	v_cmp_lt_f32_e64 s[30:31], v15, v26
	s_and_b64 s[36:37], s[22:23], s[36:37]
	s_or_b64 s[30:31], s[30:31], s[36:37]
	v_cmp_eq_f32_e64 s[36:37], v12, v26
	v_cndmask_b32_e64 v28, 0, 1, s[30:31]
	v_cmp_lt_f32_e64 s[30:31], v12, v26
	s_and_b64 s[36:37], s[18:19], s[36:37]
	s_or_b64 s[30:31], s[30:31], s[36:37]
	v_cmp_eq_f32_e64 s[36:37], v13, v26
	v_cndmask_b32_e64 v29, 0, 1, s[30:31]
	v_cmp_lt_f32_e64 s[30:31], v13, v26
	s_and_b64 s[36:37], s[20:21], s[36:37]
	s_or_b64 s[30:31], s[30:31], s[36:37]
	v_cmp_eq_f32_e64 s[36:37], v10, v26
	v_cndmask_b32_e64 v30, 0, 1, s[30:31]
	v_cmp_lt_f32_e64 s[30:31], v10, v26
	s_and_b64 s[36:37], s[24:25], s[36:37]
	s_or_b64 s[30:31], s[30:31], s[36:37]
	v_cmp_eq_f32_e64 s[36:37], v11, v26
	v_cndmask_b32_e64 v31, 0, 1, s[30:31]
	v_cmp_lt_f32_e64 s[30:31], v11, v26
	s_and_b64 s[36:37], s[28:29], s[36:37]
	s_or_b64 s[30:31], s[30:31], s[36:37]
	v_cmp_eq_f32_e64 s[36:37], v16, v26
	v_cndmask_b32_e64 v38, 0, 1, s[30:31]
	v_cmp_lt_f32_e64 s[30:31], v16, v26
	s_and_b64 s[36:37], s[34:35], s[36:37]
	s_or_b64 s[30:31], s[30:31], s[36:37]
	v_cmp_eq_f32_e64 s[36:37], v9, v26
	v_cndmask_b32_e64 v39, 0, 1, s[30:31]
	v_cmp_lt_f32_e64 s[30:31], v9, v26
	s_and_b64 s[0:1], s[0:1], s[36:37]
	s_or_b64 s[0:1], s[30:31], s[0:1]
	s_waitcnt lgkmcnt(0)
	v_cmp_eq_f32_e64 s[36:37], v14, v40
	v_cmp_lt_i32_e64 s[30:31], 14, v32
	v_cndmask_b32_e64 v26, 0, 1, s[0:1]
	v_cmp_lt_f32_e64 s[0:1], v14, v40
	s_and_b64 s[36:37], s[30:31], s[36:37]
	s_or_b64 s[0:1], s[0:1], s[36:37]
	v_addc_co_u32_e64 v19, s[0:1], v19, v27, s[0:1]
	v_cmp_eq_f32_e64 s[36:37], v15, v40
	v_cmp_lt_f32_e64 s[0:1], v15, v40
	s_and_b64 s[36:37], s[26:27], s[36:37]
	s_or_b64 s[0:1], s[0:1], s[36:37]
	v_addc_co_u32_e64 v20, s[0:1], v20, v28, s[0:1]
	v_cmp_eq_f32_e64 s[36:37], v12, v40
	v_cmp_lt_f32_e64 s[0:1], v12, v40
	s_and_b64 s[36:37], s[22:23], s[36:37]
	s_or_b64 s[0:1], s[0:1], s[36:37]
	v_addc_co_u32_e64 v21, s[0:1], v21, v29, s[0:1]
	v_cmp_eq_f32_e64 s[36:37], v13, v40
	v_cmp_lt_f32_e64 s[0:1], v13, v40
	s_and_b64 s[36:37], s[18:19], s[36:37]
	s_or_b64 s[0:1], s[0:1], s[36:37]
	v_addc_co_u32_e64 v22, s[0:1], v22, v30, s[0:1]
	v_cmp_eq_f32_e64 s[36:37], v10, v40
	v_cmp_lt_f32_e64 s[0:1], v10, v40
	s_and_b64 s[36:37], s[20:21], s[36:37]
	s_or_b64 s[0:1], s[0:1], s[36:37]
	v_addc_co_u32_e64 v23, s[0:1], v23, v31, s[0:1]
	v_cmp_eq_f32_e64 s[36:37], v11, v40
	v_cmp_lt_f32_e64 s[0:1], v11, v40
	s_and_b64 s[36:37], s[24:25], s[36:37]
	s_or_b64 s[0:1], s[0:1], s[36:37]
	v_addc_co_u32_e64 v24, s[0:1], v24, v38, s[0:1]
	v_cmp_eq_f32_e64 s[36:37], v16, v40
	v_cmp_lt_f32_e64 s[0:1], v16, v40
	s_and_b64 s[36:37], s[28:29], s[36:37]
	s_or_b64 s[0:1], s[0:1], s[36:37]
	v_addc_co_u32_e64 v25, s[0:1], v25, v39, s[0:1]
	v_cmp_eq_f32_e64 s[36:37], v9, v40
	v_cmp_lt_f32_e64 s[0:1], v9, v40
	s_and_b64 s[34:35], s[34:35], s[36:37]
	s_or_b64 s[0:1], s[0:1], s[34:35]
	v_addc_co_u32_e64 v18, s[0:1], v18, v26, s[0:1]
	ds_bpermute_b32 v26, v17, v10 offset:128
	v_cmp_lt_i32_e64 s[34:35], 18, v32
	ds_bpermute_b32 v40, v17, v11 offset:128
	s_waitcnt lgkmcnt(1)
	v_cmp_eq_f32_e64 s[36:37], v14, v26
	v_cmp_lt_f32_e64 s[0:1], v14, v26
	s_and_b64 s[36:37], s[34:35], s[36:37]
	s_or_b64 s[0:1], s[0:1], s[36:37]
	v_cmp_eq_f32_e64 s[36:37], v15, v26
	v_cndmask_b32_e64 v27, 0, 1, s[0:1]
	v_cmp_lt_f32_e64 s[0:1], v15, v26
	s_and_b64 s[36:37], s[30:31], s[36:37]
	s_or_b64 s[0:1], s[0:1], s[36:37]
	v_cmp_eq_f32_e64 s[36:37], v12, v26
	v_cndmask_b32_e64 v28, 0, 1, s[0:1]
	v_cmp_lt_f32_e64 s[0:1], v12, v26
	s_and_b64 s[36:37], s[26:27], s[36:37]
	s_or_b64 s[0:1], s[0:1], s[36:37]
	v_cmp_eq_f32_e64 s[36:37], v13, v26
	v_cndmask_b32_e64 v29, 0, 1, s[0:1]
	v_cmp_lt_f32_e64 s[0:1], v13, v26
	s_and_b64 s[36:37], s[22:23], s[36:37]
	s_or_b64 s[0:1], s[0:1], s[36:37]
	v_cmp_eq_f32_e64 s[36:37], v10, v26
	v_cndmask_b32_e64 v30, 0, 1, s[0:1]
	v_cmp_lt_f32_e64 s[0:1], v10, v26
	s_and_b64 s[36:37], s[18:19], s[36:37]
	s_or_b64 s[0:1], s[0:1], s[36:37]
	v_cmp_eq_f32_e64 s[36:37], v11, v26
	v_cndmask_b32_e64 v31, 0, 1, s[0:1]
	v_cmp_lt_f32_e64 s[0:1], v11, v26
	s_and_b64 s[36:37], s[20:21], s[36:37]
	s_or_b64 s[0:1], s[0:1], s[36:37]
	v_cmp_eq_f32_e64 s[36:37], v16, v26
	v_cndmask_b32_e64 v38, 0, 1, s[0:1]
	v_cmp_lt_f32_e64 s[0:1], v16, v26
	s_and_b64 s[36:37], s[24:25], s[36:37]
	s_or_b64 s[0:1], s[0:1], s[36:37]
	v_cmp_eq_f32_e64 s[36:37], v9, v26
	v_cndmask_b32_e64 v39, 0, 1, s[0:1]
	v_cmp_lt_f32_e64 s[0:1], v9, v26
	s_and_b64 s[28:29], s[28:29], s[36:37]
	s_or_b64 s[0:1], s[0:1], s[28:29]
	v_cndmask_b32_e64 v26, 0, 1, s[0:1]
	s_waitcnt lgkmcnt(0)
	v_cmp_eq_f32_e64 s[36:37], v14, v40
	v_cmp_lt_i32_e64 s[0:1], 22, v32
	v_cmp_lt_f32_e64 s[28:29], v14, v40
	s_and_b64 s[36:37], s[0:1], s[36:37]
	s_or_b64 s[28:29], s[28:29], s[36:37]
	v_addc_co_u32_e64 v19, s[28:29], v19, v27, s[28:29]
	v_cmp_eq_f32_e64 s[36:37], v15, v40
	v_cmp_lt_f32_e64 s[28:29], v15, v40
	s_and_b64 s[36:37], s[34:35], s[36:37]
	s_or_b64 s[28:29], s[28:29], s[36:37]
	v_addc_co_u32_e64 v20, s[28:29], v20, v28, s[28:29]
	v_cmp_eq_f32_e64 s[36:37], v12, v40
	v_cmp_lt_f32_e64 s[28:29], v12, v40
	s_and_b64 s[36:37], s[30:31], s[36:37]
	s_or_b64 s[28:29], s[28:29], s[36:37]
	v_addc_co_u32_e64 v21, s[28:29], v21, v29, s[28:29]
	v_cmp_eq_f32_e64 s[36:37], v13, v40
	v_cmp_lt_f32_e64 s[28:29], v13, v40
	s_and_b64 s[36:37], s[26:27], s[36:37]
	s_or_b64 s[28:29], s[28:29], s[36:37]
	v_addc_co_u32_e64 v22, s[28:29], v22, v30, s[28:29]
	v_cmp_eq_f32_e64 s[36:37], v10, v40
	v_cmp_lt_f32_e64 s[28:29], v10, v40
	s_and_b64 s[36:37], s[22:23], s[36:37]
	s_or_b64 s[28:29], s[28:29], s[36:37]
	v_addc_co_u32_e64 v23, s[28:29], v23, v31, s[28:29]
	v_cmp_eq_f32_e64 s[36:37], v11, v40
	v_cmp_lt_f32_e64 s[28:29], v11, v40
	s_and_b64 s[36:37], s[18:19], s[36:37]
	s_or_b64 s[28:29], s[28:29], s[36:37]
	v_addc_co_u32_e64 v24, s[28:29], v24, v38, s[28:29]
	v_cmp_eq_f32_e64 s[36:37], v16, v40
	v_cmp_lt_f32_e64 s[28:29], v16, v40
	s_and_b64 s[36:37], s[20:21], s[36:37]
	s_or_b64 s[28:29], s[28:29], s[36:37]
	v_addc_co_u32_e64 v25, s[28:29], v25, v39, s[28:29]
	v_cmp_eq_f32_e64 s[36:37], v9, v40
	v_cmp_lt_f32_e64 s[28:29], v9, v40
	s_and_b64 s[24:25], s[24:25], s[36:37]
	s_or_b64 s[24:25], s[28:29], s[24:25]
	v_addc_co_u32_e64 v18, s[24:25], v18, v26, s[24:25]
	ds_bpermute_b32 v26, v17, v16 offset:128
	v_cmp_lt_i32_e64 s[36:37], 26, v32
	ds_bpermute_b32 v40, v17, v9 offset:128
	s_waitcnt lgkmcnt(1)
	v_cmp_eq_f32_e64 s[28:29], v14, v26
	v_cmp_lt_f32_e64 s[24:25], v14, v26
	s_and_b64 s[28:29], s[36:37], s[28:29]
	s_or_b64 s[24:25], s[24:25], s[28:29]
	v_cmp_eq_f32_e64 s[28:29], v15, v26
	v_cndmask_b32_e64 v27, 0, 1, s[24:25]
	v_cmp_lt_f32_e64 s[24:25], v15, v26
	s_and_b64 s[28:29], s[0:1], s[28:29]
	s_or_b64 s[24:25], s[24:25], s[28:29]
	v_cmp_eq_f32_e64 s[28:29], v12, v26
	v_cndmask_b32_e64 v28, 0, 1, s[24:25]
	v_cmp_lt_f32_e64 s[24:25], v12, v26
	s_and_b64 s[28:29], s[34:35], s[28:29]
	s_or_b64 s[24:25], s[24:25], s[28:29]
	v_cmp_eq_f32_e64 s[28:29], v13, v26
	v_cndmask_b32_e64 v29, 0, 1, s[24:25]
	v_cmp_lt_f32_e64 s[24:25], v13, v26
	s_and_b64 s[28:29], s[30:31], s[28:29]
	s_or_b64 s[24:25], s[24:25], s[28:29]
	v_cmp_eq_f32_e64 s[28:29], v10, v26
	v_cndmask_b32_e64 v30, 0, 1, s[24:25]
	v_cmp_lt_f32_e64 s[24:25], v10, v26
	s_and_b64 s[28:29], s[26:27], s[28:29]
	s_or_b64 s[24:25], s[24:25], s[28:29]
	v_cmp_eq_f32_e64 s[28:29], v11, v26
	v_cndmask_b32_e64 v31, 0, 1, s[24:25]
	v_cmp_lt_f32_e64 s[24:25], v11, v26
	s_and_b64 s[28:29], s[22:23], s[28:29]
	s_or_b64 s[24:25], s[24:25], s[28:29]
	v_cmp_eq_f32_e64 s[28:29], v16, v26
	v_cndmask_b32_e64 v38, 0, 1, s[24:25]
	v_cmp_lt_f32_e64 s[24:25], v16, v26
	s_and_b64 s[28:29], s[18:19], s[28:29]
	s_or_b64 s[24:25], s[24:25], s[28:29]
	v_cmp_eq_f32_e64 s[28:29], v9, v26
	v_cndmask_b32_e64 v39, 0, 1, s[24:25]
	v_cmp_lt_f32_e64 s[24:25], v9, v26
	s_and_b64 s[20:21], s[20:21], s[28:29]
	s_or_b64 s[20:21], s[24:25], s[20:21]
	s_waitcnt lgkmcnt(0)
	v_cmp_eq_f32_e64 s[24:25], v14, v40
	v_cmp_lt_i32_e64 s[28:29], 30, v32
	v_cndmask_b32_e64 v26, 0, 1, s[20:21]
	v_cmp_lt_f32_e64 s[20:21], v14, v40
	s_and_b64 s[24:25], s[28:29], s[24:25]
	s_or_b64 s[20:21], s[20:21], s[24:25]
	v_addc_co_u32_e64 v19, s[20:21], v19, v27, s[20:21]
	v_cmp_eq_f32_e64 s[24:25], v15, v40
	v_cmp_lt_f32_e64 s[20:21], v15, v40
	s_and_b64 s[24:25], s[36:37], s[24:25]
	s_or_b64 s[20:21], s[20:21], s[24:25]
	v_addc_co_u32_e64 v20, s[20:21], v20, v28, s[20:21]
	v_cmp_eq_f32_e64 s[24:25], v12, v40
	v_cmp_lt_f32_e64 s[20:21], v12, v40
	s_and_b64 s[0:1], s[0:1], s[24:25]
	s_or_b64 s[0:1], s[20:21], s[0:1]
	v_addc_co_u32_e64 v21, s[0:1], v21, v29, s[0:1]
	v_cmp_eq_f32_e64 s[20:21], v13, v40
	v_cmp_lt_f32_e64 s[0:1], v13, v40
	s_and_b64 s[20:21], s[34:35], s[20:21]
	s_or_b64 s[0:1], s[0:1], s[20:21]
	v_addc_co_u32_e64 v22, s[0:1], v22, v30, s[0:1]
	v_cmp_eq_f32_e64 s[20:21], v10, v40
	v_cmp_lt_f32_e64 s[0:1], v10, v40
	s_and_b64 s[20:21], s[30:31], s[20:21]
	s_or_b64 s[0:1], s[0:1], s[20:21]
	v_addc_co_u32_e64 v23, s[0:1], v23, v31, s[0:1]
	v_cmp_eq_f32_e64 s[20:21], v11, v40
	v_cmp_lt_f32_e64 s[0:1], v11, v40
	s_and_b64 s[20:21], s[26:27], s[20:21]
	s_or_b64 s[0:1], s[0:1], s[20:21]
	v_addc_co_u32_e64 v24, s[0:1], v24, v38, s[0:1]
	v_cmp_eq_f32_e64 s[20:21], v16, v40
	v_cmp_lt_f32_e64 s[0:1], v16, v40
	s_and_b64 s[20:21], s[22:23], s[20:21]
	s_or_b64 s[0:1], s[0:1], s[20:21]
	v_addc_co_u32_e64 v25, s[0:1], v25, v39, s[0:1]
	v_cmp_eq_f32_e64 s[20:21], v9, v40
	v_cmp_lt_f32_e64 s[0:1], v9, v40
	s_and_b64 s[18:19], s[18:19], s[20:21]
	s_or_b64 s[0:1], s[0:1], s[18:19]
	v_addc_co_u32_e64 v18, s[0:1], v18, v26, s[0:1]
	ds_bpermute_b32 v26, v17, v14 offset:192
	v_cmp_lt_i32_e64 s[18:19], 3, v32
	v_cmp_lt_i32_e64 s[24:25], -5, v32
	v_cmp_lt_i32_e64 s[28:29], -9, v32
	v_cmp_lt_i32_e64 s[34:35], -13, v32
	s_waitcnt lgkmcnt(0)
	v_cmp_eq_f32_e64 s[20:21], v14, v26
	v_cmp_lt_f32_e64 s[0:1], v14, v26
	s_and_b64 s[20:21], s[18:19], s[20:21]
	s_or_b64 s[0:1], s[0:1], s[20:21]
	v_cmp_eq_f32_e64 s[22:23], v15, v26
	v_cmp_lt_i32_e64 s[20:21], -1, v32
	v_cndmask_b32_e64 v27, 0, 1, s[0:1]
	v_cmp_lt_f32_e64 s[0:1], v15, v26
	s_and_b64 s[22:23], s[20:21], s[22:23]
	s_or_b64 s[0:1], s[0:1], s[22:23]
	v_cmp_eq_f32_e64 s[22:23], v12, v26
	v_cndmask_b32_e64 v28, 0, 1, s[0:1]
	v_cmp_lt_f32_e64 s[0:1], v12, v26
	s_and_b64 s[22:23], s[24:25], s[22:23]
	s_or_b64 s[0:1], s[0:1], s[22:23]
	v_cmp_eq_f32_e64 s[22:23], v13, v26
	v_cndmask_b32_e64 v29, 0, 1, s[0:1]
	v_cmp_lt_f32_e64 s[0:1], v13, v26
	s_and_b64 s[22:23], s[28:29], s[22:23]
	s_or_b64 s[0:1], s[0:1], s[22:23]
	v_cmp_eq_f32_e64 s[22:23], v10, v26
	v_cndmask_b32_e64 v30, 0, 1, s[0:1]
	v_cmp_lt_f32_e64 s[0:1], v10, v26
	s_and_b64 s[22:23], s[34:35], s[22:23]
	s_or_b64 s[0:1], s[0:1], s[22:23]
	v_cndmask_b32_e64 v31, 0, 1, s[0:1]
	s_movk_i32 s0, 0xffef
	v_cmp_eq_f32_e64 s[26:27], v11, v26
	v_cmp_lt_i32_e64 s[0:1], s0, v32
	v_cmp_lt_f32_e64 s[22:23], v11, v26
	s_and_b64 s[26:27], s[0:1], s[26:27]
	s_movk_i32 s30, 0xffeb
	s_or_b64 s[22:23], s[22:23], s[26:27]
	v_cmp_eq_f32_e64 s[26:27], v16, v26
	v_cmp_lt_i32_e64 s[30:31], s30, v32
	ds_bpermute_b32 v40, v17, v15 offset:192
	v_cndmask_b32_e64 v38, 0, 1, s[22:23]
	v_cmp_lt_f32_e64 s[22:23], v16, v26
	s_and_b64 s[26:27], s[30:31], s[26:27]
	s_movk_i32 s36, 0xffe7
	s_or_b64 s[22:23], s[22:23], s[26:27]
	v_cmp_eq_f32_e64 s[26:27], v9, v26
	v_cmp_lt_i32_e64 s[36:37], s36, v32
	v_cndmask_b32_e64 v39, 0, 1, s[22:23]
	v_cmp_lt_f32_e64 s[22:23], v9, v26
	s_and_b64 s[26:27], s[36:37], s[26:27]
	s_or_b64 s[22:23], s[22:23], s[26:27]
	v_cndmask_b32_e64 v26, 0, 1, s[22:23]
	s_waitcnt lgkmcnt(0)
	v_cmp_eq_f32_e64 s[36:37], v14, v40
	v_cmp_lt_i32_e64 s[22:23], 7, v32
	v_cmp_lt_f32_e64 s[26:27], v14, v40
	s_and_b64 s[36:37], s[22:23], s[36:37]
	s_or_b64 s[26:27], s[26:27], s[36:37]
	v_addc_co_u32_e64 v19, s[26:27], v19, v27, s[26:27]
	v_cmp_eq_f32_e64 s[36:37], v15, v40
	v_cmp_lt_f32_e64 s[26:27], v15, v40
	s_and_b64 s[36:37], s[18:19], s[36:37]
	s_or_b64 s[26:27], s[26:27], s[36:37]
	v_addc_co_u32_e64 v20, s[26:27], v20, v28, s[26:27]
	v_cmp_eq_f32_e64 s[36:37], v12, v40
	v_cmp_lt_f32_e64 s[26:27], v12, v40
	s_and_b64 s[36:37], s[20:21], s[36:37]
	s_or_b64 s[26:27], s[26:27], s[36:37]
	v_addc_co_u32_e64 v21, s[26:27], v21, v29, s[26:27]
	v_cmp_eq_f32_e64 s[36:37], v13, v40
	v_cmp_lt_f32_e64 s[26:27], v13, v40
	s_and_b64 s[36:37], s[24:25], s[36:37]
	s_or_b64 s[26:27], s[26:27], s[36:37]
	v_addc_co_u32_e64 v22, s[26:27], v22, v30, s[26:27]
	v_cmp_eq_f32_e64 s[36:37], v10, v40
	v_cmp_lt_f32_e64 s[26:27], v10, v40
	s_and_b64 s[36:37], s[28:29], s[36:37]
	s_or_b64 s[26:27], s[26:27], s[36:37]
	v_addc_co_u32_e64 v23, s[26:27], v23, v31, s[26:27]
	v_cmp_eq_f32_e64 s[36:37], v11, v40
	v_cmp_lt_f32_e64 s[26:27], v11, v40
	s_and_b64 s[36:37], s[34:35], s[36:37]
	s_or_b64 s[26:27], s[26:27], s[36:37]
	v_addc_co_u32_e64 v24, s[26:27], v24, v38, s[26:27]
	v_cmp_eq_f32_e64 s[36:37], v16, v40
	v_cmp_lt_f32_e64 s[26:27], v16, v40
	s_and_b64 s[36:37], s[0:1], s[36:37]
	s_or_b64 s[26:27], s[26:27], s[36:37]
	v_addc_co_u32_e64 v25, s[26:27], v25, v39, s[26:27]
	v_cmp_eq_f32_e64 s[36:37], v9, v40
	v_cmp_lt_f32_e64 s[26:27], v9, v40
	s_and_b64 s[30:31], s[30:31], s[36:37]
	s_or_b64 s[26:27], s[26:27], s[30:31]
	v_addc_co_u32_e64 v18, s[26:27], v18, v26, s[26:27]
	ds_bpermute_b32 v26, v17, v12 offset:192
	v_cmp_lt_i32_e64 s[26:27], 11, v32
	ds_bpermute_b32 v40, v17, v13 offset:192
	s_waitcnt lgkmcnt(1)
	v_cmp_eq_f32_e64 s[36:37], v14, v26
	v_cmp_lt_f32_e64 s[30:31], v14, v26
	s_and_b64 s[36:37], s[26:27], s[36:37]
	s_or_b64 s[30:31], s[30:31], s[36:37]
	v_cmp_eq_f32_e64 s[36:37], v15, v26
	v_cndmask_b32_e64 v27, 0, 1, s[30:31]
	v_cmp_lt_f32_e64 s[30:31], v15, v26
	s_and_b64 s[36:37], s[22:23], s[36:37]
	s_or_b64 s[30:31], s[30:31], s[36:37]
	v_cmp_eq_f32_e64 s[36:37], v12, v26
	v_cndmask_b32_e64 v28, 0, 1, s[30:31]
	v_cmp_lt_f32_e64 s[30:31], v12, v26
	s_and_b64 s[36:37], s[18:19], s[36:37]
	s_or_b64 s[30:31], s[30:31], s[36:37]
	v_cmp_eq_f32_e64 s[36:37], v13, v26
	v_cndmask_b32_e64 v29, 0, 1, s[30:31]
	v_cmp_lt_f32_e64 s[30:31], v13, v26
	s_and_b64 s[36:37], s[20:21], s[36:37]
	s_or_b64 s[30:31], s[30:31], s[36:37]
	v_cmp_eq_f32_e64 s[36:37], v10, v26
	v_cndmask_b32_e64 v30, 0, 1, s[30:31]
	v_cmp_lt_f32_e64 s[30:31], v10, v26
	s_and_b64 s[36:37], s[24:25], s[36:37]
	s_or_b64 s[30:31], s[30:31], s[36:37]
	v_cmp_eq_f32_e64 s[36:37], v11, v26
	v_cndmask_b32_e64 v31, 0, 1, s[30:31]
	v_cmp_lt_f32_e64 s[30:31], v11, v26
	s_and_b64 s[36:37], s[28:29], s[36:37]
	s_or_b64 s[30:31], s[30:31], s[36:37]
	v_cmp_eq_f32_e64 s[36:37], v16, v26
	v_cndmask_b32_e64 v38, 0, 1, s[30:31]
	v_cmp_lt_f32_e64 s[30:31], v16, v26
	s_and_b64 s[36:37], s[34:35], s[36:37]
	s_or_b64 s[30:31], s[30:31], s[36:37]
	v_cmp_eq_f32_e64 s[36:37], v9, v26
	v_cndmask_b32_e64 v39, 0, 1, s[30:31]
	v_cmp_lt_f32_e64 s[30:31], v9, v26
	s_and_b64 s[0:1], s[0:1], s[36:37]
	s_or_b64 s[0:1], s[30:31], s[0:1]
	s_waitcnt lgkmcnt(0)
	v_cmp_eq_f32_e64 s[36:37], v14, v40
	v_cmp_lt_i32_e64 s[30:31], 15, v32
	v_cndmask_b32_e64 v26, 0, 1, s[0:1]
	v_cmp_lt_f32_e64 s[0:1], v14, v40
	s_and_b64 s[36:37], s[30:31], s[36:37]
	s_or_b64 s[0:1], s[0:1], s[36:37]
	v_addc_co_u32_e64 v19, s[0:1], v19, v27, s[0:1]
	v_cmp_eq_f32_e64 s[36:37], v15, v40
	v_cmp_lt_f32_e64 s[0:1], v15, v40
	s_and_b64 s[36:37], s[26:27], s[36:37]
	s_or_b64 s[0:1], s[0:1], s[36:37]
	v_addc_co_u32_e64 v20, s[0:1], v20, v28, s[0:1]
	v_cmp_eq_f32_e64 s[36:37], v12, v40
	v_cmp_lt_f32_e64 s[0:1], v12, v40
	s_and_b64 s[36:37], s[22:23], s[36:37]
	s_or_b64 s[0:1], s[0:1], s[36:37]
	v_addc_co_u32_e64 v21, s[0:1], v21, v29, s[0:1]
	v_cmp_eq_f32_e64 s[36:37], v13, v40
	v_cmp_lt_f32_e64 s[0:1], v13, v40
	s_and_b64 s[36:37], s[18:19], s[36:37]
	s_or_b64 s[0:1], s[0:1], s[36:37]
	v_addc_co_u32_e64 v22, s[0:1], v22, v30, s[0:1]
	v_cmp_eq_f32_e64 s[36:37], v10, v40
	v_cmp_lt_f32_e64 s[0:1], v10, v40
	s_and_b64 s[36:37], s[20:21], s[36:37]
	s_or_b64 s[0:1], s[0:1], s[36:37]
	v_addc_co_u32_e64 v23, s[0:1], v23, v31, s[0:1]
	v_cmp_eq_f32_e64 s[36:37], v11, v40
	v_cmp_lt_f32_e64 s[0:1], v11, v40
	s_and_b64 s[36:37], s[24:25], s[36:37]
	s_or_b64 s[0:1], s[0:1], s[36:37]
	v_addc_co_u32_e64 v24, s[0:1], v24, v38, s[0:1]
	v_cmp_eq_f32_e64 s[36:37], v16, v40
	v_cmp_lt_f32_e64 s[0:1], v16, v40
	s_and_b64 s[36:37], s[28:29], s[36:37]
	s_or_b64 s[0:1], s[0:1], s[36:37]
	v_addc_co_u32_e64 v25, s[0:1], v25, v39, s[0:1]
	v_cmp_eq_f32_e64 s[36:37], v9, v40
	v_cmp_lt_f32_e64 s[0:1], v9, v40
	s_and_b64 s[34:35], s[34:35], s[36:37]
	s_or_b64 s[0:1], s[0:1], s[34:35]
	v_addc_co_u32_e64 v18, s[0:1], v18, v26, s[0:1]
	ds_bpermute_b32 v26, v17, v10 offset:192
	v_cmp_lt_i32_e64 s[34:35], 19, v32
	ds_bpermute_b32 v40, v17, v11 offset:192
	s_waitcnt lgkmcnt(1)
	v_cmp_eq_f32_e64 s[36:37], v14, v26
	v_cmp_lt_f32_e64 s[0:1], v14, v26
	s_and_b64 s[36:37], s[34:35], s[36:37]
	s_or_b64 s[0:1], s[0:1], s[36:37]
	v_cmp_eq_f32_e64 s[36:37], v15, v26
	v_cndmask_b32_e64 v27, 0, 1, s[0:1]
	v_cmp_lt_f32_e64 s[0:1], v15, v26
	s_and_b64 s[36:37], s[30:31], s[36:37]
	s_or_b64 s[0:1], s[0:1], s[36:37]
	v_cmp_eq_f32_e64 s[36:37], v12, v26
	v_cndmask_b32_e64 v28, 0, 1, s[0:1]
	v_cmp_lt_f32_e64 s[0:1], v12, v26
	s_and_b64 s[36:37], s[26:27], s[36:37]
	s_or_b64 s[0:1], s[0:1], s[36:37]
	v_cmp_eq_f32_e64 s[36:37], v13, v26
	v_cndmask_b32_e64 v29, 0, 1, s[0:1]
	v_cmp_lt_f32_e64 s[0:1], v13, v26
	s_and_b64 s[36:37], s[22:23], s[36:37]
	s_or_b64 s[0:1], s[0:1], s[36:37]
	v_cmp_eq_f32_e64 s[36:37], v10, v26
	v_cndmask_b32_e64 v30, 0, 1, s[0:1]
	v_cmp_lt_f32_e64 s[0:1], v10, v26
	s_and_b64 s[36:37], s[18:19], s[36:37]
	s_or_b64 s[0:1], s[0:1], s[36:37]
	v_cmp_eq_f32_e64 s[36:37], v11, v26
	v_cndmask_b32_e64 v31, 0, 1, s[0:1]
	v_cmp_lt_f32_e64 s[0:1], v11, v26
	s_and_b64 s[36:37], s[20:21], s[36:37]
	s_or_b64 s[0:1], s[0:1], s[36:37]
	v_cmp_eq_f32_e64 s[36:37], v16, v26
	v_cndmask_b32_e64 v38, 0, 1, s[0:1]
	v_cmp_lt_f32_e64 s[0:1], v16, v26
	s_and_b64 s[36:37], s[24:25], s[36:37]
	s_or_b64 s[0:1], s[0:1], s[36:37]
	v_cmp_eq_f32_e64 s[36:37], v9, v26
	v_cndmask_b32_e64 v39, 0, 1, s[0:1]
	v_cmp_lt_f32_e64 s[0:1], v9, v26
	s_and_b64 s[28:29], s[28:29], s[36:37]
	s_or_b64 s[0:1], s[0:1], s[28:29]
	v_cndmask_b32_e64 v26, 0, 1, s[0:1]
	s_waitcnt lgkmcnt(0)
	v_cmp_eq_f32_e64 s[36:37], v14, v40
	v_cmp_lt_i32_e64 s[0:1], 23, v32
	v_cmp_lt_f32_e64 s[28:29], v14, v40
	s_and_b64 s[36:37], s[0:1], s[36:37]
	s_or_b64 s[28:29], s[28:29], s[36:37]
	v_addc_co_u32_e64 v19, s[28:29], v19, v27, s[28:29]
	v_cmp_eq_f32_e64 s[36:37], v15, v40
	v_cmp_lt_f32_e64 s[28:29], v15, v40
	s_and_b64 s[36:37], s[34:35], s[36:37]
	s_or_b64 s[28:29], s[28:29], s[36:37]
	v_addc_co_u32_e64 v20, s[28:29], v20, v28, s[28:29]
	v_cmp_eq_f32_e64 s[36:37], v12, v40
	v_cmp_lt_f32_e64 s[28:29], v12, v40
	s_and_b64 s[36:37], s[30:31], s[36:37]
	s_or_b64 s[28:29], s[28:29], s[36:37]
	v_addc_co_u32_e64 v21, s[28:29], v21, v29, s[28:29]
	v_cmp_eq_f32_e64 s[36:37], v13, v40
	v_cmp_lt_f32_e64 s[28:29], v13, v40
	s_and_b64 s[36:37], s[26:27], s[36:37]
	s_or_b64 s[28:29], s[28:29], s[36:37]
	v_addc_co_u32_e64 v22, s[28:29], v22, v30, s[28:29]
	v_cmp_eq_f32_e64 s[36:37], v10, v40
	v_cmp_lt_f32_e64 s[28:29], v10, v40
	s_and_b64 s[36:37], s[22:23], s[36:37]
	s_or_b64 s[28:29], s[28:29], s[36:37]
	v_addc_co_u32_e64 v23, s[28:29], v23, v31, s[28:29]
	v_cmp_eq_f32_e64 s[36:37], v11, v40
	v_cmp_lt_f32_e64 s[28:29], v11, v40
	s_and_b64 s[36:37], s[18:19], s[36:37]
	s_or_b64 s[28:29], s[28:29], s[36:37]
	v_addc_co_u32_e64 v24, s[28:29], v24, v38, s[28:29]
	v_cmp_eq_f32_e64 s[36:37], v16, v40
	v_cmp_lt_f32_e64 s[28:29], v16, v40
	s_and_b64 s[36:37], s[20:21], s[36:37]
	s_or_b64 s[28:29], s[28:29], s[36:37]
	v_addc_co_u32_e64 v25, s[28:29], v25, v39, s[28:29]
	v_cmp_eq_f32_e64 s[36:37], v9, v40
	v_cmp_lt_f32_e64 s[28:29], v9, v40
	s_and_b64 s[24:25], s[24:25], s[36:37]
	s_or_b64 s[24:25], s[28:29], s[24:25]
	v_addc_co_u32_e64 v18, s[24:25], v18, v26, s[24:25]
	ds_bpermute_b32 v26, v17, v16 offset:192
	v_cmp_lt_i32_e64 s[36:37], 27, v32
	ds_bpermute_b32 v17, v17, v9 offset:192
	s_waitcnt lgkmcnt(1)
	v_cmp_eq_f32_e64 s[28:29], v14, v26
	v_cmp_lt_f32_e64 s[24:25], v14, v26
	s_and_b64 s[28:29], s[36:37], s[28:29]
	s_or_b64 s[24:25], s[24:25], s[28:29]
	v_cmp_eq_f32_e64 s[28:29], v15, v26
	v_cndmask_b32_e64 v27, 0, 1, s[24:25]
	v_cmp_lt_f32_e64 s[24:25], v15, v26
	s_and_b64 s[28:29], s[0:1], s[28:29]
	s_or_b64 s[24:25], s[24:25], s[28:29]
	v_cmp_eq_f32_e64 s[28:29], v12, v26
	v_cndmask_b32_e64 v28, 0, 1, s[24:25]
	v_cmp_lt_f32_e64 s[24:25], v12, v26
	s_and_b64 s[28:29], s[34:35], s[28:29]
	s_or_b64 s[24:25], s[24:25], s[28:29]
	v_cmp_eq_f32_e64 s[28:29], v13, v26
	v_cndmask_b32_e64 v29, 0, 1, s[24:25]
	v_cmp_lt_f32_e64 s[24:25], v13, v26
	s_and_b64 s[28:29], s[30:31], s[28:29]
	s_or_b64 s[24:25], s[24:25], s[28:29]
	v_cmp_eq_f32_e64 s[28:29], v10, v26
	v_cndmask_b32_e64 v30, 0, 1, s[24:25]
	v_cmp_lt_f32_e64 s[24:25], v10, v26
	s_and_b64 s[28:29], s[26:27], s[28:29]
	s_or_b64 s[24:25], s[24:25], s[28:29]
	v_cmp_eq_f32_e64 s[28:29], v11, v26
	v_cndmask_b32_e64 v31, 0, 1, s[24:25]
	v_cmp_lt_f32_e64 s[24:25], v11, v26
	s_and_b64 s[28:29], s[22:23], s[28:29]
	s_or_b64 s[24:25], s[24:25], s[28:29]
	v_cmp_eq_f32_e64 s[28:29], v16, v26
	v_cndmask_b32_e64 v38, 0, 1, s[24:25]
	v_cmp_lt_f32_e64 s[24:25], v16, v26
	s_and_b64 s[28:29], s[18:19], s[28:29]
	s_or_b64 s[24:25], s[24:25], s[28:29]
	v_cmp_eq_f32_e64 s[28:29], v9, v26
	v_cndmask_b32_e64 v39, 0, 1, s[24:25]
	v_cmp_lt_f32_e64 s[24:25], v9, v26
	s_and_b64 s[20:21], s[20:21], s[28:29]
	s_or_b64 s[20:21], s[24:25], s[20:21]
	s_waitcnt lgkmcnt(0)
	v_cmp_eq_f32_e64 s[24:25], v14, v17
	v_cmp_lt_i32_e64 s[28:29], 31, v32
	v_cndmask_b32_e64 v26, 0, 1, s[20:21]
	v_cmp_lt_f32_e64 s[20:21], v14, v17
	s_and_b64 s[24:25], s[28:29], s[24:25]
	s_or_b64 s[20:21], s[20:21], s[24:25]
	v_addc_co_u32_e64 v14, s[20:21], v19, v27, s[20:21]
	v_cmp_eq_f32_e64 s[24:25], v15, v17
	v_cmp_lt_f32_e64 s[20:21], v15, v17
	s_and_b64 s[24:25], s[36:37], s[24:25]
	s_or_b64 s[20:21], s[20:21], s[24:25]
	v_addc_co_u32_e64 v15, s[20:21], v20, v28, s[20:21]
	v_cmp_eq_f32_e64 s[24:25], v12, v17
	v_cmp_lt_f32_e64 s[20:21], v12, v17
	s_and_b64 s[0:1], s[0:1], s[24:25]
	s_or_b64 s[0:1], s[20:21], s[0:1]
	v_addc_co_u32_e64 v12, s[0:1], v21, v29, s[0:1]
	v_cmp_eq_f32_e64 s[20:21], v13, v17
	v_cmp_lt_f32_e64 s[0:1], v13, v17
	s_and_b64 s[20:21], s[34:35], s[20:21]
	s_or_b64 s[0:1], s[0:1], s[20:21]
	v_addc_co_u32_e64 v13, s[0:1], v22, v30, s[0:1]
	v_cmp_eq_f32_e64 s[20:21], v10, v17
	v_cmp_lt_f32_e64 s[0:1], v10, v17
	s_and_b64 s[20:21], s[30:31], s[20:21]
	s_or_b64 s[0:1], s[0:1], s[20:21]
	v_addc_co_u32_e64 v10, s[0:1], v23, v31, s[0:1]
	v_cmp_eq_f32_e64 s[20:21], v11, v17
	v_cmp_lt_f32_e64 s[0:1], v11, v17
	s_and_b64 s[20:21], s[26:27], s[20:21]
	s_or_b64 s[0:1], s[0:1], s[20:21]
	v_addc_co_u32_e64 v11, s[0:1], v24, v38, s[0:1]
	v_cmp_eq_f32_e64 s[20:21], v16, v17
	v_cmp_lt_f32_e64 s[0:1], v16, v17
	s_and_b64 s[20:21], s[22:23], s[20:21]
	s_or_b64 s[0:1], s[0:1], s[20:21]
	v_addc_co_u32_e64 v16, s[0:1], v25, v39, s[0:1]
	v_cmp_eq_f32_e64 s[20:21], v9, v17
	v_cmp_lt_f32_e64 s[0:1], v9, v17
	s_and_b64 s[18:19], s[18:19], s[20:21]
	s_or_b64 s[0:1], s[0:1], s[18:19]
	v_addc_co_u32_e64 v9, s[0:1], v18, v26, s[0:1]
	v_cmp_lt_u32_e64 s[0:1], 7, v14
	s_or_b64 s[0:1], vcc, s[0:1]
	v_lshlrev_b32_e64 v14, v32, 1
	v_cmp_lt_u32_e32 vcc, 7, v15
	v_cndmask_b32_e64 v14, v14, 0, s[0:1]
	s_or_b64 s[0:1], s[4:5], vcc
	v_cmp_lt_u32_e32 vcc, 7, v12
	v_cndmask_b32_e64 v2, v2, 0, s[0:1]
	s_or_b64 s[0:1], s[6:7], vcc
	v_cmp_lt_u32_e32 vcc, 7, v13
	v_cndmask_b32_e64 v3, v3, 0, s[0:1]
	s_or_b64 s[0:1], s[8:9], vcc
	v_or_b32_e32 v2, v2, v14
	v_cndmask_b32_e64 v4, v4, 0, s[0:1]
	v_cmp_lt_u32_e32 vcc, 7, v10
	v_or3_b32 v2, v2, v3, v4
	s_or_b64 s[0:1], s[10:11], vcc
	v_lshlrev_b32_e64 v3, v5, 1
	v_cmp_lt_u32_e32 vcc, 7, v11
	v_cndmask_b32_e64 v3, v3, 0, s[0:1]
	s_or_b64 s[0:1], s[12:13], vcc
	v_lshlrev_b32_e64 v4, v6, 1
	v_cndmask_b32_e64 v4, v4, 0, s[0:1]
	v_cmp_lt_u32_e32 vcc, 7, v16
	v_or3_b32 v2, v2, v3, v4
	s_or_b64 s[0:1], s[14:15], vcc
	v_lshlrev_b32_e64 v3, v7, 1
	v_cmp_lt_u32_e32 vcc, 7, v9
	v_cndmask_b32_e64 v3, v3, 0, s[0:1]
	s_or_b64 s[0:1], s[16:17], vcc
	v_lshlrev_b32_e64 v4, v8, 1
	v_cndmask_b32_e64 v4, v4, 0, s[0:1]
	v_or3_b32 v2, v2, v3, v4
	ds_bpermute_b32 v3, v193, v2
	v_cmp_lt_i32_e32 vcc, v214, v213
	s_waitcnt lgkmcnt(0)
	v_or_b32_e32 v2, v2, v3
	ds_bpermute_b32 v3, v194, v2
	s_waitcnt lgkmcnt(0)
	v_or_b32_e32 v195, v2, v3
	v_cndmask_b32_e32 v2, v211, v214, vcc
	v_lshlrev_b32_e32 v2, 2, v2
	ds_bpermute_b32 v2, v2, v195
	v_cmp_lt_i32_e32 vcc, v215, v213
	s_waitcnt lgkmcnt(0)
	v_or_b32_e32 v2, v195, v2
	v_cndmask_b32_e32 v3, v211, v215, vcc
	v_lshlrev_b32_e32 v3, 2, v3
	ds_bpermute_b32 v3, v3, v2
	v_cmp_lt_i32_e32 vcc, v216, v213
	s_waitcnt lgkmcnt(0)
	v_or_b32_e32 v2, v2, v3
	v_cndmask_b32_e32 v3, v211, v216, vcc
	v_lshlrev_b32_e32 v3, 2, v3
	ds_bpermute_b32 v3, v3, v2
	v_cmp_lt_i32_e32 vcc, v217, v213
	s_waitcnt lgkmcnt(0)
	v_or_b32_e32 v2, v2, v3
	v_cndmask_b32_e32 v3, v211, v217, vcc
	v_lshlrev_b32_e32 v3, 2, v3
	ds_bpermute_b32 v3, v3, v2
	s_waitcnt lgkmcnt(0)
	v_or_b32_e32 v40, v2, v3
	s_add_u32 s16, s86, 0x29200000
	v_lshl_add_u64 v[0:1], v[146:147], 1, v[0:1]
	s_mov_b64 s[0:1], 0x15200000
	s_addc_u32 s17, s87, 0
	v_lshl_add_u64 v[38:39], v[0:1], 0, s[0:1]
	s_lshl_b32 s82, s2, 9
	v_lshl_add_u64 v[28:29], v[38:39], 0, s[82:83]
	global_load_dwordx4 v[0:3], v[28:29], off
	global_load_dwordx4 v[4:7], v[28:29], off offset:64
	global_load_dwordx4 v[8:11], v[28:29], off offset:128
	global_load_dwordx4 v[12:15], v[28:29], off offset:192
	global_load_dwordx4 v[16:19], v[28:29], off offset:256
	global_load_dwordx4 v[20:23], v[28:29], off offset:320
	global_load_dwordx4 v[24:27], v[28:29], off offset:384
	s_nop 0
	global_load_dwordx4 v[28:31], v[28:29], off offset:448
	v_lshlrev_b64 v[32:33], 3, v[32:33]
	v_sub_co_u32_e32 v32, vcc, 0, v32
	v_mul_f32_e32 v196, 0x3fb8aa3b, v34
	v_readfirstlane_b32 s18, v40
	v_subb_co_u32_e32 v33, vcc, 0, v33, vcc
	v_mov_b32_e32 v34, 0x1ff
	s_ff1_i32_b32 s0, s18
	v_sub_co_u32_e32 v34, vcc, s81, v34
	s_ashr_i32 s95, s94, 31
	s_lshl_b32 s19, s0, 6
	v_readfirstlane_b32 s0, v34
	s_lshl_b64 s[6:7], s[94:95], 19
	s_lshl_b32 s4, s2, 6
	s_lshl_b64 s[8:9], s[84:85], 18
	s_sub_i32 s2, s81, 17
	s_add_i32 s20, s18, -1
	s_and_b32 s5, s0, 0xffffffe0
	v_lshl_add_u64 v[32:33], v[38:39], 0, v[32:33]
	s_and_b64 s[0:1], vcc, exec
	v_lshlrev_b32_e32 v34, 11, v190
	v_mul_f32_e32 v197, 0x3fb8aa3b, v35
	v_mul_f32_e32 v198, 0x3fb8aa3b, v36
	v_mul_f32_e32 v199, 0x3fb8aa3b, v37
	s_cselect_b32 s21, 0, s5
	v_add_u32_e32 v200, 0xfffffe01, v191
	v_lshl_add_u64 v[150:151], v[32:33], 0, s[82:83]
	s_mov_b64 s[10:11], 0
	s_lshl_b32 s22, s4, 1
	v_lshlrev_b32_e32 v152, 1, v34
	v_readlane_b32 s56, v252, 21
	v_readlane_b32 s57, v252, 22
	v_lshlrev_b32_e32 v250, 1, v144
	v_lshrrev_b32_e32 v255, 2, v190
	v_and_b32_e32 v251, 3, v190
	v_lshl_or_b32 v255, v255, 3, v251
	v_mov_b32_e32 v251, 0
	s_branch .LBB0_191

.LBB0_308:
	v_lshl_add_u64 v[20:21], v[16:17], 0, v[160:161]
	v_add_co_u32_e32 v20, vcc, s13, v20
	v_lshl_add_u64 v[42:43], v[18:19], 0, v[160:161]
	s_nop 0
	v_addc_co_u32_e32 v21, vcc, 0, v21, vcc
	v_add_co_u32_e32 v22, vcc, s12, v42
	s_nop 1
	v_addc_co_u32_e32 v23, vcc, 0, v43, vcc
	v_add_co_u32_e32 v24, vcc, s14, v42
	s_nop 1
	v_addc_co_u32_e32 v25, vcc, 0, v43, vcc
	v_add_co_u32_e32 v26, vcc, s15, v42
	s_nop 1
	v_addc_co_u32_e32 v27, vcc, 0, v43, vcc
	v_add_co_u32_e32 v28, vcc, s16, v42
	s_nop 1
	v_addc_co_u32_e32 v29, vcc, 0, v43, vcc
	v_lshl_add_u64 v[16:17], v[16:17], 0, s[18:19]
	v_lshl_add_u64 v[18:19], v[18:19], 0, s[30:31]
	global_load_dwordx4 v[34:37], v[20:21], off
	global_load_dwordx4 v[44:47], v[22:23], off
	global_load_dwordx4 v[48:51], v[24:25], off
	global_load_dwordx4 v[52:55], v[26:27], off
	global_load_dwordx4 v[56:59], v[28:29], off
	global_load_dwordx4 v[60:63], v[20:21], off offset:64
	global_load_dwordx4 v[64:67], v[22:23], off offset:64
	global_load_dwordx4 v[68:71], v[24:25], off offset:64
	global_load_dwordx4 v[72:75], v[26:27], off offset:64
	global_load_dwordx4 v[76:79], v[28:29], off offset:64
	global_load_dwordx4 v[80:83], v[20:21], off offset:256
	global_load_dwordx4 v[84:87], v[22:23], off offset:128
	global_load_dwordx4 v[88:91], v[24:25], off offset:128
	global_load_dwordx4 v[92:95], v[26:27], off offset:128
	global_load_dwordx4 v[96:99], v[28:29], off offset:128
	global_load_dwordx4 v[100:103], v[20:21], off offset:320
	global_load_dwordx4 v[104:107], v[22:23], off offset:192
	global_load_dwordx4 v[108:111], v[24:25], off offset:192
	global_load_dwordx4 v[112:115], v[26:27], off offset:192
	global_load_dwordx4 v[116:119], v[28:29], off offset:192
	global_load_dwordx4 v[120:123], v[20:21], off offset:512
	global_load_dwordx4 v[124:127], v[22:23], off offset:256
	global_load_dwordx4 v[128:131], v[24:25], off offset:256
	global_load_dwordx4 v[132:135], v[26:27], off offset:256
	global_load_dwordx4 v[136:139], v[28:29], off offset:256
	global_load_dwordx4 v[140:143], v[20:21], off offset:576
	global_load_dwordx4 v[144:147], v[22:23], off offset:320
	global_load_dwordx4 v[148:151], v[24:25], off offset:320
	global_load_dwordx4 v[152:155], v[26:27], off offset:320
	global_load_dwordx4 v[156:159], v[28:29], off offset:320
	global_load_dwordx4 v[166:169], v[20:21], off offset:768
	global_load_dwordx4 v[170:173], v[22:23], off offset:384
	global_load_dwordx4 v[174:177], v[24:25], off offset:384
	global_load_dwordx4 v[178:181], v[26:27], off offset:384
	global_load_dwordx4 v[182:185], v[28:29], off offset:384
	global_load_dwordx4 v[186:189], v[20:21], off offset:832
	global_load_dwordx4 v[190:193], v[22:23], off offset:448
	global_load_dwordx4 v[194:197], v[24:25], off offset:448
	global_load_dwordx4 v[198:201], v[26:27], off offset:448
	global_load_dwordx4 v[202:205], v[28:29], off offset:448
	s_add_i32 s11, s11, -8
	s_cmp_eq_u32 s11, 0
	s_waitcnt vmcnt(35)
	v_mfma_f32_16x16x32_bf16 v[12:15], v[44:47], v[34:37], v[12:15]
	v_mfma_f32_16x16x32_bf16 v[8:11], v[48:51], v[34:37], v[8:11]
	v_mfma_f32_16x16x32_bf16 v[4:7], v[52:55], v[34:37], v[4:7]
	v_mfma_f32_16x16x32_bf16 v[0:3], v[56:59], v[34:37], v[0:3]
	s_waitcnt vmcnt(30)
	v_mfma_f32_16x16x32_bf16 v[12:15], v[64:67], v[60:63], v[12:15]
	v_mfma_f32_16x16x32_bf16 v[8:11], v[68:71], v[60:63], v[8:11]
	v_mfma_f32_16x16x32_bf16 v[4:7], v[72:75], v[60:63], v[4:7]
	v_mfma_f32_16x16x32_bf16 v[0:3], v[76:79], v[60:63], v[0:3]
	s_waitcnt vmcnt(25)
	v_mfma_f32_16x16x32_bf16 v[12:15], v[84:87], v[80:83], v[12:15]
	v_mfma_f32_16x16x32_bf16 v[8:11], v[88:91], v[80:83], v[8:11]
	v_mfma_f32_16x16x32_bf16 v[4:7], v[92:95], v[80:83], v[4:7]
	v_mfma_f32_16x16x32_bf16 v[0:3], v[96:99], v[80:83], v[0:3]
	s_waitcnt vmcnt(20)
	v_mfma_f32_16x16x32_bf16 v[12:15], v[104:107], v[100:103], v[12:15]
	v_mfma_f32_16x16x32_bf16 v[8:11], v[108:111], v[100:103], v[8:11]
	v_mfma_f32_16x16x32_bf16 v[4:7], v[112:115], v[100:103], v[4:7]
	v_mfma_f32_16x16x32_bf16 v[0:3], v[116:119], v[100:103], v[0:3]
	s_waitcnt vmcnt(15)
	v_mfma_f32_16x16x32_bf16 v[12:15], v[124:127], v[120:123], v[12:15]
	v_mfma_f32_16x16x32_bf16 v[8:11], v[128:131], v[120:123], v[8:11]
	v_mfma_f32_16x16x32_bf16 v[4:7], v[132:135], v[120:123], v[4:7]
	v_mfma_f32_16x16x32_bf16 v[0:3], v[136:139], v[120:123], v[0:3]
	s_waitcnt vmcnt(10)
	v_mfma_f32_16x16x32_bf16 v[12:15], v[144:147], v[140:143], v[12:15]
	v_mfma_f32_16x16x32_bf16 v[8:11], v[148:151], v[140:143], v[8:11]
	v_mfma_f32_16x16x32_bf16 v[4:7], v[152:155], v[140:143], v[4:7]
	v_mfma_f32_16x16x32_bf16 v[0:3], v[156:159], v[140:143], v[0:3]
	s_waitcnt vmcnt(5)
	v_mfma_f32_16x16x32_bf16 v[12:15], v[170:173], v[166:169], v[12:15]
	v_mfma_f32_16x16x32_bf16 v[8:11], v[174:177], v[166:169], v[8:11]
	v_mfma_f32_16x16x32_bf16 v[4:7], v[178:181], v[166:169], v[4:7]
	v_mfma_f32_16x16x32_bf16 v[0:3], v[182:185], v[166:169], v[0:3]
	s_waitcnt vmcnt(0)
	v_mfma_f32_16x16x32_bf16 v[12:15], v[190:193], v[186:189], v[12:15]
	v_mfma_f32_16x16x32_bf16 v[8:11], v[194:197], v[186:189], v[8:11]
	v_mfma_f32_16x16x32_bf16 v[4:7], v[198:201], v[186:189], v[4:7]
	v_mfma_f32_16x16x32_bf16 v[0:3], v[202:205], v[186:189], v[0:3]
	s_cbranch_scc0 .LBB0_308
	s_lshr_b32 s82, s8, 4
	v_readlane_b32 s8, v252, 27
	s_add_u32 s8, s10, s8
	v_readlane_b32 s11, v252, 28
	s_addc_u32 s11, s2, s11
	s_and_b64 s[0:1], s[0:1], exec
	s_mov_b32 s0, 0x2480000
	s_cselect_b32 s1, s0, 0x2482000
	s_lshl_b32 s0, s9, 6
	s_or_b32 s0, s0, s38
	s_add_u32 s8, s8, s1
	s_addc_u32 s9, s11, 0
	s_ashr_i32 s1, s0, 31
	s_lshl_b64 s[0:1], s[0:1], 2
	v_and_b32_e32 v22, 3, v32
	s_add_u32 s0, s10, s0
	s_addc_u32 s1, s2, s1
	v_lshlrev_b32_e32 v160, 4, v22
	v_lshl_add_u64 v[18:19], s[0:1], 0, v[160:161]
	s_mov_b64 s[0:1], 0x300000
	v_lshl_add_u64 v[16:17], v[18:19], 0, s[0:1]
	s_mov_b32 s0, 0x300000
	v_add_co_u32_e32 v18, vcc, s0, v18
	s_lshl_b64 s[0:1], s[82:83], 14
	s_nop 0
	v_addc_co_u32_e32 v19, vcc, 0, v19, vcc
	global_load_dwordx4 v[18:21], v[18:19], off
	s_add_u32 s0, s10, s0
	s_addc_u32 s1, s2, s1
	v_lshlrev_b32_e32 v160, 1, v30
	s_mov_b64 s[10:11], 0x600000
	v_lshlrev_b32_e32 v28, 9, v22
	s_waitcnt vmcnt(0) lgkmcnt(0)
	v_pk_add_f32 v[12:13], v[12:13], v[18:19]
	s_nop 0
	v_mul_f32_e32 v18, v12, v12
	v_mul_f32_e32 v19, v13, v13
	v_fmamk_f32 v18, v18, 0xbdd2d3e8, v209
	v_fmamk_f32 v19, v19, 0xbdd2d3e8, v209
	v_mul_f32_e32 v18, v12, v18
	v_mul_f32_e32 v19, v13, v19
	v_exp_f32_e32 v18, v18
	v_exp_f32_e32 v19, v19
	v_pk_add_f32 v[14:15], v[14:15], v[20:21]
	v_add_f32_e32 v18, 1.0, v18
	v_add_f32_e32 v19, 1.0, v19
	v_rcp_f32_e32 v18, v18
	v_rcp_f32_e32 v19, v19
	s_nop 0
	v_pk_mul_f32 v[24:25], v[12:13], v[18:19]
	v_mul_f32_e32 v12, v14, v14
	v_mul_f32_e32 v13, v15, v15
	v_fmamk_f32 v12, v12, 0xbdd2d3e8, v209
	v_fmamk_f32 v13, v13, 0xbdd2d3e8, v209
	v_mul_f32_e32 v12, v14, v12
	v_mul_f32_e32 v13, v15, v13
	v_exp_f32_e32 v12, v12
	v_exp_f32_e32 v13, v13
	v_add_f32_e32 v12, 1.0, v12
	v_add_f32_e32 v13, 1.0, v13
	v_rcp_f32_e32 v12, v12
	v_rcp_f32_e32 v13, v13
	s_nop 0
	v_pk_mul_f32 v[26:27], v[14:15], v[12:13]
	global_load_dwordx4 v[12:15], v[16:17], off offset:64
	s_waitcnt vmcnt(0) lgkmcnt(0)
	v_pk_add_f32 v[8:9], v[8:9], v[12:13]
	s_nop 0
	v_mul_f32_e32 v12, v8, v8
	v_mul_f32_e32 v13, v9, v9
	v_fmamk_f32 v12, v12, 0xbdd2d3e8, v209
	v_fmamk_f32 v13, v13, 0xbdd2d3e8, v209
	v_mul_f32_e32 v12, v8, v12
	v_mul_f32_e32 v13, v9, v13
	v_exp_f32_e32 v12, v12
	v_exp_f32_e32 v13, v13
	v_pk_add_f32 v[10:11], v[10:11], v[14:15]
	v_add_f32_e32 v12, 1.0, v12
	v_add_f32_e32 v13, 1.0, v13
	v_rcp_f32_e32 v12, v12
	v_rcp_f32_e32 v13, v13
	s_nop 0
	v_pk_mul_f32 v[8:9], v[8:9], v[12:13]
	v_mul_f32_e32 v12, v10, v10
	v_mul_f32_e32 v13, v11, v11
	v_fmamk_f32 v12, v12, 0xbdd2d3e8, v209
	v_fmamk_f32 v13, v13, 0xbdd2d3e8, v209
	v_mul_f32_e32 v12, v10, v12
	v_mul_f32_e32 v13, v11, v13
	v_exp_f32_e32 v12, v12
	v_exp_f32_e32 v13, v13
	v_add_f32_e32 v12, 1.0, v12
	v_add_f32_e32 v13, 1.0, v13
	v_rcp_f32_e32 v12, v12
	v_rcp_f32_e32 v13, v13
	s_nop 0
	v_pk_mul_f32 v[10:11], v[10:11], v[12:13]
	global_load_dwordx4 v[12:15], v[16:17], off offset:128
	s_waitcnt vmcnt(0) lgkmcnt(0)
	v_pk_add_f32 v[4:5], v[4:5], v[12:13]
	s_nop 0
	v_mul_f32_e32 v12, v4, v4
	v_mul_f32_e32 v13, v5, v5
	v_fmamk_f32 v12, v12, 0xbdd2d3e8, v209
	v_fmamk_f32 v13, v13, 0xbdd2d3e8, v209
	v_mul_f32_e32 v12, v4, v12
	v_mul_f32_e32 v13, v5, v13
	v_exp_f32_e32 v12, v12
	v_exp_f32_e32 v13, v13
	v_pk_add_f32 v[6:7], v[6:7], v[14:15]
	v_add_f32_e32 v12, 1.0, v12
	v_add_f32_e32 v13, 1.0, v13
	v_rcp_f32_e32 v12, v12
	v_rcp_f32_e32 v13, v13
	s_nop 0
	v_pk_mul_f32 v[12:13], v[4:5], v[12:13]
	v_mul_f32_e32 v4, v6, v6
	v_mul_f32_e32 v5, v7, v7
	v_fmamk_f32 v4, v4, 0xbdd2d3e8, v209
	v_fmamk_f32 v5, v5, 0xbdd2d3e8, v209
	v_mul_f32_e32 v4, v6, v4
	v_mul_f32_e32 v5, v7, v5
	v_exp_f32_e32 v4, v4
	v_exp_f32_e32 v5, v5
	v_cvt_pk_bf16_f32 v12, v12, v13
	v_add_f32_e32 v4, 1.0, v4
	v_add_f32_e32 v5, 1.0, v5
	v_rcp_f32_e32 v4, v4
	v_rcp_f32_e32 v5, v5
	s_nop 0
	v_pk_mul_f32 v[14:15], v[6:7], v[4:5]
	global_load_dwordx4 v[4:7], v[16:17], off offset:192
	v_cvt_pk_bf16_f32 v13, v14, v15
	s_waitcnt vmcnt(0) lgkmcnt(0)
	v_pk_add_f32 v[0:1], v[0:1], v[4:5]
	s_nop 0
	v_mul_f32_e32 v4, v0, v0
	v_mul_f32_e32 v5, v1, v1
	v_fmamk_f32 v4, v4, 0xbdd2d3e8, v209
	v_fmamk_f32 v5, v5, 0xbdd2d3e8, v209
	v_mul_f32_e32 v4, v0, v4
	v_mul_f32_e32 v5, v1, v5
	v_exp_f32_e32 v4, v4
	v_exp_f32_e32 v5, v5
	v_pk_add_f32 v[2:3], v[2:3], v[6:7]
	v_add_f32_e32 v4, 1.0, v4
	v_add_f32_e32 v5, 1.0, v5
	v_rcp_f32_e32 v4, v4
	v_rcp_f32_e32 v5, v5
	s_nop 0
	v_pk_mul_f32 v[18:19], v[0:1], v[4:5]
	v_mul_f32_e32 v0, v2, v2
	v_mul_f32_e32 v1, v3, v3
	v_fmamk_f32 v0, v0, 0xbdd2d3e8, v209
	v_fmamk_f32 v1, v1, 0xbdd2d3e8, v209
	v_mul_f32_e32 v0, v2, v0
	v_mul_f32_e32 v1, v3, v1
	v_exp_f32_e32 v0, v0
	v_exp_f32_e32 v1, v1
	v_cvt_pk_bf16_f32 v14, v18, v19
	v_add_f32_e32 v0, 1.0, v0
	v_add_f32_e32 v1, 1.0, v1
	v_rcp_f32_e32 v0, v0
	v_rcp_f32_e32 v1, v1
	s_nop 0
	v_pk_mul_f32 v[20:21], v[2:3], v[0:1]
	v_lshl_add_u64 v[0:1], s[0:1], 0, v[160:161]
	v_lshlrev_b32_e32 v160, 3, v22
	v_lshl_add_u64 v[16:17], v[0:1], 0, s[10:11]
	v_lshl_add_u64 v[0:1], s[8:9], 0, v[160:161]
	v_lshlrev_b32_e32 v2, 7, v31
	v_mov_b32_e32 v3, v161
	v_lshl_add_u64 v[0:1], v[0:1], 0, v[2:3]
	s_mov_b64 s[8:9], 0x800000
	v_lshl_add_u64 v[22:23], v[0:1], 0, s[8:9]
	v_add_co_u32_e32 v0, vcc, s12, v0
	v_cvt_pk_bf16_f32 v2, v8, v9
	s_nop 0
	v_addc_co_u32_e32 v1, vcc, 0, v1, vcc
	global_load_dwordx2 v[4:5], v[0:1], off
	global_load_dwordx2 v[6:7], v[22:23], off offset:32
	v_cvt_pk_bf16_f32 v3, v10, v11
	global_load_dwordx2 v[8:9], v[22:23], off offset:64
	global_load_dwordx2 v[10:11], v[22:23], off offset:96
	v_cvt_pk_bf16_f32 v0, v24, v25
	v_cvt_pk_bf16_f32 v1, v26, v27
	v_cvt_pk_bf16_f32 v15, v20, v21
	s_mov_b64 s[8:9], -1
	s_and_b64 vcc, exec, s[6:7]
	s_waitcnt vmcnt(0) lgkmcnt(0)
	v_mfma_f32_16x16x32_bf16 v[4:7], v[4:7], v[0:3], 0
	v_mfma_f32_16x16x32_bf16 v[18:21], v[8:11], v[12:15], v[4:7]
	s_nop 7
	v_cndmask_b32_e64 v6, v21, 0, s[4:5]
	v_cndmask_b32_e64 v7, v20, 0, s[4:5]
	v_cndmask_b32_e64 v8, v19, 0, s[4:5]
	v_cndmask_b32_e64 v9, v18, 0, s[4:5]
	s_cbranch_vccz .LBB0_311
	v_lshlrev_b32_e32 v4, 1, v28
	v_mov_b32_e32 v5, v161
	v_lshl_add_u64 v[4:5], v[16:17], 0, v[4:5]
	v_cvt_pk_bf16_f32 v10, v9, v8
	global_store_short v[4:5], v10, off
	v_cvt_pk_bf16_f32 v10, v8, s0
	global_store_short v[4:5], v10, off offset:256
	v_cvt_pk_bf16_f32 v10, v7, v6
	global_store_short v[4:5], v10, off offset:512
	v_cvt_pk_bf16_f32 v10, v6, s0
	global_store_short v[4:5], v10, off offset:768
	s_mov_b64 s[8:9], 0

.LBB0_381:
	v_lshl_add_u64 v[20:21], v[16:17], 0, v[160:161]
	v_add_co_u32_e32 v20, vcc, s6, v20
	v_lshl_add_u64 v[42:43], v[18:19], 0, v[160:161]
	s_nop 0
	v_addc_co_u32_e32 v21, vcc, 0, v21, vcc
	v_add_co_u32_e32 v22, vcc, s10, v42
	s_nop 1
	v_addc_co_u32_e32 v23, vcc, 0, v43, vcc
	v_add_co_u32_e32 v24, vcc, s7, v42
	s_nop 1
	v_addc_co_u32_e32 v25, vcc, 0, v43, vcc
	v_add_co_u32_e32 v26, vcc, s8, v42
	s_nop 1
	v_addc_co_u32_e32 v27, vcc, 0, v43, vcc
	v_add_co_u32_e32 v28, vcc, s9, v42
	s_nop 1
	v_addc_co_u32_e32 v29, vcc, 0, v43, vcc
	v_lshl_add_u64 v[16:17], v[16:17], 0, s[12:13]
	v_lshl_add_u64 v[18:19], v[18:19], 0, s[14:15]
	global_load_dwordx4 v[34:37], v[20:21], off
	global_load_dwordx4 v[44:47], v[22:23], off
	global_load_dwordx4 v[48:51], v[24:25], off
	global_load_dwordx4 v[52:55], v[26:27], off
	global_load_dwordx4 v[56:59], v[28:29], off
	global_load_dwordx4 v[60:63], v[20:21], off offset:64
	global_load_dwordx4 v[64:67], v[22:23], off offset:64
	global_load_dwordx4 v[68:71], v[24:25], off offset:64
	global_load_dwordx4 v[72:75], v[26:27], off offset:64
	global_load_dwordx4 v[76:79], v[28:29], off offset:64
	global_load_dwordx4 v[80:83], v[20:21], off offset:256
	global_load_dwordx4 v[84:87], v[22:23], off offset:128
	global_load_dwordx4 v[88:91], v[24:25], off offset:128
	global_load_dwordx4 v[92:95], v[26:27], off offset:128
	global_load_dwordx4 v[96:99], v[28:29], off offset:128
	global_load_dwordx4 v[100:103], v[20:21], off offset:320
	global_load_dwordx4 v[104:107], v[22:23], off offset:192
	global_load_dwordx4 v[108:111], v[24:25], off offset:192
	global_load_dwordx4 v[112:115], v[26:27], off offset:192
	global_load_dwordx4 v[116:119], v[28:29], off offset:192
	global_load_dwordx4 v[120:123], v[20:21], off offset:512
	global_load_dwordx4 v[124:127], v[22:23], off offset:256
	global_load_dwordx4 v[128:131], v[24:25], off offset:256
	global_load_dwordx4 v[132:135], v[26:27], off offset:256
	global_load_dwordx4 v[136:139], v[28:29], off offset:256
	global_load_dwordx4 v[140:143], v[20:21], off offset:576
	global_load_dwordx4 v[144:147], v[22:23], off offset:320
	global_load_dwordx4 v[148:151], v[24:25], off offset:320
	global_load_dwordx4 v[152:155], v[26:27], off offset:320
	global_load_dwordx4 v[156:159], v[28:29], off offset:320
	global_load_dwordx4 v[166:169], v[20:21], off offset:768
	global_load_dwordx4 v[170:173], v[22:23], off offset:384
	global_load_dwordx4 v[174:177], v[24:25], off offset:384
	global_load_dwordx4 v[178:181], v[26:27], off offset:384
	global_load_dwordx4 v[182:185], v[28:29], off offset:384
	global_load_dwordx4 v[186:189], v[20:21], off offset:832
	global_load_dwordx4 v[190:193], v[22:23], off offset:448
	global_load_dwordx4 v[194:197], v[24:25], off offset:448
	global_load_dwordx4 v[198:201], v[26:27], off offset:448
	global_load_dwordx4 v[202:205], v[28:29], off offset:448
	s_add_i32 s2, s2, -8
	s_cmp_eq_u32 s2, 0
	s_waitcnt vmcnt(35)
	v_mfma_f32_16x16x32_bf16 v[12:15], v[44:47], v[34:37], v[12:15]
	v_mfma_f32_16x16x32_bf16 v[8:11], v[48:51], v[34:37], v[8:11]
	v_mfma_f32_16x16x32_bf16 v[4:7], v[52:55], v[34:37], v[4:7]
	v_mfma_f32_16x16x32_bf16 v[0:3], v[56:59], v[34:37], v[0:3]
	s_waitcnt vmcnt(30)
	v_mfma_f32_16x16x32_bf16 v[12:15], v[64:67], v[60:63], v[12:15]
	v_mfma_f32_16x16x32_bf16 v[8:11], v[68:71], v[60:63], v[8:11]
	v_mfma_f32_16x16x32_bf16 v[4:7], v[72:75], v[60:63], v[4:7]
	v_mfma_f32_16x16x32_bf16 v[0:3], v[76:79], v[60:63], v[0:3]
	s_waitcnt vmcnt(25)
	v_mfma_f32_16x16x32_bf16 v[12:15], v[84:87], v[80:83], v[12:15]
	v_mfma_f32_16x16x32_bf16 v[8:11], v[88:91], v[80:83], v[8:11]
	v_mfma_f32_16x16x32_bf16 v[4:7], v[92:95], v[80:83], v[4:7]
	v_mfma_f32_16x16x32_bf16 v[0:3], v[96:99], v[80:83], v[0:3]
	s_waitcnt vmcnt(20)
	v_mfma_f32_16x16x32_bf16 v[12:15], v[104:107], v[100:103], v[12:15]
	v_mfma_f32_16x16x32_bf16 v[8:11], v[108:111], v[100:103], v[8:11]
	v_mfma_f32_16x16x32_bf16 v[4:7], v[112:115], v[100:103], v[4:7]
	v_mfma_f32_16x16x32_bf16 v[0:3], v[116:119], v[100:103], v[0:3]
	s_waitcnt vmcnt(15)
	v_mfma_f32_16x16x32_bf16 v[12:15], v[124:127], v[120:123], v[12:15]
	v_mfma_f32_16x16x32_bf16 v[8:11], v[128:131], v[120:123], v[8:11]
	v_mfma_f32_16x16x32_bf16 v[4:7], v[132:135], v[120:123], v[4:7]
	v_mfma_f32_16x16x32_bf16 v[0:3], v[136:139], v[120:123], v[0:3]
	s_waitcnt vmcnt(10)
	v_mfma_f32_16x16x32_bf16 v[12:15], v[144:147], v[140:143], v[12:15]
	v_mfma_f32_16x16x32_bf16 v[8:11], v[148:151], v[140:143], v[8:11]
	v_mfma_f32_16x16x32_bf16 v[4:7], v[152:155], v[140:143], v[4:7]
	v_mfma_f32_16x16x32_bf16 v[0:3], v[156:159], v[140:143], v[0:3]
	s_waitcnt vmcnt(5)
	v_mfma_f32_16x16x32_bf16 v[12:15], v[170:173], v[166:169], v[12:15]
	v_mfma_f32_16x16x32_bf16 v[8:11], v[174:177], v[166:169], v[8:11]
	v_mfma_f32_16x16x32_bf16 v[4:7], v[178:181], v[166:169], v[4:7]
	v_mfma_f32_16x16x32_bf16 v[0:3], v[182:185], v[166:169], v[0:3]
	s_waitcnt vmcnt(0)
	v_mfma_f32_16x16x32_bf16 v[12:15], v[190:193], v[186:189], v[12:15]
	v_mfma_f32_16x16x32_bf16 v[8:11], v[194:197], v[186:189], v[8:11]
	v_mfma_f32_16x16x32_bf16 v[4:7], v[198:201], v[186:189], v[4:7]
	v_mfma_f32_16x16x32_bf16 v[0:3], v[202:205], v[186:189], v[0:3]
	s_cbranch_scc0 .LBB0_381
	v_readlane_b32 s2, v252, 27
	s_add_u32 s2, s0, s2
	v_readlane_b32 s6, v252, 28
	s_addc_u32 s7, s1, s6
	v_readlane_b32 s6, v252, 31
	s_lshl_b32 s6, s6, 7
	v_readlane_b32 s8, v253, 49
	s_or_b32 s8, s6, s8
	v_readlane_b32 s6, v253, 48
	s_add_u32 s6, s2, s6
	s_addc_u32 s7, s7, 0
	s_ashr_i32 s9, s8, 31
	s_lshl_b64 s[8:9], s[8:9], 2
	v_and_b32_e32 v22, 3, v32
	s_add_u32 s8, s0, s8
	s_addc_u32 s9, s1, s9
	v_lshlrev_b32_e32 v160, 4, v22
	v_lshl_add_u64 v[18:19], s[8:9], 0, v[160:161]
	s_mov_b64 s[8:9], 0x300000
	s_mov_b32 s2, 0x300000
	v_lshl_add_u64 v[16:17], v[18:19], 0, s[8:9]
	v_add_co_u32_e32 v18, vcc, s2, v18
	v_readlane_b32 s8, v253, 51
	s_nop 0
	v_addc_co_u32_e32 v19, vcc, 0, v19, vcc
	global_load_dwordx4 v[18:21], v[18:19], off
	v_readlane_b32 s9, v253, 52
	s_add_u32 s0, s0, s8
	s_addc_u32 s1, s1, s9
	v_lshlrev_b32_e32 v160, 1, v30
	s_mov_b64 s[8:9], 0x600000
	v_lshlrev_b32_e32 v28, 9, v22
	s_waitcnt vmcnt(0) lgkmcnt(0)
	v_pk_add_f32 v[12:13], v[12:13], v[18:19]
	s_nop 0
	v_mul_f32_e32 v18, v12, v12
	v_mul_f32_e32 v19, v13, v13
	v_fmamk_f32 v18, v18, 0xbdd2d3e8, v209
	v_fmamk_f32 v19, v19, 0xbdd2d3e8, v209
	v_mul_f32_e32 v18, v12, v18
	v_mul_f32_e32 v19, v13, v19
	v_exp_f32_e32 v18, v18
	v_exp_f32_e32 v19, v19
	v_pk_add_f32 v[14:15], v[14:15], v[20:21]
	v_add_f32_e32 v18, 1.0, v18
	v_add_f32_e32 v19, 1.0, v19
	v_rcp_f32_e32 v18, v18
	v_rcp_f32_e32 v19, v19
	s_nop 0
	v_pk_mul_f32 v[24:25], v[12:13], v[18:19]
	v_mul_f32_e32 v12, v14, v14
	v_mul_f32_e32 v13, v15, v15
	v_fmamk_f32 v12, v12, 0xbdd2d3e8, v209
	v_fmamk_f32 v13, v13, 0xbdd2d3e8, v209
	v_mul_f32_e32 v12, v14, v12
	v_mul_f32_e32 v13, v15, v13
	v_exp_f32_e32 v12, v12
	v_exp_f32_e32 v13, v13
	v_add_f32_e32 v12, 1.0, v12
	v_add_f32_e32 v13, 1.0, v13
	v_rcp_f32_e32 v12, v12
	v_rcp_f32_e32 v13, v13
	s_nop 0
	v_pk_mul_f32 v[26:27], v[14:15], v[12:13]
	global_load_dwordx4 v[12:15], v[16:17], off offset:64
	s_waitcnt vmcnt(0) lgkmcnt(0)
	v_pk_add_f32 v[8:9], v[8:9], v[12:13]
	s_nop 0
	v_mul_f32_e32 v12, v8, v8
	v_mul_f32_e32 v13, v9, v9
	v_fmamk_f32 v12, v12, 0xbdd2d3e8, v209
	v_fmamk_f32 v13, v13, 0xbdd2d3e8, v209
	v_mul_f32_e32 v12, v8, v12
	v_mul_f32_e32 v13, v9, v13
	v_exp_f32_e32 v12, v12
	v_exp_f32_e32 v13, v13
	v_pk_add_f32 v[10:11], v[10:11], v[14:15]
	v_add_f32_e32 v12, 1.0, v12
	v_add_f32_e32 v13, 1.0, v13
	v_rcp_f32_e32 v12, v12
	v_rcp_f32_e32 v13, v13
	s_nop 0
	v_pk_mul_f32 v[8:9], v[8:9], v[12:13]
	v_mul_f32_e32 v12, v10, v10
	v_mul_f32_e32 v13, v11, v11
	v_fmamk_f32 v12, v12, 0xbdd2d3e8, v209
	v_fmamk_f32 v13, v13, 0xbdd2d3e8, v209
	v_mul_f32_e32 v12, v10, v12
	v_mul_f32_e32 v13, v11, v13
	v_exp_f32_e32 v12, v12
	v_exp_f32_e32 v13, v13
	v_add_f32_e32 v12, 1.0, v12
	v_add_f32_e32 v13, 1.0, v13
	v_rcp_f32_e32 v12, v12
	v_rcp_f32_e32 v13, v13
	s_nop 0
	v_pk_mul_f32 v[10:11], v[10:11], v[12:13]
	global_load_dwordx4 v[12:15], v[16:17], off offset:128
	s_waitcnt vmcnt(0) lgkmcnt(0)
	v_pk_add_f32 v[4:5], v[4:5], v[12:13]
	s_nop 0
	v_mul_f32_e32 v12, v4, v4
	v_mul_f32_e32 v13, v5, v5
	v_fmamk_f32 v12, v12, 0xbdd2d3e8, v209
	v_fmamk_f32 v13, v13, 0xbdd2d3e8, v209
	v_mul_f32_e32 v12, v4, v12
	v_mul_f32_e32 v13, v5, v13
	v_exp_f32_e32 v12, v12
	v_exp_f32_e32 v13, v13
	v_pk_add_f32 v[6:7], v[6:7], v[14:15]
	v_add_f32_e32 v12, 1.0, v12
	v_add_f32_e32 v13, 1.0, v13
	v_rcp_f32_e32 v12, v12
	v_rcp_f32_e32 v13, v13
	s_nop 0
	v_pk_mul_f32 v[12:13], v[4:5], v[12:13]
	v_mul_f32_e32 v4, v6, v6
	v_mul_f32_e32 v5, v7, v7
	v_fmamk_f32 v4, v4, 0xbdd2d3e8, v209
	v_fmamk_f32 v5, v5, 0xbdd2d3e8, v209
	v_mul_f32_e32 v4, v6, v4
	v_mul_f32_e32 v5, v7, v5
	v_exp_f32_e32 v4, v4
	v_exp_f32_e32 v5, v5
	v_cvt_pk_bf16_f32 v12, v12, v13
	v_add_f32_e32 v4, 1.0, v4
	v_add_f32_e32 v5, 1.0, v5
	v_rcp_f32_e32 v4, v4
	v_rcp_f32_e32 v5, v5
	s_nop 0
	v_pk_mul_f32 v[14:15], v[6:7], v[4:5]
	global_load_dwordx4 v[4:7], v[16:17], off offset:192
	v_cvt_pk_bf16_f32 v13, v14, v15
	s_waitcnt vmcnt(0) lgkmcnt(0)
	v_pk_add_f32 v[0:1], v[0:1], v[4:5]
	s_nop 0
	v_mul_f32_e32 v4, v0, v0
	v_mul_f32_e32 v5, v1, v1
	v_fmamk_f32 v4, v4, 0xbdd2d3e8, v209
	v_fmamk_f32 v5, v5, 0xbdd2d3e8, v209
	v_mul_f32_e32 v4, v0, v4
	v_mul_f32_e32 v5, v1, v5
	v_exp_f32_e32 v4, v4
	v_exp_f32_e32 v5, v5
	v_pk_add_f32 v[2:3], v[2:3], v[6:7]
	v_add_f32_e32 v4, 1.0, v4
	v_add_f32_e32 v5, 1.0, v5
	v_rcp_f32_e32 v4, v4
	v_rcp_f32_e32 v5, v5
	s_nop 0
	v_pk_mul_f32 v[18:19], v[0:1], v[4:5]
	v_mul_f32_e32 v0, v2, v2
	v_mul_f32_e32 v1, v3, v3
	v_fmamk_f32 v0, v0, 0xbdd2d3e8, v209
	v_fmamk_f32 v1, v1, 0xbdd2d3e8, v209
	v_mul_f32_e32 v0, v2, v0
	v_mul_f32_e32 v1, v3, v1
	v_exp_f32_e32 v0, v0
	v_exp_f32_e32 v1, v1
	v_cvt_pk_bf16_f32 v14, v18, v19
	v_add_f32_e32 v0, 1.0, v0
	v_add_f32_e32 v1, 1.0, v1
	v_rcp_f32_e32 v0, v0
	v_rcp_f32_e32 v1, v1
	s_nop 0
	v_pk_mul_f32 v[20:21], v[2:3], v[0:1]
	v_lshl_add_u64 v[0:1], s[0:1], 0, v[160:161]
	v_lshlrev_b32_e32 v160, 3, v22
	v_lshl_add_u64 v[16:17], v[0:1], 0, s[8:9]
	v_lshl_add_u64 v[0:1], s[6:7], 0, v[160:161]
	v_lshlrev_b32_e32 v2, 7, v31
	v_mov_b32_e32 v3, v161
	v_lshl_add_u64 v[0:1], v[0:1], 0, v[2:3]
	s_mov_b64 s[6:7], 0x800000
	v_lshl_add_u64 v[22:23], v[0:1], 0, s[6:7]
	v_add_co_u32_e32 v0, vcc, s10, v0
	v_cvt_pk_bf16_f32 v2, v8, v9
	s_nop 0
	v_addc_co_u32_e32 v1, vcc, 0, v1, vcc
	global_load_dwordx2 v[4:5], v[0:1], off
	global_load_dwordx2 v[6:7], v[22:23], off offset:32
	v_cvt_pk_bf16_f32 v3, v10, v11
	global_load_dwordx2 v[8:9], v[22:23], off offset:64
	global_load_dwordx2 v[10:11], v[22:23], off offset:96
	v_cvt_pk_bf16_f32 v0, v24, v25
	v_cvt_pk_bf16_f32 v1, v26, v27
	v_cvt_pk_bf16_f32 v15, v20, v21
	v_readlane_b32 s8, v253, 45
	v_readlane_b32 s9, v253, 46
	s_mov_b64 s[6:7], -1
	s_and_b64 vcc, exec, s[8:9]
	s_waitcnt vmcnt(0) lgkmcnt(0)
	v_mfma_f32_16x16x32_bf16 v[4:7], v[4:7], v[0:3], 0
	v_mfma_f32_16x16x32_bf16 v[8:11], v[8:11], v[12:15], v[4:7]
	s_nop 6
	v_lshlrev_b32_e32 v4, 1, v28
	v_cndmask_b32_e64 v6, v11, 0, s[4:5]
	v_cndmask_b32_e64 v5, v10, 0, s[4:5]
	v_cndmask_b32_e64 v7, v9, 0, s[4:5]
	v_cndmask_b32_e64 v8, v8, 0, s[4:5]
	v_cvt_pk_bf16_f32 v8, v8, v7
	v_cvt_pk_bf16_f32 v9, v5, v6
	s_cbranch_vccz .LBB0_384
	v_mov_b32_e32 v5, v161
	v_lshl_add_u64 v[10:11], v[16:17], 0, v[4:5]
	v_cvt_pk_bf16_f32 v5, v7, s0
	global_store_short v[10:11], v8, off
	global_store_short v[10:11], v5, off offset:256
	global_store_short v[10:11], v9, off offset:512
	v_cvt_pk_bf16_f32 v5, v6, s0
	global_store_short v[10:11], v5, off offset:768
	s_mov_b64 s[6:7], 0

.LBB0_425:
	s_or_b64 exec, exec, s[4:5]
	s_add_u32 s6, s0, 0x1d200000
	s_addc_u32 s7, s1, 0
	s_add_u32 s4, s0, 0x2f200000
	v_readlane_b32 s11, v252, 31
	s_addc_u32 s5, s1, 0
	s_lshl_b32 s12, s11, 3
	s_ashr_i32 s13, s12, 31
	s_lshl_b64 s[12:13], s[12:13], 2
	s_add_u32 s14, s8, s12
	s_addc_u32 s2, s2, s13
	s_lshl_b32 s12, s11, 9
	v_ashrrev_i32_e32 v58, 2, v0
	s_ashr_i32 s13, s12, 31
	v_and_b32_e32 v59, -8, v58
	v_readlane_b32 s16, v253, 55
	s_lshl_b64 s[12:13], s[12:13], 2
	v_lshlrev_b32_e32 v1, 1, v48
	v_add_u32_e32 v0, s16, v59
	s_add_u32 s12, s10, s12
	v_and_b32_e32 v172, 62, v1
	v_ashrrev_i32_e32 v1, 31, v0
	s_addc_u32 s13, s9, s13
	v_lshl_add_u64 v[0:1], v[0:1], 1, s[0:1]
	s_mov_b64 s[8:9], 0x21200000
	v_add_u32_e32 v173, -3, v172
	v_lshl_add_u64 v[116:117], v[0:1], 0, s[8:9]
	s_mov_b64 s[8:9], 0x25200000
	v_lshl_add_u64 v[118:119], v[0:1], 0, s[8:9]
	v_max_i32_e32 v0, 0, v173
	v_readlane_b32 s15, v253, 58
	v_and_b32_e32 v170, 63, v48
	s_lshl_b32 s82, s16, 1
	v_add_u32_e32 v0, s15, v0
	v_ashrrev_i32_e32 v1, 31, v0
	v_lshlrev_b64 v[0:1], 10, v[0:1]
	v_lshl_add_u64 v[2:3], v[116:117], 0, v[0:1]
	v_lshl_add_u64 v[0:1], v[118:119], 0, v[0:1]
	global_load_dwordx4 v[28:31], v[2:3], off
	global_load_dwordx4 v[24:27], v[0:1], off
	v_sub_u32_e64 v0, v172, 2 clamp
	v_or_b32_e32 v0, s15, v0
	v_ashrrev_i32_e32 v1, 31, v0
	v_lshlrev_b64 v[0:1], 10, v[0:1]
	v_lshl_add_u64 v[2:3], v[116:117], 0, v[0:1]
	v_lshl_add_u64 v[0:1], v[118:119], 0, v[0:1]
	global_load_dwordx4 v[32:35], v[2:3], off
	global_load_dwordx4 v[8:11], v[0:1], off
	v_sub_u32_e64 v0, v172, 1 clamp
	v_or_b32_e32 v0, s15, v0
	v_ashrrev_i32_e32 v1, 31, v0
	v_lshlrev_b64 v[0:1], 10, v[0:1]
	v_or_b32_e32 v120, s15, v172
	v_lshl_add_u64 v[2:3], v[116:117], 0, v[0:1]
	v_lshl_add_u64 v[0:1], v[118:119], 0, v[0:1]
	v_ashrrev_i32_e32 v121, 31, v120
	global_load_dwordx4 v[36:39], v[2:3], off
	global_load_dwordx4 v[12:15], v[0:1], off
	v_lshlrev_b64 v[0:1], 10, v[120:121]
	v_lshl_add_u64 v[2:3], v[116:117], 0, v[0:1]
	v_lshl_add_u64 v[0:1], v[118:119], 0, v[0:1]
	global_load_dwordx4 v[40:43], v[2:3], off
	global_load_dwordx4 v[16:19], v[0:1], off
	v_or_b32_e32 v0, 1, v120
	v_ashrrev_i32_e32 v1, 31, v0
	v_lshlrev_b64 v[0:1], 10, v[0:1]
	v_or_b32_e32 v50, s15, v170
	v_lshl_add_u64 v[2:3], v[116:117], 0, v[0:1]
	v_lshl_add_u64 v[0:1], v[118:119], 0, v[0:1]
	v_ashrrev_i32_e32 v51, 31, v50
	global_load_dwordx4 v[44:47], v[2:3], off
	global_load_dwordx4 v[20:23], v[0:1], off
	v_lshlrev_b64 v[0:1], 10, v[50:51]
	v_lshl_add_u64 v[0:1], s[6:7], 0, v[0:1]
	v_readlane_b32 s18, v253, 39
	v_lshl_add_u64 v[0:1], v[0:1], 0, s[82:83]
	s_lshl_b32 s8, s18, 1
	s_mov_b32 s9, s83
	v_lshl_add_u64 v[0:1], v[0:1], 0, s[8:9]
	v_readlane_b32 s9, v253, 54
	s_lshl_b32 s10, s9, 2
	s_add_u32 s0, s0, s82
	v_and_b32_e32 v171, 15, v48
	s_addc_u32 s1, s1, 0
	v_bfe_u32 v49, v48, 4, 2
	v_or_b32_e32 v52, s15, v171
	s_add_u32 s0, s0, s8
	v_lshlrev_b64 v[50:51], 7, v[50:51]
	s_addc_u32 s1, s1, 0
	v_lshlrev_b32_e32 v160, 3, v49
	v_or_b32_e32 v56, 16, v52
	v_lshl_add_u64 v[50:51], s[4:5], 0, v[50:51]
	s_mov_b32 s11, s83
	v_lshl_add_u64 v[54:55], s[0:1], 0, v[160:161]
	s_mov_b64 s[0:1], 0x11200000
	v_ashrrev_i32_e32 v53, 31, v52
	v_ashrrev_i32_e32 v57, 31, v56
	v_lshl_add_u64 v[50:51], v[50:51], 0, s[10:11]
	v_lshl_add_u64 v[122:123], v[54:55], 0, s[0:1]
	v_lshlrev_b64 v[54:55], 10, v[52:53]
	v_lshlrev_b64 v[56:57], 10, v[56:57]
	global_load_dwordx4 v[4:7], v[0:1], off
	s_nop 0
	global_load_dwordx4 v[0:3], v[0:1], off offset:16
	v_lshl_add_u64 v[54:55], v[122:123], 0, v[54:55]
	v_lshl_add_u64 v[56:57], v[122:123], 0, v[56:57]
	global_load_dword v196, v[50:51], off
	global_load_dword v204, v[50:51], off offset:16
	global_load_dwordx2 v[142:143], v[54:55], off
	global_load_dwordx2 v[140:141], v[56:57], off
	v_or_b32_e32 v50, 32, v52
	v_ashrrev_i32_e32 v51, 31, v50
	v_or_b32_e32 v52, 48, v52
	v_lshlrev_b64 v[50:51], 10, v[50:51]
	v_ashrrev_i32_e32 v53, 31, v52
	v_lshl_add_u64 v[50:51], v[122:123], 0, v[50:51]
	v_lshlrev_b64 v[52:53], 10, v[52:53]
	v_lshl_add_u64 v[52:53], v[122:123], 0, v[52:53]
	global_load_dwordx2 v[138:139], v[50:51], off
	global_load_dwordx2 v[128:129], v[52:53], off
	s_add_u32 s0, s6, s82
	s_addc_u32 s1, s7, 0
	s_add_u32 s22, s0, s8
	s_addc_u32 s23, s1, 0
	v_lshlrev_b32_e32 v50, 2, v59
	v_readlane_b32 s0, v254, 57
	s_add_u32 s24, s4, s10
	s_addc_u32 s25, s5, 0
	v_add_u32_e32 v121, s0, v50
	v_readlane_b32 s0, v254, 56
	v_lshlrev_b32_e32 v52, 2, v171
	v_and_b32_e32 v124, 48, v48
	v_lshl_add_u32 v175, v170, 3, s0
	v_readlane_b32 s0, v254, 58
	v_or_b32_e32 v48, s18, v171
	s_add_u32 s26, s14, s10
	v_add_u32_e32 v176, s0, v52
	v_mul_lo_u32 v53, v48, s93
	v_readlane_b32 s0, v254, 51
	s_addc_u32 s27, s2, 0
	v_mov_b32_e32 v125, v161
	v_add3_u32 v178, s0, v53, v124
	v_mov_b32_e32 v53, s0
	s_lshl_b32 s0, s16, 2
	s_add_u32 s0, s12, s0
	s_addc_u32 s1, s13, 0
	s_lshl_b32 s2, s18, 2
	s_add_u32 s0, s0, s2
	s_addc_u32 s1, s1, 0
	v_mad_u32_u24 v53, v171, s93, v53
	v_lshl_add_u64 v[126:127], s[0:1], 0, v[124:125]
	s_movk_i32 s0, 0xfef2
	v_mad_i32_i24 v86, v171, s0, v53
	v_readlane_b32 s0, v253, 43
	s_movk_i32 s8, 0x90
	v_lshlrev_b32_e32 v60, 2, v49
	v_lshl_add_u32 v182, v171, 1, s0
	v_readlane_b32 s0, v254, 59
	v_mul_u32_u24_e32 v51, 0x110, v172
	v_mul_lo_u32 v48, v48, s8
	v_add_u32_e32 v183, s0, v50
	v_readlane_b32 s0, v254, 60
	v_lshl_add_u32 v125, v49, 5, s33
	v_lshlrev_b32_e32 v49, 1, v59
	v_add_u32_e32 v185, s0, v50
	v_readlane_b32 s0, v253, 44
	v_add3_u32 v181, 0, v48, v160
	v_or_b32_e32 v48, s18, v60
	v_add3_u32 v184, 0, v51, v49
	v_or_b32_e32 v49, 7, v58
	v_lshl_add_u32 v186, v170, 1, s0
	v_or_b32_e32 v188, 16, v171
	v_readlane_b32 s0, v254, 55
	v_lshl_add_u32 v84, v172, 1, 0
	v_add_u32_e32 v177, 0, v124
	v_mul_u32_u24_e32 v85, 0x110, v171
	v_mul_lo_u32 v87, v59, s8
	v_mul_lo_u32 v88, v49, s8
	v_or_b32_e32 v49, s57, v171
	v_mul_u32_u24_e32 v89, 0x110, v188
	v_or_b32_e32 v189, 32, v171
	v_or_b32_e32 v190, 48, v171
	v_mul_u32_u24_e32 v90, 0x90, v171
	v_mul_lo_u32 v91, v48, s93
	v_mov_b32_e32 v48, s0
	s_mov_b32 s28, 0
	v_lshl_add_u32 v174, v170, 2, s33
	v_cmp_gt_u32_e64 s[4:5], 16, v170
	v_add_u32_e32 v179, v53, v124
	v_add_u32_e32 v180, s33, v52
	v_cmp_eq_u32_e64 s[6:7], 0, v171
	v_cmp_eq_u32_e64 s[8:9], 0, v170
	v_cmp_gt_u32_e64 s[10:11], 2, v170
	v_cmp_gt_u32_e64 s[12:13], 4, v170
	v_cmp_gt_u32_e64 s[14:15], 8, v170
	v_cmp_gt_u32_e64 s[16:17], 32, v170
	v_lshlrev_b32_e32 v187, 3, v49
	v_lshlrev_b32_e32 v191, 3, v171
	v_lshlrev_b32_e32 v192, 3, v188
	v_lshlrev_b32_e32 v193, 3, v189
	v_lshlrev_b32_e32 v194, 3, v190
	v_add_u32_e32 v195, s18, v60
	v_mad_u32_u24 v197, v171, s93, v48
	v_mov_b32_e32 v48, 0
	v_mov_b32_e32 v49, 0
	v_mov_b32_e32 v50, 0
	v_mov_b32_e32 v51, 0
	v_mov_b32_e32 v76, 0
	v_mov_b32_e32 v77, 0
	v_mov_b32_e32 v78, 0
	v_mov_b32_e32 v79, 0
	v_mov_b32_e32 v72, 0
	v_mov_b32_e32 v73, 0
	v_mov_b32_e32 v74, 0
	v_mov_b32_e32 v75, 0
	v_mov_b32_e32 v68, 0
	v_mov_b32_e32 v69, 0
	v_mov_b32_e32 v70, 0
	v_mov_b32_e32 v71, 0
	v_mov_b32_e32 v64, 0
	v_mov_b32_e32 v65, 0
	v_mov_b32_e32 v66, 0
	v_mov_b32_e32 v67, 0
	v_mov_b32_e32 v60, 0
	v_mov_b32_e32 v61, 0
	v_mov_b32_e32 v62, 0
	v_mov_b32_e32 v63, 0
	v_mov_b32_e32 v56, 0
	v_mov_b32_e32 v57, 0
	v_mov_b32_e32 v58, 0
	v_mov_b32_e32 v59, 0
	v_mov_b32_e32 v52, 0
	v_mov_b32_e32 v53, 0
	v_mov_b32_e32 v54, 0
	v_mov_b32_e32 v55, 0
	v_mov_b32_e32 v80, 0
	v_mov_b32_e32 v81, 0
	v_mov_b32_e32 v82, 0
	v_mov_b32_e32 v83, 0
	v_add_u32_e32 v198, v84, v87
	v_add_u32_e32 v199, v84, v88
	v_add_u32_e32 v200, v177, v85
	v_add_u32_e32 v201, v177, v90
	v_add_u32_e32 v202, v86, v91
	v_add_u32_e32 v203, v177, v89
	s_mov_b32 s2, 0
	v_mov_b64_e32 v[242:243], s[26:27]
	global_load_dwordx4 v[244:247], v[126:127], off
	global_load_dword v248, v[242:243], off
	global_load_dword v249, v[242:243], off offset:16
	s_branch .LBB0_427

.LBB0_427:
	s_lshl_b32 s29, s2, 6
	s_waitcnt lgkmcnt(0)
	s_barrier
	v_or_b32_e32 v136, s29, v172
	ds_read_b128 v[94:97], v183
	ds_read_b128 v[84:87], v183 offset:16
	ds_read_b128 v[98:101], v121
	ds_read_b128 v[88:91], v121 offset:16
	ds_read_b128 v[102:105], v121 offset:512
	ds_read_b128 v[106:109], v121 offset:1024
	ds_read_b128 v[110:113], v121 offset:1536
	s_waitcnt vmcnt(0) lgkmcnt(0)
	v_lshlrev_b32_e32 v92, 16, v32
	v_and_b32_e32 v32, 0xffff0000, v32
	v_cmp_eq_u32_e32 vcc, 0, v136
	v_lshlrev_b32_e32 v130, 16, v40
	v_and_b32_e32 v131, 0xffff0000, v40
	v_cndmask_b32_e64 v93, v32, 0, vcc
	v_cndmask_b32_e64 v92, v92, 0, vcc
	v_lshlrev_b32_e32 v32, 16, v36
	v_and_b32_e32 v36, 0xffff0000, v36
	v_cndmask_b32_e64 v115, v36, 0, vcc
	v_cndmask_b32_e64 v114, v32, 0, vcc
	v_pk_fma_f32 v[134:135], v[92:93], v[98:99], v[94:95]
	v_lshlrev_b32_e32 v132, 16, v44
	v_pk_fma_f32 v[134:135], v[114:115], v[102:103], v[134:135]
	v_and_b32_e32 v133, 0xffff0000, v44
	v_pk_fma_f32 v[134:135], v[106:107], v[130:131], v[134:135]
	v_lshlrev_b32_e32 v36, 16, v28
	v_pk_fma_f32 v[144:145], v[110:111], v[132:133], v[134:135]
	v_and_b32_e32 v28, 0xffff0000, v28
	v_cmp_lt_u32_e64 s[18:19], 2, v136
	v_mul_f32_e32 v32, 0xbfb8aa3b, v144
	v_exp_f32_e32 v32, v32
	v_cndmask_b32_e64 v133, 0, v28, s[18:19]
	v_cndmask_b32_e64 v132, 0, v36, s[18:19]
	v_pk_fma_f32 v[94:95], v[132:133], v[98:99], v[94:95]
	v_add_f32_e32 v32, 1.0, v32
	v_pk_fma_f32 v[92:93], v[92:93], v[102:103], v[94:95]
	v_rcp_f32_e32 v102, v32
	v_pk_fma_f32 v[92:93], v[114:115], v[106:107], v[92:93]
	v_mul_f32_e32 v36, 0xbfb8aa3b, v145
	v_pk_fma_f32 v[98:99], v[110:111], v[130:131], v[92:93]
	v_exp_f32_e32 v36, v36
	v_mul_f32_e32 v28, 0xbfb8aa3b, v98
	v_exp_f32_e32 v28, v28
	v_mul_f32_e32 v32, 0xbfb8aa3b, v99
	v_exp_f32_e32 v32, v32
	v_lshlrev_b32_e32 v40, 16, v41
	v_add_f32_e32 v28, 1.0, v28
	v_rcp_f32_e32 v106, v28
	v_add_f32_e32 v28, 1.0, v32
	v_rcp_f32_e32 v107, v28
	v_add_f32_e32 v28, 1.0, v36
	v_rcp_f32_e32 v103, v28
	v_lshlrev_b32_e32 v28, 16, v33
	v_and_b32_e32 v32, 0xffff0000, v33
	v_cndmask_b32_e64 v33, v32, 0, vcc
	v_cndmask_b32_e64 v32, v28, 0, vcc
	v_lshlrev_b32_e32 v28, 16, v37
	v_and_b32_e32 v36, 0xffff0000, v37
	v_cndmask_b32_e64 v37, v36, 0, vcc
	v_cndmask_b32_e64 v36, v28, 0, vcc
	v_lshlrev_b32_e32 v28, 16, v29
	v_and_b32_e32 v29, 0xffff0000, v29
	v_cndmask_b32_e64 v29, 0, v29, s[18:19]
	v_cndmask_b32_e64 v28, 0, v28, s[18:19]
	v_pk_fma_f32 v[28:29], v[28:29], v[100:101], v[96:97]
	v_and_b32_e32 v41, 0xffff0000, v41
	v_pk_fma_f32 v[28:29], v[32:33], v[104:105], v[28:29]
	v_pk_mul_f32 v[98:99], v[98:99], v[106:107]
	v_pk_fma_f32 v[28:29], v[36:37], v[108:109], v[28:29]
	v_pk_fma_f32 v[106:107], v[32:33], v[100:101], v[96:97]
	v_pk_fma_f32 v[28:29], v[112:113], v[40:41], v[28:29]
	v_pk_fma_f32 v[106:107], v[36:37], v[104:105], v[106:107]
	v_mul_f32_e32 v32, 0xbfb8aa3b, v28
	v_mul_f32_e32 v33, 0xbfb8aa3b, v29
	v_exp_f32_e32 v32, v32
	v_exp_f32_e32 v33, v33
	v_lshlrev_b32_e32 v44, 16, v45
	v_and_b32_e32 v45, 0xffff0000, v45
	v_pk_fma_f32 v[106:107], v[108:109], v[40:41], v[106:107]
	v_add_f32_e32 v32, 1.0, v32
	v_pk_fma_f32 v[44:45], v[112:113], v[44:45], v[106:107]
	v_add_f32_e32 v33, 1.0, v33
	v_mul_f32_e32 v37, 0xbfb8aa3b, v45
	v_rcp_f32_e32 v32, v32
	v_rcp_f32_e32 v33, v33
	v_exp_f32_e32 v37, v37
	ds_read_b128 v[92:95], v121 offset:528
	ds_read_b128 v[130:133], v121 offset:1040
	ds_read_b128 v[134:137], v121 offset:1552
	v_pk_mul_f32 v[32:33], v[28:29], v[32:33]
	v_add_f32_e32 v28, 1.0, v37
	v_rcp_f32_e32 v37, v28
	v_lshlrev_b32_e32 v28, 16, v34
	v_and_b32_e32 v29, 0xffff0000, v34
	v_cndmask_b32_e64 v29, v29, 0, vcc
	v_cndmask_b32_e64 v28, v28, 0, vcc
	v_lshlrev_b32_e32 v34, 16, v38
	v_and_b32_e32 v38, 0xffff0000, v38
	v_cndmask_b32_e64 v41, v38, 0, vcc
	v_cndmask_b32_e64 v40, v34, 0, vcc
	v_pk_fma_f32 v[104:105], v[28:29], v[88:89], v[84:85]
	v_lshlrev_b32_e32 v96, 16, v42
	v_and_b32_e32 v97, 0xffff0000, v42
	s_waitcnt lgkmcnt(2)
	v_pk_fma_f32 v[104:105], v[40:41], v[92:93], v[104:105]
	v_lshlrev_b32_e32 v100, 16, v46
	v_and_b32_e32 v101, 0xffff0000, v46
	s_waitcnt lgkmcnt(1)
	v_pk_fma_f32 v[104:105], v[130:131], v[96:97], v[104:105]
	v_lshlrev_b32_e32 v38, 16, v30
	v_and_b32_e32 v30, 0xffff0000, v30
	s_waitcnt lgkmcnt(0)
	v_pk_fma_f32 v[100:101], v[134:135], v[100:101], v[104:105]
	v_cndmask_b32_e64 v105, 0, v30, s[18:19]
	v_cndmask_b32_e64 v104, 0, v38, s[18:19]
	v_pk_fma_f32 v[84:85], v[104:105], v[88:89], v[84:85]
	v_mul_f32_e32 v34, 0xbfb8aa3b, v100
	v_pk_fma_f32 v[28:29], v[28:29], v[92:93], v[84:85]
	v_exp_f32_e32 v34, v34
	v_pk_fma_f32 v[28:29], v[40:41], v[130:131], v[28:29]
	v_mul_f32_e32 v106, 0xbfb8aa3b, v44
	v_pk_fma_f32 v[28:29], v[134:135], v[96:97], v[28:29]
	v_exp_f32_e32 v36, v106
	v_mul_f32_e32 v30, 0xbfb8aa3b, v28
	v_exp_f32_e32 v38, v30
	v_add_f32_e32 v30, 1.0, v34
	v_add_f32_e32 v36, 1.0, v36
	v_rcp_f32_e32 v36, v36
	v_add_f32_e32 v34, 1.0, v38
	v_mul_f32_e32 v38, 0xbfb8aa3b, v29
	v_exp_f32_e32 v38, v38
	v_mul_f32_e32 v40, 0xbfb8aa3b, v101
	v_exp_f32_e32 v42, v40
	v_rcp_f32_e32 v40, v34
	v_add_f32_e32 v34, 1.0, v38
	v_rcp_f32_e32 v41, v34
	v_lshlrev_b32_e32 v34, 16, v35
	v_and_b32_e32 v35, 0xffff0000, v35
	v_cndmask_b32_e64 v35, v35, 0, vcc
	v_cndmask_b32_e64 v34, v34, 0, vcc
	v_lshlrev_b32_e32 v38, 16, v39
	v_and_b32_e32 v39, 0xffff0000, v39
	v_pk_mul_f32 v[36:37], v[44:45], v[36:37]
	v_cndmask_b32_e64 v39, v39, 0, vcc
	v_cndmask_b32_e64 v38, v38, 0, vcc
	v_lshlrev_b32_e32 v44, 16, v47
	v_and_b32_e32 v45, 0xffff0000, v47
	v_pk_fma_f32 v[46:47], v[34:35], v[90:91], v[86:87]
	v_add_f32_e32 v84, 1.0, v42
	v_lshlrev_b32_e32 v42, 16, v43
	v_and_b32_e32 v43, 0xffff0000, v43
	v_pk_fma_f32 v[46:47], v[38:39], v[94:95], v[46:47]
	v_rcp_f32_e32 v30, v30
	v_pk_fma_f32 v[46:47], v[132:133], v[42:43], v[46:47]
	v_pk_mul_f32 v[40:41], v[28:29], v[40:41]
	v_pk_fma_f32 v[44:45], v[136:137], v[44:45], v[46:47]
	v_pk_mul_f32 v[102:103], v[144:145], v[102:103]
	v_mul_f32_e32 v46, 0xbfb8aa3b, v44
	v_exp_f32_e32 v85, v46
	v_lshlrev_b32_e32 v46, 16, v31
	v_and_b32_e32 v31, 0xffff0000, v31
	v_cndmask_b32_e64 v47, 0, v31, s[18:19]
	v_cndmask_b32_e64 v46, 0, v46, s[18:19]
	v_pk_fma_f32 v[46:47], v[46:47], v[90:91], v[86:87]
	v_cvt_pk_bf16_f32 v28, v98, v99
	v_pk_fma_f32 v[34:35], v[34:35], v[94:95], v[46:47]
	v_cvt_pk_bf16_f32 v29, v32, v33
	v_pk_fma_f32 v[34:35], v[38:39], v[132:133], v[34:35]
	v_add_f32_e32 v38, 1.0, v85
	v_pk_fma_f32 v[34:35], v[136:137], v[42:43], v[34:35]
	v_rcp_f32_e32 v38, v38
	v_mul_f32_e32 v31, 0xbfb8aa3b, v34
	v_exp_f32_e32 v39, v31
	v_mul_f32_e32 v42, 0xbfb8aa3b, v35
	v_exp_f32_e32 v43, v42
	v_mul_f32_e32 v42, 0xbfb8aa3b, v45
	v_exp_f32_e32 v46, v42
	v_add_f32_e32 v39, 1.0, v39
	v_rcp_f32_e32 v42, v39
	v_add_f32_e32 v39, 1.0, v43
	v_rcp_f32_e32 v43, v39
	v_add_f32_e32 v39, 1.0, v46
	v_rcp_f32_e32 v31, v84
	v_rcp_f32_e32 v39, v39
	v_pk_mul_f32 v[34:35], v[34:35], v[42:43]
	v_cvt_pk_bf16_f32 v32, v102, v103
	v_pk_mul_f32 v[46:47], v[100:101], v[30:31]
	v_pk_mul_f32 v[38:39], v[44:45], v[38:39]
	v_cvt_pk_bf16_f32 v30, v40, v41
	v_cvt_pk_bf16_f32 v31, v34, v35
	v_cvt_pk_bf16_f32 v33, v36, v37
	v_cvt_pk_bf16_f32 v34, v46, v47
	v_cvt_pk_bf16_f32 v35, v38, v39
	ds_write_b128 v184, v[28:31]
	ds_write_b128 v184, v[32:35] offset:272
	v_lshlrev_b32_e32 v28, 16, v24
	v_and_b32_e32 v24, 0xffff0000, v24
	v_cndmask_b32_e64 v106, 0, v24, s[18:19]
	v_and_b32_e32 v24, 0xffff0000, v25
	v_cndmask_b32_e64 v44, 0, v28, s[18:19]
	v_lshlrev_b32_e32 v28, 16, v25
	v_lshlrev_b32_e32 v25, 16, v26
	v_cndmask_b32_e64 v110, 0, v24, s[18:19]
	v_and_b32_e32 v24, 0xffff0000, v26
	v_lshlrev_b32_e32 v45, 16, v8
	v_cndmask_b32_e64 v112, 0, v25, s[18:19]
	v_lshlrev_b32_e32 v25, 16, v27
	v_cndmask_b32_e64 v114, 0, v24, s[18:19]
	v_and_b32_e32 v24, 0xffff0000, v27
	v_cndmask_b32_e64 v130, v45, 0, vcc
	v_cndmask_b32_e64 v108, 0, v28, s[18:19]
	v_cndmask_b32_e64 v84, 0, v25, s[18:19]
	v_cndmask_b32_e64 v46, 0, v24, s[18:19]
	ds_read_b128 v[86:89], v185
	ds_read_b128 v[32:35], v185 offset:16
	ds_read_b128 v[90:93], v121 offset:2560
	ds_read_b128 v[40:43], v121 offset:2576
	ds_read_b128 v[94:97], v121 offset:3072
	ds_read_b128 v[36:39], v121 offset:3088
	ds_read_b128 v[98:101], v121 offset:3584
	ds_read_b128 v[24:27], v121 offset:3600
	ds_read_b128 v[102:105], v121 offset:4096
	ds_read_b128 v[28:31], v121 offset:4112
	v_and_b32_e32 v8, 0xffff0000, v8
	v_mov_b32_e32 v45, v130
	s_waitcnt lgkmcnt(7)
	v_mov_b32_e32 v146, v90
	s_waitcnt lgkmcnt(5)
	v_mov_b32_e32 v147, v94
	v_cndmask_b32_e64 v131, v8, 0, vcc
	v_lshlrev_b32_e32 v8, 16, v12
	v_pk_mul_f32 v[44:45], v[44:45], v[146:147]
	v_cndmask_b32_e64 v132, v8, 0, vcc
	v_add_f32_e32 v8, v86, v44
	v_add_f32_e32 v8, v8, v45
	v_mov_b32_e32 v107, v131
	v_mov_b32_e32 v44, v91
	v_mov_b32_e32 v45, v95
	v_and_b32_e32 v12, 0xffff0000, v12
	v_lshlrev_b32_e32 v134, 16, v16
	v_pk_mul_f32 v[44:45], v[106:107], v[44:45]
	v_cndmask_b32_e64 v133, v12, 0, vcc
	v_pk_fma_f32 v[144:145], v[130:131], v[90:91], v[86:87]
	v_add_f32_e32 v12, v87, v44
	v_mov_b32_e32 v86, v132
	s_waitcnt lgkmcnt(1)
	v_mov_b32_e32 v87, v102
	v_mov_b32_e32 v90, v98
	v_mov_b32_e32 v91, v134
	v_pk_mul_f32 v[86:87], v[86:87], v[90:91]
	v_and_b32_e32 v135, 0xffff0000, v16
	v_add_f32_e32 v8, v8, v86
	v_add_f32_e32 v8, v8, v87
	v_mul_f32_e32 v16, 0xbfb8aa3b, v8
	v_exp_f32_e32 v16, v16
	v_add_f32_e32 v12, v12, v45
	v_pk_fma_f32 v[44:45], v[132:133], v[94:95], v[144:145]
	v_lshlrev_b32_e32 v136, 16, v20
	v_and_b32_e32 v137, 0xffff0000, v20
	v_pk_fma_f32 v[44:45], v[98:99], v[134:135], v[44:45]
	v_add_f32_e32 v16, 1.0, v16
	v_pk_fma_f32 v[44:45], v[102:103], v[136:137], v[44:45]
	v_mov_b32_e32 v86, v133
	v_mul_f32_e32 v20, 0xbfb8aa3b, v44
	v_mov_b32_e32 v87, v103
	v_mov_b32_e32 v134, v99
	v_rcp_f32_e32 v16, v16
	v_exp_f32_e32 v20, v20
	v_pk_mul_f32 v[86:87], v[86:87], v[134:135]
	v_mul_f32_e32 v47, 0xbfb8aa3b, v45
	v_add_f32_e32 v12, v12, v86
	v_add_f32_e32 v12, v12, v87
	v_mul_f32_e32 v8, v8, v16
	v_add_f32_e32 v16, 1.0, v20
	v_mul_f32_e32 v20, 0xbfb8aa3b, v12
	v_exp_f32_e32 v20, v20
	v_rcp_f32_e32 v86, v16
	v_exp_f32_e32 v47, v47
	v_mul_f32_e32 v94, 0x3db504f3, v8
	v_add_f32_e32 v16, 1.0, v20
	v_rcp_f32_e32 v16, v16
	v_add_f32_e32 v20, 1.0, v47
	v_rcp_f32_e32 v87, v20
	v_mov_b32_e32 v90, v92
	v_mul_f32_e32 v8, v12, v16
	v_mul_f32_e32 v95, 0x3db504f3, v8
	v_lshlrev_b32_e32 v8, 16, v9
	v_cndmask_b32_e64 v8, v8, 0, vcc
	v_and_b32_e32 v9, 0xffff0000, v9
	v_mov_b32_e32 v109, v8
	v_mov_b32_e32 v91, v96
	v_cndmask_b32_e64 v9, v9, 0, vcc
	v_pk_mul_f32 v[90:91], v[108:109], v[90:91]
	v_pk_mul_f32 v[44:45], v[44:45], v[86:87]
	v_pk_fma_f32 v[86:87], v[8:9], v[92:93], v[88:89]
	v_add_f32_e32 v8, v88, v90
	v_add_f32_e32 v47, v8, v91
	v_mov_b32_e32 v111, v9
	v_mov_b32_e32 v8, v93
	v_mov_b32_e32 v9, v97
	v_lshlrev_b32_e32 v12, 16, v13
	v_and_b32_e32 v13, 0xffff0000, v13
	v_pk_mul_f32 v[8:9], v[110:111], v[8:9]
	v_cndmask_b32_e64 v13, v13, 0, vcc
	v_cndmask_b32_e64 v12, v12, 0, vcc
	v_lshlrev_b32_e32 v16, 16, v17
	v_add_f32_e32 v8, v89, v8
	v_add_f32_e32 v85, v8, v9
	v_pk_fma_f32 v[8:9], v[12:13], v[96:97], v[86:87]
	v_mov_b32_e32 v86, v12
	v_mov_b32_e32 v87, v104
	v_mov_b32_e32 v88, v100
	v_mov_b32_e32 v89, v16
	v_pk_mul_f32 v[86:87], v[86:87], v[88:89]
	v_and_b32_e32 v17, 0xffff0000, v17
	v_add_f32_e32 v12, v47, v86
	v_add_f32_e32 v47, v12, v87
	v_lshlrev_b32_e32 v20, 16, v21
	v_and_b32_e32 v21, 0xffff0000, v21
	v_pk_fma_f32 v[8:9], v[100:101], v[16:17], v[8:9]
	v_mul_f32_e32 v16, 0xbfb8aa3b, v47
	v_mov_b32_e32 v12, v13
	v_mov_b32_e32 v13, v105
	v_exp_f32_e32 v86, v16
	v_mov_b32_e32 v16, v101
	v_pk_fma_f32 v[8:9], v[104:105], v[20:21], v[8:9]
	v_pk_mul_f32 v[12:13], v[12:13], v[16:17]
	v_mul_f32_e32 v17, 0xbfb8aa3b, v8
	v_exp_f32_e32 v17, v17
	v_add_f32_e32 v12, v85, v12
	v_add_f32_e32 v20, v12, v13
	v_mul_f32_e32 v13, 0xbfb8aa3b, v20
	v_add_f32_e32 v12, 1.0, v17
	v_exp_f32_e32 v13, v13
	v_mul_f32_e32 v17, 0xbfb8aa3b, v9
	v_exp_f32_e32 v17, v17
	v_rcp_f32_e32 v12, v12
	v_add_f32_e32 v13, 1.0, v13
	v_rcp_f32_e32 v21, v13
	v_add_f32_e32 v13, 1.0, v17
	v_rcp_f32_e32 v13, v13
	v_add_f32_e32 v16, 1.0, v86
	v_rcp_f32_e32 v16, v16
	v_mov_b32_e32 v90, v40
	v_pk_mul_f32 v[8:9], v[8:9], v[12:13]
	v_lshlrev_b32_e32 v12, 16, v10
	v_and_b32_e32 v10, 0xffff0000, v10
	v_cndmask_b32_e64 v13, v10, 0, vcc
	v_cndmask_b32_e64 v12, v12, 0, vcc
	v_mul_f32_e32 v16, v47, v16
	v_pk_fma_f32 v[88:89], v[12:13], v[40:41], v[32:33]
	v_mov_b32_e32 v113, v12
	v_mov_b32_e32 v115, v13
	v_mov_b32_e32 v12, v41
	v_mov_b32_e32 v13, v37
	v_mul_f32_e32 v92, 0x3db504f3, v16
	v_mul_f32_e32 v16, v20, v21
	v_lshlrev_b32_e32 v10, 16, v14
	v_and_b32_e32 v14, 0xffff0000, v14
	v_mov_b32_e32 v91, v36
	v_pk_mul_f32 v[12:13], v[114:115], v[12:13]
	v_mul_f32_e32 v93, 0x3db504f3, v16
	v_cndmask_b32_e64 v17, v14, 0, vcc
	v_cndmask_b32_e64 v16, v10, 0, vcc
	v_lshlrev_b32_e32 v20, 16, v18
	v_pk_mul_f32 v[90:91], v[112:113], v[90:91]
	v_add_f32_e32 v12, v33, v12
	v_add_f32_e32 v10, v32, v90
	v_add_f32_e32 v14, v12, v13
	v_pk_fma_f32 v[12:13], v[16:17], v[36:37], v[88:89]
	v_mov_b32_e32 v32, v16
	s_waitcnt lgkmcnt(0)
	v_mov_b32_e32 v33, v28
	v_mov_b32_e32 v36, v24
	v_mov_b32_e32 v37, v20
	v_add_f32_e32 v10, v10, v91
	v_pk_mul_f32 v[32:33], v[32:33], v[36:37]
	v_and_b32_e32 v21, 0xffff0000, v18
	v_add_f32_e32 v10, v10, v32
	v_add_f32_e32 v10, v10, v33
	v_mul_f32_e32 v18, 0xbfb8aa3b, v10
	v_exp_f32_e32 v18, v18
	v_pk_fma_f32 v[12:13], v[24:25], v[20:21], v[12:13]
	v_mov_b32_e32 v16, v17
	v_mov_b32_e32 v17, v29
	v_mov_b32_e32 v20, v25
	v_pk_mul_f32 v[16:17], v[16:17], v[20:21]
	v_add_f32_e32 v18, 1.0, v18
	v_add_f32_e32 v14, v14, v16
	v_lshlrev_b32_e32 v86, 16, v22
	v_and_b32_e32 v87, 0xffff0000, v22
	v_rcp_f32_e32 v18, v18
	v_add_f32_e32 v14, v14, v17
	v_pk_fma_f32 v[12:13], v[28:29], v[86:87], v[12:13]
	v_mul_f32_e32 v17, 0xbfb8aa3b, v14
	v_mul_f32_e32 v20, 0xbfb8aa3b, v12
	v_exp_f32_e32 v17, v17
	v_exp_f32_e32 v20, v20
	v_mul_f32_e32 v10, v10, v18
	v_mul_f32_e32 v18, 0xbfb8aa3b, v13
	v_exp_f32_e32 v18, v18
	v_add_f32_e32 v17, 1.0, v17
	v_add_f32_e32 v16, 1.0, v20
	v_rcp_f32_e32 v20, v17
	v_add_f32_e32 v17, 1.0, v18
	v_rcp_f32_e32 v16, v16
	v_rcp_f32_e32 v17, v17
	v_mul_f32_e32 v24, 0x3db504f3, v10
	v_mul_f32_e32 v10, v14, v20
	v_mul_f32_e32 v25, 0x3db504f3, v10
	v_lshlrev_b32_e32 v10, 16, v11
	v_cndmask_b32_e64 v10, v10, 0, vcc
	v_pk_mul_f32 v[12:13], v[12:13], v[16:17]
	v_and_b32_e32 v11, 0xffff0000, v11
	v_lshlrev_b32_e32 v16, 16, v23
	v_and_b32_e32 v17, 0xffff0000, v23
	v_mov_b32_e32 v85, v10
	v_mov_b32_e32 v22, v42
	v_mov_b32_e32 v23, v38
	s_mov_b32 s0, s2
	s_mov_b32 s2, 0x3db504f3
	v_cndmask_b32_e64 v11, v11, 0, vcc
	v_pk_mul_f32 v[22:23], v[84:85], v[22:23]
	v_pk_mul_f32 v[20:21], v[12:13], s[2:3] op_sel_hi:[1,0]
	v_lshlrev_b32_e32 v12, 16, v15
	v_and_b32_e32 v13, 0xffff0000, v15
	v_lshlrev_b32_e32 v14, 16, v19
	v_and_b32_e32 v15, 0xffff0000, v19
	v_pk_fma_f32 v[18:19], v[10:11], v[42:43], v[34:35]
	v_add_f32_e32 v10, v34, v22
	v_add_f32_e32 v28, v10, v23
	v_mov_b32_e32 v47, v11
	v_mov_b32_e32 v10, v43
	v_mov_b32_e32 v11, v39
	v_pk_mul_f32 v[10:11], v[46:47], v[10:11]
	v_cndmask_b32_e64 v13, v13, 0, vcc
	v_cndmask_b32_e64 v12, v12, 0, vcc
	v_add_f32_e32 v10, v35, v10
	v_add_f32_e32 v29, v10, v11
	v_pk_fma_f32 v[10:11], v[12:13], v[38:39], v[18:19]
	v_mov_b32_e32 v18, v12
	v_mov_b32_e32 v19, v30
	v_mov_b32_e32 v22, v26
	v_mov_b32_e32 v23, v14
	v_pk_mul_f32 v[18:19], v[18:19], v[22:23]
	v_pk_fma_f32 v[10:11], v[26:27], v[14:15], v[10:11]
	v_add_f32_e32 v12, v28, v18
	v_add_f32_e32 v18, v12, v19
	v_mul_f32_e32 v14, 0xbfb8aa3b, v18
	v_mov_b32_e32 v12, v13
	v_mov_b32_e32 v13, v31
	v_exp_f32_e32 v19, v14
	v_mov_b32_e32 v14, v27
	v_pk_fma_f32 v[10:11], v[30:31], v[16:17], v[10:11]
	v_pk_mul_f32 v[12:13], v[12:13], v[14:15]
	v_mul_f32_e32 v15, 0xbfb8aa3b, v10
	v_exp_f32_e32 v15, v15
	v_add_f32_e32 v12, v29, v12
	v_add_f32_e32 v16, v12, v13
	v_mul_f32_e32 v13, 0xbfb8aa3b, v16
	v_add_f32_e32 v12, 1.0, v15
	v_exp_f32_e32 v13, v13
	v_mul_f32_e32 v15, 0xbfb8aa3b, v11
	v_exp_f32_e32 v15, v15
	v_add_f32_e32 v14, 1.0, v19
	v_rcp_f32_e32 v14, v14
	v_add_f32_e32 v13, 1.0, v13
	v_rcp_f32_e32 v17, v13
	v_add_f32_e32 v13, 1.0, v15
	v_rcp_f32_e32 v12, v12
	v_rcp_f32_e32 v13, v13
	v_mul_f32_e32 v14, v18, v14
	v_mul_f32_e32 v22, 0x3db504f3, v14
	v_mul_f32_e32 v14, v16, v17
	v_mul_f32_e32 v23, 0x3db504f3, v14
	v_pk_mul_f32 v[10:11], v[10:11], v[12:13]
	v_pk_mul_f32 v[44:45], v[44:45], s[2:3] op_sel_hi:[1,0]
	v_pk_mul_f32 v[8:9], v[8:9], s[2:3] op_sel_hi:[1,0]
	v_pk_mul_f32 v[18:19], v[10:11], s[2:3] op_sel_hi:[1,0]
	v_cvt_pk_bf16_f32 v10, v94, v95
	v_cvt_pk_bf16_f32 v11, v92, v93
	v_cvt_pk_bf16_f32 v12, v24, v25
	v_cvt_pk_bf16_f32 v13, v22, v23
	v_cvt_pk_bf16_f32 v14, v44, v45
	v_cvt_pk_bf16_f32 v15, v8, v9
	v_cvt_pk_bf16_f32 v16, v20, v21
	v_cvt_pk_bf16_f32 v17, v18, v19
	ds_write_b128 v184, v[10:13] offset:17408
	ds_write_b128 v184, v[14:17] offset:17680
	v_mov_b32_e32 v84, v248
	v_mov_b32_e32 v85, v249
	v_add_u32_e32 v12, 0x8800, v198
	v_cvt_pk_bf16_f32 v8, v92, v8
	v_cvt_pk_bf16_f32 v9, v93, v9
	s_add_i32 s2, s0, 1
	ds_write2_b32 v12, v8, v9 offset0:72 offset1:108
	v_cvt_pk_bf16_f32 v8, v24, v20
	v_cvt_pk_bf16_f32 v9, v25, v21
	s_lshl_b32 s1, s2, 6
	ds_write2_b32 v12, v8, v9 offset0:144 offset1:180
	v_cvt_pk_bf16_f32 v8, v22, v18
	s_cmp_lg_u32 s0, 31
	v_cvt_pk_bf16_f32 v10, v94, v44
	v_cvt_pk_bf16_f32 v11, v95, v45
	ds_write_b32 v198, v8 offset:35680
	v_cvt_pk_bf16_f32 v8, v23, v19
	s_cselect_b32 s0, s1, 0x7c0
	ds_write2_b32 v12, v10, v11 offset1:36
	ds_write_b32 v199, v8 offset:34816
	ds_write_b16 v186, v4 offset:53248
	ds_write_b16_d16_hi v186, v4 offset:53392
	ds_write_b16 v186, v5 offset:53536
	ds_write_b16_d16_hi v186, v5 offset:53680
	ds_write_b16 v186, v6 offset:53824
	ds_write_b16_d16_hi v186, v6 offset:53968
	ds_write_b16 v186, v7 offset:54112
	ds_write_b16_d16_hi v186, v7 offset:54256
	ds_write_b16 v186, v0 offset:54400
	ds_write_b16_d16_hi v186, v0 offset:54544
	ds_write_b16 v186, v1 offset:54688
	ds_write_b16_d16_hi v186, v1 offset:54832
	ds_write_b16 v186, v2 offset:54976
	ds_write_b16_d16_hi v186, v2 offset:55120
	ds_write_b16 v186, v3 offset:55264
	ds_write_b16_d16_hi v186, v3 offset:55408
	v_add_u32_e32 v4, s0, v173
	v_max_i32_e32 v0, 0, v4
	v_readlane_b32 s1, v253, 58
	v_readlane_b32 s18, v253, 56
	s_nop 0
	v_add_f32_e32 v92, v196, v84
	v_add_u32_e32 v0, s1, v0
	v_ashrrev_i32_e32 v1, 31, v0
	v_lshlrev_b64 v[0:1], 10, v[0:1]
	v_lshl_add_u64 v[2:3], v[116:117], 0, v[0:1]
	v_lshl_add_u64 v[0:1], v[118:119], 0, v[0:1]
	global_load_dwordx4 v[28:31], v[2:3], off
	global_load_dwordx4 v[24:27], v[0:1], off
	v_max_i32_e32 v0, -1, v4
	v_add_u32_e32 v0, s18, v0
	v_ashrrev_i32_e32 v1, 31, v0
	v_lshlrev_b64 v[0:1], 10, v[0:1]
	v_lshl_add_u64 v[2:3], v[116:117], 0, v[0:1]
	v_lshl_add_u64 v[0:1], v[118:119], 0, v[0:1]
	global_load_dwordx4 v[32:35], v[2:3], off
	global_load_dwordx4 v[8:11], v[0:1], off
	v_max_i32_e32 v0, -2, v4
	v_readlane_b32 s18, v253, 57
	s_nop 1
	v_add_u32_e32 v0, s18, v0
	v_ashrrev_i32_e32 v1, 31, v0
	v_lshlrev_b64 v[0:1], 10, v[0:1]
	v_lshl_add_u64 v[2:3], v[116:117], 0, v[0:1]
	v_lshl_add_u64 v[0:1], v[118:119], 0, v[0:1]
	global_load_dwordx4 v[36:39], v[2:3], off
	global_load_dwordx4 v[12:15], v[0:1], off
	v_add_u32_e32 v0, s0, v120
	v_ashrrev_i32_e32 v1, 31, v0
	v_lshlrev_b64 v[0:1], 10, v[0:1]
	v_lshl_add_u64 v[2:3], v[116:117], 0, v[0:1]
	v_lshl_add_u64 v[0:1], v[118:119], 0, v[0:1]
	global_load_dwordx4 v[40:43], v[2:3], off
	global_load_dwordx4 v[16:19], v[0:1], off
	v_max_i32_e32 v0, -4, v4
	v_readlane_b32 s18, v253, 59
	s_nop 1
	v_add_u32_e32 v0, s18, v0
	v_ashrrev_i32_e32 v1, 31, v0
	v_lshlrev_b64 v[0:1], 10, v[0:1]
	v_lshl_add_u64 v[2:3], v[116:117], 0, v[0:1]
	v_lshl_add_u64 v[0:1], v[118:119], 0, v[0:1]
	global_load_dwordx4 v[44:47], v[2:3], off
	global_load_dwordx4 v[20:23], v[0:1], off
	v_add_f32_e32 v2, v204, v85
	s_mov_b32 s18, 0xbfb8aa3b
	v_mul_f32_e64 v0, |v2|, s18
	v_exp_f32_e32 v0, v0
	s_add_i32 s18, s0, s1
	s_mov_b32 s0, 0x800000
	v_min_f32_e32 v2, 0, v2
	v_add_f32_e32 v0, 1.0, v0
	v_cmp_gt_f32_e32 vcc, s0, v0
	s_mov_b32 s0, 0x3f317217
	v_or_b32_e32 v84, s18, v170
	v_cndmask_b32_e64 v1, 0, 32, vcc
	v_ldexp_f32 v0, v0, v1
	v_log_f32_e32 v3, v0
	v_ashrrev_i32_e32 v85, 31, v84
	v_lshlrev_b64 v[0:1], 10, v[84:85]
	v_lshlrev_b64 v[84:85], 7, v[84:85]
	v_mul_f32_e32 v4, 0x3f317217, v3
	v_fma_f32 v4, v3, s0, -v4
	v_fmac_f32_e32 v4, 0x3377d1cf, v3
	s_mov_b32 s0, 0x7f800000
	v_fmac_f32_e32 v4, 0x3f317217, v3
	v_cmp_lt_f32_e64 s[0:1], |v3|, s0
	v_lshl_add_u64 v[0:1], s[22:23], 0, v[0:1]
	v_lshl_add_u64 v[84:85], s[24:25], 0, v[84:85]
	v_cndmask_b32_e64 v3, v3, v4, s[0:1]
	v_cndmask_b32_e32 v4, 0, v225, vcc
	v_sub_f32_e32 v3, v3, v4
	v_sub_f32_e32 v86, v2, v3
	v_add_u32_e32 v2, -1, v211
	v_cmp_lt_i32_e32 vcc, v2, v212
	v_readlane_b32 s0, v253, 41
	v_readlane_b32 s1, v253, 42
	v_cndmask_b32_e32 v2, v2, v211, vcc
	v_lshlrev_b32_e32 v93, 2, v2
	ds_bpermute_b32 v87, v93, v86
	global_load_dwordx4 v[4:7], v[0:1], off
	s_nop 0
	global_load_dwordx4 v[0:3], v[0:1], off offset:16
	s_waitcnt lgkmcnt(0)
	v_add_f32_e32 v87, v86, v87
	v_cndmask_b32_e64 v90, v87, v86, s[8:9]
	v_add_u32_e32 v86, -2, v211
	v_cmp_lt_i32_e32 vcc, v86, v212
	s_nop 1
	v_cndmask_b32_e32 v86, v86, v211, vcc
	v_lshlrev_b32_e32 v94, 2, v86
	ds_bpermute_b32 v91, v94, v90
	v_or_b32_e32 v86, s18, v171
	v_ashrrev_i32_e32 v87, 31, v86
	v_lshlrev_b64 v[88:89], 10, v[86:87]
	v_lshl_add_u64 v[88:89], v[122:123], 0, v[88:89]
	s_waitcnt lgkmcnt(0)
	v_add_f32_e32 v87, v90, v91
	v_cndmask_b32_e64 v87, v87, v90, s[10:11]
	v_add_u32_e32 v90, -4, v211
	v_cmp_lt_i32_e32 vcc, v90, v212
	s_nop 1
	v_cndmask_b32_e32 v90, v90, v211, vcc
	v_lshlrev_b32_e32 v95, 2, v90
	ds_bpermute_b32 v96, v95, v87
	v_or_b32_e32 v90, 16, v86
	v_ashrrev_i32_e32 v91, 31, v90
	v_lshlrev_b64 v[90:91], 10, v[90:91]
	v_lshl_add_u64 v[90:91], v[122:123], 0, v[90:91]
	s_waitcnt lgkmcnt(0)
	v_add_f32_e32 v96, v87, v96
	v_cndmask_b32_e64 v87, v96, v87, s[12:13]
	v_add_u32_e32 v96, -8, v211
	v_cmp_lt_i32_e32 vcc, v96, v212
	global_load_dword v196, v[84:85], off
	global_load_dword v204, v[84:85], off offset:16
	global_load_dwordx2 v[130:131], v[88:89], off
	global_load_dwordx2 v[132:133], v[90:91], off
	v_cndmask_b32_e32 v96, v96, v211, vcc
	v_lshlrev_b32_e32 v96, 2, v96
	ds_bpermute_b32 v97, v96, v87
	v_or_b32_e32 v84, 32, v86
	v_ashrrev_i32_e32 v85, 31, v84
	v_or_b32_e32 v86, 48, v86
	v_lshlrev_b64 v[84:85], 10, v[84:85]
	s_waitcnt lgkmcnt(0)
	v_add_f32_e32 v88, v87, v97
	v_cndmask_b32_e64 v88, v88, v87, s[14:15]
	v_add_u32_e32 v87, -16, v211
	v_cmp_lt_i32_e32 vcc, v87, v212
	v_lshl_add_u64 v[84:85], v[122:123], 0, v[84:85]
	s_nop 0
	v_cndmask_b32_e32 v87, v87, v211, vcc
	v_lshlrev_b32_e32 v89, 2, v87
	v_ashrrev_i32_e32 v87, 31, v86
	ds_bpermute_b32 v90, v89, v88
	v_lshlrev_b64 v[86:87], 10, v[86:87]
	v_lshl_add_u64 v[86:87], v[122:123], 0, v[86:87]
	global_load_dwordx2 v[134:135], v[84:85], off
	global_load_dwordx2 v[136:137], v[86:87], off
	s_waitcnt lgkmcnt(0)
	v_add_f32_e32 v90, v88, v90
	v_cndmask_b32_e64 v88, v90, v88, s[4:5]
	v_subrev_u32_e32 v90, 32, v211
	v_cmp_lt_i32_e32 vcc, v90, v212
	s_nop 1
	v_cndmask_b32_e32 v90, v90, v211, vcc
	v_lshlrev_b32_e32 v90, 2, v90
	ds_bpermute_b32 v91, v90, v88
	s_andn2_b64 vcc, exec, s[0:1]
	s_mov_b64 s[0:1], -1
	s_waitcnt lgkmcnt(0)
	v_add_f32_e32 v84, v88, v91
	v_cndmask_b32_e64 v84, v84, v88, s[16:17]
	v_sub_f32_e32 v85, v92, v84
	ds_bpermute_b32 v86, v93, v85
	s_waitcnt lgkmcnt(0)
	v_max_f32_e32 v86, v86, v86
	v_max_f32_e32 v86, v85, v86
	v_cndmask_b32_e64 v86, v86, v85, s[8:9]
	ds_bpermute_b32 v87, v94, v86
	s_waitcnt lgkmcnt(0)
	v_max_f32_e32 v87, v87, v87
	v_max_f32_e32 v87, v86, v87
	v_cndmask_b32_e64 v86, v87, v86, s[10:11]
	ds_bpermute_b32 v87, v95, v86
	s_waitcnt lgkmcnt(0)
	v_max_f32_e32 v87, v87, v87
	v_max_f32_e32 v87, v86, v87
	v_cndmask_b32_e64 v86, v87, v86, s[12:13]
	ds_bpermute_b32 v87, v96, v86
	s_waitcnt lgkmcnt(0)
	v_max_f32_e32 v87, v87, v87
	v_max_f32_e32 v87, v86, v87
	v_cndmask_b32_e64 v86, v87, v86, s[14:15]
	ds_bpermute_b32 v87, v89, v86
	s_waitcnt lgkmcnt(0)
	v_max_f32_e32 v87, v87, v87
	v_max_f32_e32 v87, v86, v87
	v_cndmask_b32_e64 v86, v87, v86, s[4:5]
	ds_bpermute_b32 v87, v90, v86
	v_max_f32_e32 v88, v86, v86
	s_waitcnt lgkmcnt(0)
	v_max_f32_e32 v87, v87, v87
	v_max_f32_e32 v87, v88, v87
	v_cndmask_b32_e64 v86, v87, v86, s[16:17]
	v_max_f32_e32 v86, v86, v86
	v_max_f32_e64 v87, s28, s28
	v_max_f32_e32 v86, v87, v86
	v_lshl_or_b32 v87, v211, 2, v226
	ds_bpermute_b32 v88, v87, v86
	v_add_f32_e32 v84, v84, v86
	v_sub_f32_e32 v89, s28, v86
	v_mul_f32_e32 v89, 0x3fb8aa3b, v89
	v_mul_f32_e32 v90, 0xbfb8aa3b, v84
	s_waitcnt lgkmcnt(0)
	v_sub_f32_e32 v91, v85, v88
	v_exp_f32_e32 v89, v89
	v_exp_f32_e32 v90, v90
	v_mul_f32_e32 v91, 0x3fb8aa3b, v91
	v_sub_f32_e32 v88, s28, v88
	v_exp_f32_e32 v91, v91
	v_mul_f32_e32 v88, 0x3fb8aa3b, v88
	ds_bpermute_b32 v84, v87, v84
	v_exp_f32_e32 v88, v88
	ds_write2st64_b32 v174, v86, v85 offset1:1
	ds_write2st64_b32 v174, v89, v90 offset0:2 offset1:3
	ds_write_b32 v174, v91 offset:1024
	s_waitcnt lgkmcnt(0)
	s_barrier
	v_readfirstlane_b32 s18, v88
	s_waitcnt lgkmcnt(0)
	v_readfirstlane_b32 s28, v84
	s_cbranch_vccnz .LBB0_429
	v_xor_b32_e32 v144, 32, v211
	s_mov_b64 s[0:1], 0

.LBB0_450:
	s_or_b64 exec, exec, s[0:1]
	v_readlane_b32 s0, v253, 58
	s_or_b32 s0, s29, s0
	s_add_i32 s1, 0, 0x1b100
	s_waitcnt lgkmcnt(0)
	s_barrier
	v_add_u32_e32 v94, s1, v191
	s_waitcnt lgkmcnt(0)
	ds_read2st64_b64 v[88:91], v94 offset1:1
	s_brev_b32 s30, 60
	s_mov_b32 s19, 0x800000
	v_pk_mul_f32 v[50:51], v[50:51], s[18:19] op_sel_hi:[1,0]
	v_pk_mul_f32 v[48:49], v[48:49], s[18:19] op_sel_hi:[1,0]
	s_waitcnt lgkmcnt(0)
	v_pk_add_f32 v[88:89], v[88:89], 0 op_sel_hi:[1,0]
	v_pk_mul_f32 v[74:75], v[74:75], s[18:19] op_sel_hi:[1,0]
	v_pk_add_f32 v[92:93], v[88:89], v[90:91]
	ds_read2st64_b64 v[88:91], v94 offset0:2 offset1:3
	v_pk_mul_f32 v[72:73], v[72:73], s[18:19] op_sel_hi:[1,0]
	v_pk_mul_f32 v[70:71], v[70:71], s[18:19] op_sel_hi:[1,0]
	v_pk_mul_f32 v[68:69], v[68:69], s[18:19] op_sel_hi:[1,0]
	v_pk_mul_f32 v[66:67], v[66:67], s[18:19] op_sel_hi:[1,0]
	s_waitcnt lgkmcnt(0)
	v_pk_add_f32 v[88:89], v[92:93], v[88:89]
	v_pk_mul_f32 v[64:65], v[64:65], s[18:19] op_sel_hi:[1,0]
	v_pk_add_f32 v[92:93], v[88:89], v[90:91]
	ds_read2st64_b64 v[88:91], v94 offset0:4 offset1:5
	v_pk_mul_f32 v[78:79], v[78:79], s[18:19] op_sel_hi:[1,0]
	v_pk_mul_f32 v[76:77], v[76:77], s[18:19] op_sel_hi:[1,0]
	v_pk_mul_f32 v[82:83], v[82:83], s[18:19] op_sel_hi:[1,0]
	v_pk_mul_f32 v[80:81], v[80:81], s[18:19] op_sel_hi:[1,0]
	s_waitcnt lgkmcnt(0)
	v_pk_add_f32 v[88:89], v[92:93], v[88:89]
	s_nop 0
	v_pk_add_f32 v[92:93], v[88:89], v[90:91]
	ds_read2st64_b64 v[88:91], v94 offset0:6 offset1:7
	v_mov_b64_e32 v[94:95], v[244:245]
	v_mov_b64_e32 v[96:97], v[246:247]
	s_waitcnt lgkmcnt(0)
	v_pk_add_f32 v[88:89], v[92:93], v[88:89]
	v_lshlrev_b32_e32 v93, 16, v142
	v_mul_f32_e32 v93, 0xbfb8aa3b, v93
	v_exp_f32_e32 v93, v93
	v_pk_add_f32 v[88:89], v[88:89], v[90:91]
	v_add_f32_e32 v93, 1.0, v93
	v_pk_mul_f32 v[90:91], v[88:89], s[30:31] op_sel_hi:[1,0]
	v_rcp_f32_e32 v98, v93
	v_and_b32_e32 v93, 0xffff0000, v142
	v_fma_f32 v88, -v90, v90, v91
	v_mul_f32_e32 v93, 0xbfb8aa3b, v93
	v_max_f32_e32 v88, 0, v88
	v_exp_f32_e32 v93, v93
	v_add_f32_e32 v88, 0x358637bd, v88
	v_cmp_gt_f32_e32 vcc, s19, v88
	v_mul_f32_e32 v89, 0x4b800000, v88
	v_add_f32_e32 v93, 1.0, v93
	v_cndmask_b32_e32 v88, v88, v89, vcc
	v_rsq_f32_e32 v88, v88
	v_rcp_f32_e32 v99, v93
	v_pk_add_f32 v[100:101], v[154:155], v[90:91] op_sel_hi:[1,0] neg_lo:[0,1] neg_hi:[0,1]
	v_pk_add_f32 v[90:91], v[152:153], v[90:91] op_sel_hi:[1,0] neg_lo:[0,1] neg_hi:[0,1]
	v_mul_f32_e32 v89, 0x45800000, v88
	v_cndmask_b32_e32 v92, v88, v89, vcc
	v_pk_mul_f32 v[98:99], v[98:99], v[100:101]
	v_or_b32_e32 v88, s0, v171
	v_pk_mul_f32 v[98:99], v[98:99], v[92:93] op_sel_hi:[1,0]
	v_lshlrev_b32_e32 v93, 16, v143
	v_mul_f32_e32 v93, 0xbfb8aa3b, v93
	v_exp_f32_e32 v93, v93
	v_ashrrev_i32_e32 v89, 31, v88
	v_lshlrev_b64 v[88:89], 10, v[88:89]
	v_lshl_add_u64 v[88:89], v[122:123], 0, v[88:89]
	v_add_f32_e32 v93, 1.0, v93
	s_nop 0
	v_pk_mul_f32 v[94:95], v[94:95], v[98:99]
	v_rcp_f32_e32 v98, v93
	v_and_b32_e32 v93, 0xffff0000, v143
	v_mul_f32_e32 v93, 0xbfb8aa3b, v93
	v_exp_f32_e32 v93, v93
	s_nop 0
	v_add_f32_e32 v93, 1.0, v93
	v_rcp_f32_e32 v99, v93
	s_nop 0
	v_pk_mul_f32 v[90:91], v[98:99], v[90:91]
	s_nop 0
	v_pk_mul_f32 v[90:91], v[90:91], v[92:93] op_sel_hi:[1,0]
	v_cvt_pk_bf16_f32 v92, v94, v95
	v_pk_mul_f32 v[90:91], v[96:97], v[90:91]
	v_add_u32_e32 v94, s1, v192
	v_cvt_pk_bf16_f32 v93, v90, v91
	global_store_dwordx2 v[88:89], v[92:93], off
	ds_read2st64_b64 v[88:91], v94 offset1:1
	v_lshlrev_b32_e32 v97, 16, v140
	v_mul_f32_e32 v97, 0xbfb8aa3b, v97
	v_exp_f32_e32 v97, v97
	s_waitcnt lgkmcnt(0)
	v_pk_add_f32 v[88:89], v[88:89], 0 op_sel_hi:[1,0]
	s_nop 0
	v_pk_add_f32 v[92:93], v[88:89], v[90:91]
	ds_read2st64_b64 v[88:91], v94 offset0:2 offset1:3
	v_add_f32_e32 v97, 1.0, v97
	v_rcp_f32_e32 v98, v97
	v_and_b32_e32 v97, 0xffff0000, v140
	v_mul_f32_e32 v97, 0xbfb8aa3b, v97
	s_waitcnt lgkmcnt(0)
	v_pk_add_f32 v[88:89], v[92:93], v[88:89]
	v_exp_f32_e32 v97, v97
	v_pk_add_f32 v[92:93], v[88:89], v[90:91]
	ds_read2st64_b64 v[88:91], v94 offset0:4 offset1:5
	v_add_f32_e32 v97, 1.0, v97
	v_rcp_f32_e32 v99, v97
	s_waitcnt lgkmcnt(0)
	v_pk_add_f32 v[88:89], v[92:93], v[88:89]
	s_nop 0
	v_pk_add_f32 v[92:93], v[88:89], v[90:91]
	ds_read2st64_b64 v[88:91], v94 offset0:6 offset1:7
	s_waitcnt lgkmcnt(0)
	v_pk_add_f32 v[88:89], v[92:93], v[88:89]
	s_nop 0
	v_pk_add_f32 v[88:89], v[88:89], v[90:91]
	v_mov_b64_e32 v[90:91], v[244:245]
	v_mov_b64_e32 v[92:93], v[246:247]
	v_pk_mul_f32 v[94:95], v[88:89], s[30:31] op_sel_hi:[1,0]
	s_nop 0
	v_fma_f32 v88, -v94, v94, v95
	v_max_f32_e32 v88, 0, v88
	v_add_f32_e32 v88, 0x358637bd, v88
	v_cmp_gt_f32_e32 vcc, s19, v88
	v_mul_f32_e32 v89, 0x4b800000, v88
	v_pk_add_f32 v[100:101], v[150:151], v[94:95] op_sel_hi:[1,0] neg_lo:[0,1] neg_hi:[0,1]
	v_cndmask_b32_e32 v88, v88, v89, vcc
	v_rsq_f32_e32 v88, v88
	v_pk_mul_f32 v[98:99], v[98:99], v[100:101]
	v_pk_add_f32 v[94:95], v[148:149], v[94:95] op_sel_hi:[1,0] neg_lo:[0,1] neg_hi:[0,1]
	v_mul_f32_e32 v89, 0x45800000, v88
	v_cndmask_b32_e32 v96, v88, v89, vcc
	v_pk_mul_f32 v[98:99], v[98:99], v[96:97] op_sel_hi:[1,0]
	v_lshlrev_b32_e32 v97, 16, v141
	v_mul_f32_e32 v97, 0xbfb8aa3b, v97
	v_exp_f32_e32 v97, v97
	v_or_b32_e32 v88, s0, v188
	v_ashrrev_i32_e32 v89, 31, v88
	v_lshlrev_b64 v[88:89], 10, v[88:89]
	v_add_f32_e32 v97, 1.0, v97
	v_lshl_add_u64 v[88:89], v[122:123], 0, v[88:89]
	s_waitcnt lgkmcnt(0)
	v_pk_mul_f32 v[90:91], v[90:91], v[98:99]
	v_rcp_f32_e32 v98, v97
	v_and_b32_e32 v97, 0xffff0000, v141
	v_mul_f32_e32 v97, 0xbfb8aa3b, v97
	v_exp_f32_e32 v97, v97
	v_cvt_pk_bf16_f32 v90, v90, v91
	v_add_f32_e32 v97, 1.0, v97
	v_rcp_f32_e32 v99, v97
	s_nop 0
	v_pk_mul_f32 v[94:95], v[98:99], v[94:95]
	s_nop 0
	v_pk_mul_f32 v[94:95], v[94:95], v[96:97] op_sel_hi:[1,0]
	v_lshlrev_b32_e32 v97, 16, v138
	v_pk_mul_f32 v[92:93], v[92:93], v[94:95]
	v_add_u32_e32 v94, s1, v193
	v_cvt_pk_bf16_f32 v91, v92, v93
	global_store_dwordx2 v[88:89], v[90:91], off
	ds_read2st64_b64 v[88:91], v94 offset1:1
	v_mul_f32_e32 v97, 0xbfb8aa3b, v97
	v_exp_f32_e32 v97, v97
	s_waitcnt lgkmcnt(0)
	v_pk_add_f32 v[88:89], v[88:89], 0 op_sel_hi:[1,0]
	s_nop 0
	v_pk_add_f32 v[92:93], v[88:89], v[90:91]
	ds_read2st64_b64 v[88:91], v94 offset0:2 offset1:3
	v_add_f32_e32 v97, 1.0, v97
	v_rcp_f32_e32 v98, v97
	v_and_b32_e32 v97, 0xffff0000, v138
	v_mul_f32_e32 v97, 0xbfb8aa3b, v97
	s_waitcnt lgkmcnt(0)
	v_pk_add_f32 v[88:89], v[92:93], v[88:89]
	v_exp_f32_e32 v97, v97
	v_pk_add_f32 v[92:93], v[88:89], v[90:91]
	ds_read2st64_b64 v[88:91], v94 offset0:4 offset1:5
	v_add_f32_e32 v97, 1.0, v97
	v_rcp_f32_e32 v99, v97
	s_waitcnt lgkmcnt(0)
	v_pk_add_f32 v[88:89], v[92:93], v[88:89]
	s_nop 0
	v_pk_add_f32 v[92:93], v[88:89], v[90:91]
	ds_read2st64_b64 v[88:91], v94 offset0:6 offset1:7
	s_waitcnt lgkmcnt(0)
	v_pk_add_f32 v[88:89], v[92:93], v[88:89]
	s_nop 0
	v_pk_add_f32 v[88:89], v[88:89], v[90:91]
	v_mov_b64_e32 v[90:91], v[244:245]
	v_mov_b64_e32 v[92:93], v[246:247]
	v_pk_mul_f32 v[94:95], v[88:89], s[30:31] op_sel_hi:[1,0]
	s_nop 0
	v_fma_f32 v88, -v94, v94, v95
	v_max_f32_e32 v88, 0, v88
	v_add_f32_e32 v88, 0x358637bd, v88
	v_cmp_gt_f32_e32 vcc, s19, v88
	v_mul_f32_e32 v89, 0x4b800000, v88
	v_pk_add_f32 v[100:101], v[146:147], v[94:95] op_sel_hi:[1,0] neg_lo:[0,1] neg_hi:[0,1]
	v_cndmask_b32_e32 v88, v88, v89, vcc
	v_rsq_f32_e32 v88, v88
	v_pk_mul_f32 v[98:99], v[98:99], v[100:101]
	v_pk_add_f32 v[94:95], v[144:145], v[94:95] op_sel_hi:[1,0] neg_lo:[0,1] neg_hi:[0,1]
	v_mul_f32_e32 v89, 0x45800000, v88
	v_cndmask_b32_e32 v96, v88, v89, vcc
	v_pk_mul_f32 v[98:99], v[98:99], v[96:97] op_sel_hi:[1,0]
	v_lshlrev_b32_e32 v97, 16, v139
	v_mul_f32_e32 v97, 0xbfb8aa3b, v97
	v_exp_f32_e32 v97, v97
	v_or_b32_e32 v88, s0, v189
	v_ashrrev_i32_e32 v89, 31, v88
	v_lshlrev_b64 v[88:89], 10, v[88:89]
	v_add_f32_e32 v97, 1.0, v97
	v_lshl_add_u64 v[88:89], v[122:123], 0, v[88:89]
	s_waitcnt lgkmcnt(0)
	v_pk_mul_f32 v[90:91], v[90:91], v[98:99]
	v_rcp_f32_e32 v98, v97
	v_and_b32_e32 v97, 0xffff0000, v139
	v_mul_f32_e32 v97, 0xbfb8aa3b, v97
	v_exp_f32_e32 v97, v97
	v_cvt_pk_bf16_f32 v90, v90, v91
	v_add_f32_e32 v97, 1.0, v97
	v_rcp_f32_e32 v99, v97
	s_nop 0
	v_pk_mul_f32 v[94:95], v[98:99], v[94:95]
	s_nop 0
	v_pk_mul_f32 v[94:95], v[94:95], v[96:97] op_sel_hi:[1,0]
	v_or_b32_e32 v96, s0, v190
	v_pk_mul_f32 v[92:93], v[92:93], v[94:95]
	v_add_u32_e32 v94, s1, v194
	v_cvt_pk_bf16_f32 v91, v92, v93
	global_store_dwordx2 v[88:89], v[90:91], off
	ds_read2st64_b64 v[88:91], v94 offset1:1
	v_lshlrev_b32_e32 v95, 16, v128
	v_mul_f32_e32 v95, 0xbfb8aa3b, v95
	v_exp_f32_e32 v95, v95
	v_ashrrev_i32_e32 v97, 31, v96
	s_waitcnt lgkmcnt(0)
	v_pk_add_f32 v[88:89], v[88:89], 0 op_sel_hi:[1,0]
	v_add_f32_e32 v95, 1.0, v95
	v_pk_add_f32 v[92:93], v[88:89], v[90:91]
	ds_read2st64_b64 v[88:91], v94 offset0:2 offset1:3
	v_rcp_f32_e32 v98, v95
	v_and_b32_e32 v95, 0xffff0000, v128
	v_mul_f32_e32 v95, 0xbfb8aa3b, v95
	v_exp_f32_e32 v95, v95
	s_waitcnt lgkmcnt(0)
	v_pk_add_f32 v[88:89], v[92:93], v[88:89]
	v_add_f32_e32 v95, 1.0, v95
	v_pk_add_f32 v[92:93], v[88:89], v[90:91]
	ds_read2st64_b64 v[88:91], v94 offset0:4 offset1:5
	v_rcp_f32_e32 v99, v95
	s_waitcnt lgkmcnt(0)
	v_pk_add_f32 v[88:89], v[92:93], v[88:89]
	s_nop 0
	v_pk_add_f32 v[92:93], v[88:89], v[90:91]
	ds_read2st64_b64 v[88:91], v94 offset0:6 offset1:7
	s_waitcnt lgkmcnt(0)
	v_pk_add_f32 v[88:89], v[92:93], v[88:89]
	s_nop 0
	v_pk_add_f32 v[88:89], v[88:89], v[90:91]
	s_nop 0
	v_pk_mul_f32 v[92:93], v[88:89], s[30:31] op_sel_hi:[1,0]
	s_nop 0
	v_fma_f32 v88, -v92, v92, v93
	v_max_f32_e32 v88, 0, v88
	v_add_f32_e32 v88, 0x358637bd, v88
	v_cmp_gt_f32_e32 vcc, s19, v88
	v_mul_f32_e32 v89, 0x4b800000, v88
	v_pk_add_f32 v[86:87], v[86:87], v[92:93] op_sel_hi:[1,0] neg_lo:[0,1] neg_hi:[0,1]
	v_cndmask_b32_e32 v88, v88, v89, vcc
	v_rsq_f32_e32 v88, v88
	v_pk_mul_f32 v[86:87], v[98:99], v[86:87]
	v_pk_add_f32 v[84:85], v[84:85], v[92:93] op_sel_hi:[1,0] neg_lo:[0,1] neg_hi:[0,1]
	v_pk_mul_f32 v[92:93], v[52:53], s[18:19] op_sel_hi:[1,0]
	v_mul_f32_e32 v89, 0x45800000, v88
	v_cndmask_b32_e32 v94, v88, v89, vcc
	v_mov_b64_e32 v[88:89], v[244:245]
	v_mov_b64_e32 v[90:91], v[246:247]
	v_pk_mul_f32 v[86:87], v[86:87], v[94:95] op_sel_hi:[1,0]
	s_waitcnt lgkmcnt(0)
	v_pk_mul_f32 v[86:87], v[88:89], v[86:87]
	v_lshlrev_b32_e32 v88, 16, v129
	v_and_b32_e32 v89, 0xffff0000, v129
	v_mul_f32_e32 v88, 0xbfb8aa3b, v88
	v_mul_f32_e32 v89, 0xbfb8aa3b, v89
	v_exp_f32_e32 v88, v88
	v_exp_f32_e32 v89, v89
	v_cvt_pk_bf16_f32 v86, v86, v87
	v_add_f32_e32 v88, 1.0, v88
	v_add_f32_e32 v89, 1.0, v89
	v_rcp_f32_e32 v88, v88
	v_rcp_f32_e32 v89, v89
	s_nop 0
	v_pk_mul_f32 v[84:85], v[88:89], v[84:85]
	s_nop 0
	v_pk_mul_f32 v[84:85], v[84:85], v[94:95] op_sel_hi:[1,0]
	v_pk_mul_f32 v[88:89], v[56:57], s[18:19] op_sel_hi:[1,0]
	v_pk_mul_f32 v[84:85], v[90:91], v[84:85]
	v_pk_mul_f32 v[90:91], v[58:59], s[18:19] op_sel_hi:[1,0]
	v_cvt_pk_bf16_f32 v87, v84, v85
	v_lshlrev_b64 v[84:85], 10, v[96:97]
	v_lshl_add_u64 v[84:85], v[122:123], 0, v[84:85]
	global_store_dwordx2 v[84:85], v[86:87], off
	v_add_u32_e32 v96, v181, v160
	v_pk_mul_f32 v[86:87], v[62:63], s[18:19] op_sel_hi:[1,0]
	v_pk_mul_f32 v[84:85], v[60:61], s[18:19] op_sel_hi:[1,0]
	v_pk_mul_f32 v[94:95], v[54:55], s[18:19] op_sel_hi:[1,0]
	ds_read_b128 v[52:55], v125 offset:1024
	ds_read_b128 v[56:59], v125 offset:1040
	ds_read_b128 v[60:63], v96 offset:53248
	s_waitcnt lgkmcnt(0)
	v_cvt_pk_bf16_f32 v97, v52, v53
	v_cvt_pk_bf16_f32 v102, v54, v55
	v_lshlrev_b32_e32 v98, 16, v60
	v_and_b32_e32 v99, 0xffff0000, v60
	v_lshlrev_b32_e32 v60, 16, v61
	v_and_b32_e32 v61, 0xffff0000, v61
	v_pk_mul_f32 v[98:99], v[52:53], v[98:99]
	v_pk_mul_f32 v[60:61], v[54:55], v[60:61]
	v_cvt_pk_bf16_f32 v98, v98, v99
	v_cvt_pk_bf16_f32 v99, v60, v61
	v_lshlrev_b32_e32 v60, 16, v62
	v_and_b32_e32 v61, 0xffff0000, v62
	v_pk_mul_f32 v[60:61], v[56:57], v[60:61]
	v_cvt_pk_bf16_f32 v103, v56, v57
	v_cvt_pk_bf16_f32 v100, v60, v61
	v_lshlrev_b32_e32 v60, 16, v63
	v_and_b32_e32 v61, 0xffff0000, v63
	v_pk_mul_f32 v[60:61], v[58:59], v[60:61]
	v_cvt_pk_bf16_f32 v104, v58, v59
	v_cvt_pk_bf16_f32 v101, v60, v61
	ds_read_b128 v[52:55], v201 offset:34816
	ds_read_b128 v[56:59], v201 offset:39424
	s_waitcnt lgkmcnt(0)
	v_mfma_f32_16x16x32_bf16 v[56:59], v[98:101], v[56:59], v[72:75]
	ds_read_b128 v[60:63], v201 offset:41728
	s_nop 1
	ds_read_b128 v[72:75], v96 offset:34816
	v_mfma_f32_16x16x32_bf16 v[48:51], v[98:101], v[52:55], v[48:51]
	ds_read_b128 v[52:55], v201 offset:37120
	s_waitcnt lgkmcnt(0)
	v_mfma_f32_16x16x32_bf16 v[60:63], v[98:101], v[60:63], v[68:71]
	s_nop 2
	ds_read_b128 v[68:71], v201 offset:44032
	s_waitcnt lgkmcnt(0)
	v_mfma_f32_16x16x32_bf16 v[64:67], v[98:101], v[68:71], v[64:67]
	ds_read_b128 v[68:71], v201 offset:46336
	s_waitcnt lgkmcnt(0)
	v_mfma_f32_16x16x32_bf16 v[84:87], v[98:101], v[68:71], v[84:87]
	ds_read_b128 v[68:71], v201 offset:48640
	s_waitcnt lgkmcnt(0)
	v_mfma_f32_16x16x32_bf16 v[88:91], v[98:101], v[68:71], v[88:91]
	ds_read_b128 v[68:71], v201 offset:50944
	s_waitcnt lgkmcnt(0)
	v_mfma_f32_16x16x32_bf16 v[92:95], v[98:101], v[68:71], v[92:95]
	v_cndmask_b32_e64 v71, 0, v104, s[6:7]
	v_cndmask_b32_e64 v70, 0, v103, s[6:7]
	v_cndmask_b32_e64 v69, 0, v102, s[6:7]
	v_cndmask_b32_e64 v68, 0, v97, s[6:7]
	v_mfma_f32_16x16x32_bf16 v[52:55], v[98:101], v[52:55], v[76:79]
	s_nop 0
	v_mfma_f32_16x16x32_bf16 v[80:83], v[68:71], v[72:75], v[80:83]
	ds_read_b128 v[68:71], v125 offset:1152
	ds_read_b128 v[72:75], v125 offset:1168
	ds_read_b128 v[76:79], v96 offset:53312
	s_waitcnt lgkmcnt(0)
	v_cvt_pk_bf16_f32 v97, v68, v69
	v_cvt_pk_bf16_f32 v102, v70, v71
	v_lshlrev_b32_e32 v98, 16, v76
	v_and_b32_e32 v99, 0xffff0000, v76
	v_lshlrev_b32_e32 v76, 16, v77
	v_and_b32_e32 v77, 0xffff0000, v77
	v_pk_mul_f32 v[98:99], v[68:69], v[98:99]
	v_pk_mul_f32 v[76:77], v[70:71], v[76:77]
	v_cvt_pk_bf16_f32 v98, v98, v99
	v_cvt_pk_bf16_f32 v99, v76, v77
	v_lshlrev_b32_e32 v76, 16, v78
	v_and_b32_e32 v77, 0xffff0000, v78
	v_pk_mul_f32 v[76:77], v[72:73], v[76:77]
	ds_read_b128 v[68:71], v201 offset:34880
	v_cvt_pk_bf16_f32 v100, v76, v77
	v_lshlrev_b32_e32 v76, 16, v79
	v_and_b32_e32 v77, 0xffff0000, v79
	v_pk_mul_f32 v[76:77], v[74:75], v[76:77]
	v_cvt_pk_bf16_f32 v103, v72, v73
	v_cvt_pk_bf16_f32 v101, v76, v77
	v_cvt_pk_bf16_f32 v104, v74, v75
	s_waitcnt lgkmcnt(0)
	v_mfma_f32_16x16x32_bf16 v[48:51], v[98:101], v[68:71], v[48:51]
	ds_read_b128 v[68:71], v201 offset:37184
	s_waitcnt lgkmcnt(0)
	v_mfma_f32_16x16x32_bf16 v[76:79], v[98:101], v[68:71], v[52:55]
	s_nop 2
	ds_read_b128 v[52:55], v201 offset:39488
	s_waitcnt lgkmcnt(0)
	v_mfma_f32_16x16x32_bf16 v[72:75], v[98:101], v[52:55], v[56:59]
	ds_read_b128 v[52:55], v201 offset:41792
	s_waitcnt lgkmcnt(0)
	v_mfma_f32_16x16x32_bf16 v[68:71], v[98:101], v[52:55], v[60:63]
	ds_read_b128 v[52:55], v201 offset:44096
	s_waitcnt lgkmcnt(0)
	v_mfma_f32_16x16x32_bf16 v[64:67], v[98:101], v[52:55], v[64:67]
	ds_read_b128 v[52:55], v201 offset:46400
	s_waitcnt lgkmcnt(0)
	v_mfma_f32_16x16x32_bf16 v[60:63], v[98:101], v[52:55], v[84:87]
	ds_read_b128 v[52:55], v201 offset:48704
	s_nop 1
	v_cndmask_b32_e64 v87, 0, v104, s[6:7]
	v_cndmask_b32_e64 v86, 0, v103, s[6:7]
	s_waitcnt lgkmcnt(0)
	v_mfma_f32_16x16x32_bf16 v[56:59], v[98:101], v[52:55], v[88:91]
	ds_read_b128 v[52:55], v201 offset:51008
	s_nop 1
	ds_read_b128 v[88:91], v96 offset:34880
	v_cndmask_b32_e64 v85, 0, v102, s[6:7]
	s_waitcnt lgkmcnt(0)
	v_mfma_f32_16x16x32_bf16 v[52:55], v[98:101], v[52:55], v[92:95]
	v_cndmask_b32_e64 v84, 0, v97, s[6:7]
	s_nop 1
	v_cvt_pk_bf16_f32 v92, v48, s0
	ds_write_b16 v202, v92
	v_cvt_pk_bf16_f32 v92, v49, s0
	ds_write_b16 v202, v92 offset:272
	v_cvt_pk_bf16_f32 v92, v50, s0
	ds_write_b16 v202, v92 offset:544
	v_cvt_pk_bf16_f32 v92, v51, s0
	ds_write_b16 v202, v92 offset:816
	v_cvt_pk_bf16_f32 v92, v76, s0
	ds_write_b16 v202, v92 offset:32
	v_cvt_pk_bf16_f32 v92, v77, s0
	ds_write_b16 v202, v92 offset:304
	v_cvt_pk_bf16_f32 v92, v78, s0
	ds_write_b16 v202, v92 offset:576
	v_cvt_pk_bf16_f32 v92, v79, s0
	ds_write_b16 v202, v92 offset:848
	v_cvt_pk_bf16_f32 v92, v72, s0
	ds_write_b16 v202, v92 offset:64
	v_cvt_pk_bf16_f32 v92, v73, s0
	ds_write_b16 v202, v92 offset:336
	v_cvt_pk_bf16_f32 v92, v74, s0
	ds_write_b16 v202, v92 offset:608
	v_cvt_pk_bf16_f32 v92, v75, s0
	ds_write_b16 v202, v92 offset:880
	v_cvt_pk_bf16_f32 v92, v68, s0
	ds_write_b16 v202, v92 offset:96
	v_cvt_pk_bf16_f32 v92, v69, s0
	ds_write_b16 v202, v92 offset:368
	v_cvt_pk_bf16_f32 v92, v70, s0
	ds_write_b16 v202, v92 offset:640
	v_cvt_pk_bf16_f32 v92, v71, s0
	ds_write_b16 v202, v92 offset:912
	v_cvt_pk_bf16_f32 v92, v64, s0
	ds_write_b16 v202, v92 offset:128
	v_cvt_pk_bf16_f32 v92, v65, s0
	ds_write_b16 v202, v92 offset:400
	v_cvt_pk_bf16_f32 v92, v66, s0
	ds_write_b16 v202, v92 offset:672
	v_cvt_pk_bf16_f32 v92, v67, s0
	ds_write_b16 v202, v92 offset:944
	v_cvt_pk_bf16_f32 v92, v60, s0
	ds_write_b16 v202, v92 offset:160
	v_cvt_pk_bf16_f32 v92, v61, s0
	ds_write_b16 v202, v92 offset:432
	v_cvt_pk_bf16_f32 v92, v62, s0
	ds_write_b16 v202, v92 offset:704
	v_cvt_pk_bf16_f32 v92, v63, s0
	ds_write_b16 v202, v92 offset:976
	v_cvt_pk_bf16_f32 v92, v56, s0
	ds_write_b16 v202, v92 offset:192
	v_cvt_pk_bf16_f32 v92, v57, s0
	ds_write_b16 v202, v92 offset:464
	v_cvt_pk_bf16_f32 v92, v58, s0
	ds_write_b16 v202, v92 offset:736
	v_cvt_pk_bf16_f32 v92, v59, s0
	ds_write_b16 v202, v92 offset:1008
	v_cvt_pk_bf16_f32 v92, v52, s0
	v_mfma_f32_16x16x32_bf16 v[80:83], v[84:87], v[88:91], v[80:83]
	ds_write_b16 v202, v92 offset:224
	v_cvt_pk_bf16_f32 v92, v53, s0
	ds_write_b16 v202, v92 offset:496
	v_cvt_pk_bf16_f32 v92, v54, s0
	ds_write_b16 v202, v92 offset:768
	v_cvt_pk_bf16_f32 v92, v55, s0
	ds_write_b16 v202, v92 offset:1040
	s_and_saveexec_b64 s[0:1], s[4:5]
	s_cbranch_execz .LBB0_426
	v_cvt_pk_bf16_f32 v84, v80, v81
	ds_write_b16 v182, v84 offset:34816
	s_branch .LBB0_426

	.amdhsa_kernel _Z8mega_fwdILi1023EEv2KP
		.amdhsa_group_segment_fixed_size 4096
		.amdhsa_private_segment_fixed_size 0
		.amdhsa_kernarg_size 504
		.amdhsa_user_sgpr_count 2
		.amdhsa_user_sgpr_dispatch_ptr 0
		.amdhsa_user_sgpr_queue_ptr 0
		.amdhsa_user_sgpr_kernarg_segment_ptr 1
		.amdhsa_user_sgpr_dispatch_id 0
		.amdhsa_user_sgpr_kernarg_preload_length 0
		.amdhsa_user_sgpr_kernarg_preload_offset 0
		.amdhsa_user_sgpr_private_segment_size 0
		.amdhsa_uses_dynamic_stack 0
		.amdhsa_enable_private_segment 0
		.amdhsa_system_sgpr_workgroup_id_x 1
		.amdhsa_system_sgpr_workgroup_id_y 0
		.amdhsa_system_sgpr_workgroup_id_z 0
		.amdhsa_system_sgpr_workgroup_info 0
		.amdhsa_system_vgpr_workitem_id 2
		.amdhsa_next_free_vgpr 256
		.amdhsa_next_free_sgpr 102
		.amdhsa_accum_offset 256
		.amdhsa_reserve_vcc 1
		.amdhsa_float_round_mode_32 0
		.amdhsa_float_round_mode_16_64 0
		.amdhsa_float_denorm_mode_32 3
		.amdhsa_float_denorm_mode_16_64 3
		.amdhsa_dx10_clamp 1
		.amdhsa_ieee_mode 1
		.amdhsa_fp16_overflow 0
		.amdhsa_tg_split 0
		.amdhsa_exception_fp_ieee_invalid_op 0
		.amdhsa_exception_fp_denorm_src 0
		.amdhsa_exception_fp_ieee_div_zero 0
		.amdhsa_exception_fp_ieee_overflow 0
		.amdhsa_exception_fp_ieee_underflow 0
		.amdhsa_exception_fp_ieee_inexact 0
		.amdhsa_exception_int_div_zero 0
	.end_amdhsa_kernel

amdhsa.kernels:
  - .agpr_count:     0
    .args:
      - .offset:         0
        .size:           248
        .value_kind:     by_value
      - .offset:         248
        .size:           4
        .value_kind:     hidden_block_count_x
      - .offset:         252
        .size:           4
        .value_kind:     hidden_block_count_y
      - .offset:         256
        .size:           4
        .value_kind:     hidden_block_count_z
      - .offset:         260
        .size:           2
        .value_kind:     hidden_group_size_x
      - .offset:         262
        .size:           2
        .value_kind:     hidden_group_size_y
      - .offset:         264
        .size:           2
        .value_kind:     hidden_group_size_z
      - .offset:         266
        .size:           2
        .value_kind:     hidden_remainder_x
      - .offset:         268
        .size:           2
        .value_kind:     hidden_remainder_y
      - .offset:         270
        .size:           2
        .value_kind:     hidden_remainder_z
      - .offset:         288
        .size:           8
        .value_kind:     hidden_global_offset_x
      - .offset:         296
        .size:           8
        .value_kind:     hidden_global_offset_y
      - .offset:         304
        .size:           8
        .value_kind:     hidden_global_offset_z
      - .offset:         312
        .size:           2
        .value_kind:     hidden_grid_dims
      - .offset:         336
        .size:           8
        .value_kind:     hidden_multigrid_sync_arg
      - .offset:         368
        .size:           4
        .value_kind:     hidden_dynamic_lds_size
    .group_segment_fixed_size: 4096
    .kernarg_segment_align: 8
    .kernarg_segment_size: 504
    .language:       OpenCL C
    .language_version:
      - 2
      - 0
    .max_flat_workgroup_size: 512
    .name:           _Z8mega_fwdILi1023EEv2KP
    .private_segment_fixed_size: 0
    .sgpr_count:     108
    .sgpr_spill_count: 176
    .symbol:         _Z8mega_fwdILi1023EEv2KP.kd
    .uniform_work_group_size: 1
    .uses_dynamic_stack: false
    .vgpr_count:     256
    .vgpr_spill_count: 0
    .wavefront_size: 64
